# P8 top-k: bitonic compare-exchange triples (max_dpp,min_dpp,cndmask) rewritten as (mov_dpp, med3_i32 with per-lane +-INT_MAX constant); P5 main GEMM K-loop gets the paired-DMA pipelined loop
# speedup vs baseline: 1.0406x; 1.0224x over previous
.LBB0_707:
	v_add_u32_e32 v0, v206, v207
	s_movk_i32 s22, 0x1ff
	v_cmp_lt_i32_e32 vcc, s22, v0
	s_cbranch_vccnz .LBB0_706
	v_readfirstlane_b32 s22, v0
	s_ashr_i32 s23, s22, 31
	s_lshr_b32 s23, s23, 25
	s_add_i32 s23, s22, s23
	s_ashr_i32 s33, s23, 7
	s_lshl_b32 s41, s33, 3
	s_and_b32 s23, s23, 0xffffff80
	s_sub_i32 s40, 32, s41
	s_cmpk_gt_i32 s22, 0x1ff
	s_cselect_b32 s42, s40, 8
	s_abs_i32 s40, s42
	v_cvt_f32_u32_e32 v1, s40
	v_subrev_u32_e32 v0, s23, v0
	s_sub_i32 s23, 0, s40
	v_sub_u32_e32 v2, 0, v0
	v_rcp_iflag_f32_e32 v1, v1
	v_max_i32_e32 v2, v0, v2
	v_xor_b32_e32 v3, s42, v0
	v_ashrrev_i32_e32 v3, 31, v3
	v_mul_f32_e32 v1, 0x4f7ffffe, v1
	v_cvt_u32_f32_e32 v1, v1
	v_mov_b32_e32 v8, v204
	s_mulk_i32 s33, 0x78
	v_mul_lo_u32 v4, s23, v1
	v_mul_hi_u32 v4, v1, v4
	v_add_u32_e32 v1, v1, v4
	v_mul_hi_u32 v1, v2, v1
	v_mul_lo_u32 v4, v1, s40
	v_sub_u32_e32 v2, v2, v4
	v_add_u32_e32 v5, 1, v1
	v_subrev_u32_e32 v4, s40, v2
	v_cmp_le_u32_e32 vcc, s40, v2
	s_mov_b32 s22, 0
	s_nop 0
	v_cndmask_b32_e32 v1, v1, v5, vcc
	v_cndmask_b32_e32 v2, v2, v4, vcc
	v_add_u32_e32 v4, 1, v1
	v_cmp_le_u32_e32 vcc, s40, v2
	v_bfe_u32 v2, v8, 4, 2
	v_bitop3_b32 v2, v2, v8, 3 bitop3:0x78
	v_cndmask_b32_e32 v1, v1, v4, vcc
	v_xor_b32_e32 v1, v1, v3
	v_sub_u32_e32 v1, v1, v3
	v_ashrrev_i32_e32 v3, 6, v8
	v_readfirstlane_b32 s40, v1
	s_mul_i32 s23, s42, s40
	v_subrev_u32_e32 v0, s23, v0
	s_waitcnt vmcnt(1)
	v_add_u32_e32 v138, s41, v0
	s_ashr_i32 s41, s40, 31
	v_lshlrev_b32_e32 v132, 8, v138
	s_lshl_b64 s[42:43], s[40:41], 19
	v_bfe_u32 v4, v8, 2, 4
	s_mov_b32 s41, 0x1fffc0
	v_ashrrev_i32_e32 v133, 31, v132
	v_lshlrev_b32_e32 v9, 3, v2
	v_and_or_b32 v2, v8, s41, v4
	v_lshlrev_b32_e32 v5, 16, v3
	v_lshlrev_b32_e32 v10, 11, v4
	v_lshlrev_b64 v[130:131], 11, v[132:133]
	v_lshlrev_b64 v[0:1], 12, v[132:133]
	v_lshl_or_b32 v2, v2, 11, v9
	v_or3_b32 v4, v10, v5, v9
	v_lshl_add_u32 v133, v3, 12, 32
	v_lshlrev_b32_e32 v3, 11, v3
	v_lshl_add_u64 v[0:1], s[6:7], 0, v[0:1]
	s_add_u32 s90, s52, s42
	v_sub_u32_e32 v139, v133, v3
	v_ashrrev_i32_e32 v3, 31, v2
	v_ashrrev_i32_e32 v5, 31, v4
	v_readfirstlane_b32 s41, v133
	v_add_u32_e32 v12, 0x400, v133
	s_addc_u32 s91, s53, s43
	v_lshl_add_u64 v[0:1], v[2:3], 1, v[0:1]
	v_lshlrev_b64 v[2:3], 1, v[4:5]
	s_mov_b32 m0, s41
	v_readfirstlane_b32 s41, v12
	v_add_u32_e32 v12, 0x800, v133
	v_lshl_add_u64 v[4:5], s[90:91], 0, v[2:3]
	global_load_lds_dwordx4 v[0:1], off
	v_lshl_add_u64 v[6:7], v[0:1], 0, s[10:11]
	s_mov_b32 m0, s41
	s_mov_b64 s[90:91], 0x20000
	v_readfirstlane_b32 s41, v12
	v_add_u32_e32 v12, 0xc00, v133
	v_add_u32_e32 v11, 0x4000, v139
	global_load_lds_dwordx4 v[6:7], off
	v_lshl_add_u64 v[6:7], v[0:1], 0, s[90:91]
	s_mov_b32 m0, s41
	s_mov_b64 s[90:91], 0x30000
	v_readfirstlane_b32 s41, v12
	global_load_lds_dwordx4 v[6:7], off
	v_lshl_add_u64 v[6:7], v[0:1], 0, s[90:91]
	s_mov_b32 m0, s41
	v_readfirstlane_b32 s41, v11
	v_add_u32_e32 v11, 0x4400, v139
	global_load_lds_dwordx4 v[6:7], off
	s_mov_b32 m0, s41
	v_readfirstlane_b32 s41, v11
	v_add_u32_e32 v11, 0x6000, v133
	global_load_lds_dwordx4 v[4:5], off
	v_lshl_add_u64 v[6:7], v[4:5], 0, s[10:11]
	s_mov_b32 m0, s41
	v_readfirstlane_b32 s41, v11
	v_add_u32_e32 v11, 0x6400, v133
	global_load_lds_dwordx4 v[6:7], off
	v_lshl_add_u64 v[6:7], v[0:1], 0, 64
	s_mov_b32 m0, s41
	v_readfirstlane_b32 s41, v11
	v_add_u32_e32 v11, 0x6800, v133
	global_load_lds_dwordx4 v[6:7], off
	v_lshl_add_u64 v[6:7], v[0:1], 0, s[12:13]
	s_mov_b32 m0, s41
	s_mov_b64 s[90:91], 0x20040
	v_readfirstlane_b32 s41, v11
	global_load_lds_dwordx4 v[6:7], off
	v_lshl_add_u64 v[6:7], v[0:1], 0, s[90:91]
	s_mov_b32 m0, s41
	s_mov_b64 s[90:91], 0x30040
	global_load_lds_dwordx4 v[6:7], off
	v_add_u32_e32 v6, 0x6c00, v133
	v_lshl_add_u64 v[0:1], v[0:1], 0, s[90:91]
	v_readfirstlane_b32 s41, v6
	v_add_u32_e32 v6, 0xa000, v139
	s_mov_b32 m0, s41
	v_readfirstlane_b32 s41, v6
	global_load_lds_dwordx4 v[0:1], off
	v_lshl_add_u64 v[0:1], v[4:5], 0, 64
	s_mov_b32 m0, s41
	s_add_u32 s42, s94, s42
	global_load_lds_dwordx4 v[0:1], off
	v_lshl_add_u64 v[0:1], v[4:5], 0, s[12:13]
	v_add_u32_e32 v4, 0xa400, v139
	s_addc_u32 s43, s95, s43
	v_readfirstlane_b32 s41, v4
	s_mov_b32 m0, s41
	v_bfe_u32 v4, v8, 2, 2
	global_load_lds_dwordx4 v[0:1], off
	v_bfe_u32 v0, v8, 5, 1
	v_lshrrev_b32_e32 v1, 2, v8
	v_bitop3_b32 v1, v0, v1, 3 bitop3:0x78
	v_bitop3_b32 v0, v0, v4, 2 bitop3:0x36
	v_lshlrev_b32_e32 v128, 4, v0
	v_subrev_u32_e32 v0, s23, v208
	v_subrev_u32_e32 v0, s33, v0
	v_lshl_add_u64 v[134:135], s[42:43], 0, v[2:3]
	v_lshlrev_b32_e32 v0, 8, v0
	v_lshlrev_b32_e32 v2, 11, v8
	v_lshlrev_b32_e32 v140, 4, v1
	v_ashrrev_i32_e32 v1, 31, v0
	v_and_b32_e32 v2, 0xfffe0000, v2
	v_lshlrev_b64 v[0:1], 12, v[0:1]
	v_or3_b32 v2, v2, v10, v9
	v_ashrrev_i32_e32 v3, 31, v2
	v_lshl_add_u64 v[0:1], s[94:95], 0, v[0:1]
	v_lshlrev_b32_e32 v5, 6, v8
	v_lshl_add_u64 v[136:137], v[2:3], 1, v[0:1]
	v_mov_b32_e32 v0, 0
	v_and_b32_e32 v141, 0xffffe7c0, v5
	s_waitcnt vmcnt(0)
	v_and_b32_e32 v142, 0x17c0, v5
	s_mov_b64 s[42:43], 0
	v_mov_b32_e32 v1, v0
	v_mov_b32_e32 v2, v0
	v_mov_b32_e32 v3, v0
	v_mov_b32_e32 v4, v0
	v_mov_b32_e32 v5, v0
	v_mov_b32_e32 v6, v0
	v_mov_b32_e32 v7, v0
	v_mov_b32_e32 v8, v0
	v_mov_b32_e32 v9, v0
	v_mov_b32_e32 v10, v0
	v_mov_b32_e32 v11, v0
	v_mov_b32_e32 v12, v0
	v_mov_b32_e32 v13, v0
	v_mov_b32_e32 v14, v0
	v_mov_b32_e32 v15, v0
	v_mov_b32_e32 v16, v0
	v_mov_b32_e32 v17, v0
	v_mov_b32_e32 v18, v0
	v_mov_b32_e32 v19, v0
	v_mov_b32_e32 v20, v0
	v_mov_b32_e32 v21, v0
	v_mov_b32_e32 v22, v0
	v_mov_b32_e32 v23, v0
	v_mov_b32_e32 v24, v0
	v_mov_b32_e32 v25, v0
	v_mov_b32_e32 v26, v0
	v_mov_b32_e32 v27, v0
	v_mov_b32_e32 v28, v0
	v_mov_b32_e32 v29, v0
	v_mov_b32_e32 v30, v0
	v_mov_b32_e32 v31, v0
	v_mov_b32_e32 v32, v0
	v_mov_b32_e32 v33, v0
	v_mov_b32_e32 v34, v0
	v_mov_b32_e32 v35, v0
	v_mov_b32_e32 v36, v0
	v_mov_b32_e32 v37, v0
	v_mov_b32_e32 v38, v0
	v_mov_b32_e32 v39, v0
	v_mov_b32_e32 v40, v0
	v_mov_b32_e32 v41, v0
	v_mov_b32_e32 v42, v0
	v_mov_b32_e32 v43, v0
	v_mov_b32_e32 v44, v0
	v_mov_b32_e32 v45, v0
	v_mov_b32_e32 v46, v0
	v_mov_b32_e32 v47, v0
	v_mov_b32_e32 v48, v0
	v_mov_b32_e32 v49, v0
	v_mov_b32_e32 v50, v0
	v_mov_b32_e32 v51, v0
	v_mov_b32_e32 v52, v0
	v_mov_b32_e32 v53, v0
	v_mov_b32_e32 v54, v0
	v_mov_b32_e32 v55, v0
	v_mov_b32_e32 v56, v0
	v_mov_b32_e32 v57, v0
	v_mov_b32_e32 v58, v0
	v_mov_b32_e32 v59, v0
	v_mov_b32_e32 v60, v0
	v_mov_b32_e32 v61, v0
	v_mov_b32_e32 v62, v0
	v_mov_b32_e32 v63, v0
	v_mov_b32_e32 v64, v0
	v_mov_b32_e32 v65, v0
	v_mov_b32_e32 v66, v0
	v_mov_b32_e32 v67, v0
	v_mov_b32_e32 v68, v0
	v_mov_b32_e32 v69, v0
	v_mov_b32_e32 v70, v0
	v_mov_b32_e32 v71, v0
	v_mov_b32_e32 v72, v0
	v_mov_b32_e32 v73, v0
	v_mov_b32_e32 v74, v0
	v_mov_b32_e32 v75, v0
	v_mov_b32_e32 v76, v0
	v_mov_b32_e32 v77, v0
	v_mov_b32_e32 v78, v0
	v_mov_b32_e32 v79, v0
	v_mov_b32_e32 v80, v0
	v_mov_b32_e32 v81, v0
	v_mov_b32_e32 v82, v0
	v_mov_b32_e32 v83, v0
	v_mov_b32_e32 v84, v0
	v_mov_b32_e32 v85, v0
	v_mov_b32_e32 v86, v0
	v_mov_b32_e32 v87, v0
	v_mov_b32_e32 v88, v0
	v_mov_b32_e32 v89, v0
	v_mov_b32_e32 v90, v0
	v_mov_b32_e32 v91, v0
	v_mov_b32_e32 v92, v0
	v_mov_b32_e32 v93, v0
	v_mov_b32_e32 v94, v0
	v_mov_b32_e32 v95, v0
	v_mov_b32_e32 v96, v0
	v_mov_b32_e32 v97, v0
	v_mov_b32_e32 v98, v0
	v_mov_b32_e32 v99, v0
	v_mov_b32_e32 v100, v0
	v_mov_b32_e32 v101, v0
	v_mov_b32_e32 v102, v0
	v_mov_b32_e32 v103, v0
	v_mov_b32_e32 v104, v0
	v_mov_b32_e32 v105, v0
	v_mov_b32_e32 v106, v0
	v_mov_b32_e32 v107, v0
	v_mov_b32_e32 v108, v0
	v_mov_b32_e32 v109, v0
	v_mov_b32_e32 v110, v0
	v_mov_b32_e32 v111, v0
	v_mov_b32_e32 v112, v0
	v_mov_b32_e32 v113, v0
	v_mov_b32_e32 v114, v0
	v_mov_b32_e32 v115, v0
	v_mov_b32_e32 v116, v0
	v_mov_b32_e32 v117, v0
	v_mov_b32_e32 v118, v0
	v_mov_b32_e32 v119, v0
	v_mov_b32_e32 v120, v0
	v_mov_b32_e32 v121, v0
	v_mov_b32_e32 v122, v0
	v_mov_b32_e32 v123, v0
	v_mov_b32_e32 v124, v0
	v_mov_b32_e32 v125, v0
	v_mov_b32_e32 v126, v0
	v_mov_b32_e32 v127, v0
	v_add3_u32 v192, v141, v140, 32
	v_add3_u32 v193, v141, v128, 32
	v_add_u32_e32 v194, 0x4020, v142
	v_add_u32_e32 v195, v194, v128
	v_add_u32_e32 v194, v194, v140
	v_subrev_u32_e32 v196, s94, v136
	v_subrev_u32_e32 v200, s94, v134
	v_add_u32_e32 v196, 0x15c88080, v196
	v_add_u32_e32 v200, 0x18a88080, v200
	v_add_u32_e32 v197, 0x10000, v196
	v_add_u32_e32 v198, 0x20000, v196
	v_add_u32_e32 v199, 0x30000, v196
	v_add_u32_e32 v201, 0x10000, v200
	v_readfirstlane_b32 s22, v133
	v_readfirstlane_b32 s23, v139
	s_mov_b64 s[98:99], s[94:95]
	s_add_u32 s100, s94, 64
	s_addc_u32 s101, s95, 0
	s_add_u32 s23, s23, 0x4000
	s_waitcnt vmcnt(6)
	s_barrier
	ds_read_b128 v[144:147], v194 offset:0
	ds_read_b128 v[148:151], v194 offset:2048
	ds_read_b128 v[152:155], v192 offset:0
	ds_read_b128 v[156:159], v192 offset:2048
	ds_read_b128 v[160:163], v192 offset:4096
	ds_read_b128 v[164:167], v192 offset:6144
	s_waitcnt lgkmcnt(2)
	s_setprio 1
	v_mfma_f32_32x32x16_bf16 v[112:127], v[152:155], v[144:147], v[112:127]
	v_mfma_f32_32x32x16_bf16 v[96:111], v[152:155], v[148:151], v[96:111]
	v_mfma_f32_32x32x16_bf16 v[80:95], v[156:159], v[144:147], v[80:95]
	v_mfma_f32_32x32x16_bf16 v[64:79], v[156:159], v[148:151], v[64:79]
	s_setprio 0
	ds_read_b128 v[168:171], v195 offset:0
	ds_read_b128 v[172:175], v195 offset:2048
	ds_read_b128 v[176:179], v193 offset:0
	ds_read_b128 v[180:183], v193 offset:2048
	s_waitcnt lgkmcnt(4)
	s_setprio 1
	v_mfma_f32_32x32x16_bf16 v[48:63], v[160:163], v[144:147], v[48:63]
	v_mfma_f32_32x32x16_bf16 v[32:47], v[160:163], v[148:151], v[32:47]
	v_mfma_f32_32x32x16_bf16 v[16:31], v[164:167], v[144:147], v[16:31]
	v_mfma_f32_32x32x16_bf16 v[0:15], v[164:167], v[148:151], v[0:15]
	s_setprio 0
	ds_read_b128 v[184:187], v193 offset:4096
	ds_read_b128 v[188:191], v193 offset:6144
	s_waitcnt lgkmcnt(2)
	s_setprio 1
	v_mfma_f32_32x32x16_bf16 v[112:127], v[176:179], v[168:171], v[112:127]
	v_mfma_f32_32x32x16_bf16 v[96:111], v[176:179], v[172:175], v[96:111]
	v_mfma_f32_32x32x16_bf16 v[80:95], v[180:183], v[168:171], v[80:95]
	v_mfma_f32_32x32x16_bf16 v[64:79], v[180:183], v[172:175], v[64:79]
	s_setprio 0
	s_mov_b32 s33, 10
.Lp5m_kloop:
	s_waitcnt vmcnt(0) lgkmcnt(0)
	s_barrier
	ds_read_b128 v[144:147], v194 offset:24576
	ds_read_b128 v[148:151], v194 offset:26624
	ds_read_b128 v[152:155], v192 offset:24576
	ds_read_b128 v[156:159], v192 offset:26624
	ds_read_b128 v[160:163], v192 offset:28672
	ds_read_b128 v[164:167], v192 offset:30720
	s_setprio 1
	v_mfma_f32_32x32x16_bf16 v[48:63], v[184:187], v[168:171], v[48:63]
	v_mfma_f32_32x32x16_bf16 v[32:47], v[184:187], v[172:175], v[32:47]
	v_mfma_f32_32x32x16_bf16 v[16:31], v[188:191], v[168:171], v[16:31]
	v_mfma_f32_32x32x16_bf16 v[0:15], v[188:191], v[172:175], v[0:15]
	s_setprio 0
	s_add_u32 m0, s22, 0xc000
	s_nop 0
	global_load_lds_dwordx4 v196, s[98:99]
	s_add_u32 m0, s22, 0x0
	s_nop 0
	global_load_lds_dwordx4 v196, s[100:101]
	s_add_u32 m0, s22, 0xc400
	s_nop 0
	global_load_lds_dwordx4 v197, s[98:99]
	s_add_u32 m0, s22, 0x400
	s_nop 0
	global_load_lds_dwordx4 v197, s[100:101]
	s_waitcnt lgkmcnt(2)
	s_setprio 1
	v_mfma_f32_32x32x16_bf16 v[112:127], v[152:155], v[144:147], v[112:127]
	v_mfma_f32_32x32x16_bf16 v[96:111], v[152:155], v[148:151], v[96:111]
	v_mfma_f32_32x32x16_bf16 v[80:95], v[156:159], v[144:147], v[80:95]
	v_mfma_f32_32x32x16_bf16 v[64:79], v[156:159], v[148:151], v[64:79]
	s_setprio 0
	ds_read_b128 v[168:171], v195 offset:24576
	ds_read_b128 v[172:175], v195 offset:26624
	ds_read_b128 v[176:179], v193 offset:24576
	ds_read_b128 v[180:183], v193 offset:26624
	s_add_u32 m0, s22, 0xc800
	s_nop 0
	global_load_lds_dwordx4 v198, s[98:99]
	s_add_u32 m0, s22, 0x800
	s_nop 0
	global_load_lds_dwordx4 v198, s[100:101]
	s_add_u32 m0, s22, 0xcc00
	s_nop 0
	global_load_lds_dwordx4 v199, s[98:99]
	s_add_u32 m0, s22, 0xc00
	s_nop 0
	global_load_lds_dwordx4 v199, s[100:101]
	s_waitcnt lgkmcnt(4)
	s_setprio 1
	v_mfma_f32_32x32x16_bf16 v[48:63], v[160:163], v[144:147], v[48:63]
	v_mfma_f32_32x32x16_bf16 v[32:47], v[160:163], v[148:151], v[32:47]
	v_mfma_f32_32x32x16_bf16 v[16:31], v[164:167], v[144:147], v[16:31]
	v_mfma_f32_32x32x16_bf16 v[0:15], v[164:167], v[148:151], v[0:15]
	s_setprio 0
	ds_read_b128 v[184:187], v193 offset:28672
	ds_read_b128 v[188:191], v193 offset:30720
	s_add_u32 m0, s23, 0xc000
	s_nop 0
	global_load_lds_dwordx4 v200, s[98:99]
	s_add_u32 m0, s23, 0x0
	s_nop 0
	global_load_lds_dwordx4 v200, s[100:101]
	s_add_u32 m0, s23, 0xc400
	s_nop 0
	global_load_lds_dwordx4 v201, s[98:99]
	s_add_u32 m0, s23, 0x400
	s_nop 0
	global_load_lds_dwordx4 v201, s[100:101]
	s_add_u32 s98, s98, 128
	s_addc_u32 s99, s99, 0
	s_add_u32 s100, s100, 128
	s_addc_u32 s101, s101, 0
	s_waitcnt lgkmcnt(2)
	s_setprio 1
	v_mfma_f32_32x32x16_bf16 v[112:127], v[176:179], v[168:171], v[112:127]
	v_mfma_f32_32x32x16_bf16 v[96:111], v[176:179], v[172:175], v[96:111]
	v_mfma_f32_32x32x16_bf16 v[80:95], v[180:183], v[168:171], v[80:95]
	v_mfma_f32_32x32x16_bf16 v[64:79], v[180:183], v[172:175], v[64:79]
	s_setprio 0
	s_waitcnt vmcnt(0) lgkmcnt(0)
	s_barrier
	ds_read_b128 v[144:147], v194 offset:49152
	ds_read_b128 v[148:151], v194 offset:51200
	ds_read_b128 v[152:155], v192 offset:49152
	ds_read_b128 v[156:159], v192 offset:51200
	ds_read_b128 v[160:163], v192 offset:53248
	ds_read_b128 v[164:167], v192 offset:55296
	s_setprio 1
	v_mfma_f32_32x32x16_bf16 v[48:63], v[184:187], v[168:171], v[48:63]
	v_mfma_f32_32x32x16_bf16 v[32:47], v[184:187], v[172:175], v[32:47]
	v_mfma_f32_32x32x16_bf16 v[16:31], v[188:191], v[168:171], v[16:31]
	v_mfma_f32_32x32x16_bf16 v[0:15], v[188:191], v[172:175], v[0:15]
	s_setprio 0
	s_waitcnt lgkmcnt(2)
	s_setprio 1
	v_mfma_f32_32x32x16_bf16 v[112:127], v[152:155], v[144:147], v[112:127]
	v_mfma_f32_32x32x16_bf16 v[96:111], v[152:155], v[148:151], v[96:111]
	v_mfma_f32_32x32x16_bf16 v[80:95], v[156:159], v[144:147], v[80:95]
	v_mfma_f32_32x32x16_bf16 v[64:79], v[156:159], v[148:151], v[64:79]
	s_setprio 0
	ds_read_b128 v[168:171], v195 offset:49152
	ds_read_b128 v[172:175], v195 offset:51200
	ds_read_b128 v[176:179], v193 offset:49152
	ds_read_b128 v[180:183], v193 offset:51200
	s_waitcnt lgkmcnt(4)
	s_setprio 1
	v_mfma_f32_32x32x16_bf16 v[48:63], v[160:163], v[144:147], v[48:63]
	v_mfma_f32_32x32x16_bf16 v[32:47], v[160:163], v[148:151], v[32:47]
	v_mfma_f32_32x32x16_bf16 v[16:31], v[164:167], v[144:147], v[16:31]
	v_mfma_f32_32x32x16_bf16 v[0:15], v[164:167], v[148:151], v[0:15]
	s_setprio 0
	ds_read_b128 v[184:187], v193 offset:53248
	ds_read_b128 v[188:191], v193 offset:55296
	s_waitcnt lgkmcnt(2)
	s_setprio 1
	v_mfma_f32_32x32x16_bf16 v[112:127], v[176:179], v[168:171], v[112:127]
	v_mfma_f32_32x32x16_bf16 v[96:111], v[176:179], v[172:175], v[96:111]
	v_mfma_f32_32x32x16_bf16 v[80:95], v[180:183], v[168:171], v[80:95]
	v_mfma_f32_32x32x16_bf16 v[64:79], v[180:183], v[172:175], v[64:79]
	s_setprio 0
	s_waitcnt vmcnt(0) lgkmcnt(0)
	s_barrier
	ds_read_b128 v[144:147], v194 offset:0
	ds_read_b128 v[148:151], v194 offset:2048
	ds_read_b128 v[152:155], v192 offset:0
	ds_read_b128 v[156:159], v192 offset:2048
	ds_read_b128 v[160:163], v192 offset:4096
	ds_read_b128 v[164:167], v192 offset:6144
	s_setprio 1
	v_mfma_f32_32x32x16_bf16 v[48:63], v[184:187], v[168:171], v[48:63]
	v_mfma_f32_32x32x16_bf16 v[32:47], v[184:187], v[172:175], v[32:47]
	v_mfma_f32_32x32x16_bf16 v[16:31], v[188:191], v[168:171], v[16:31]
	v_mfma_f32_32x32x16_bf16 v[0:15], v[188:191], v[172:175], v[0:15]
	s_setprio 0
	s_add_u32 m0, s22, 0x6000
	s_nop 0
	global_load_lds_dwordx4 v196, s[98:99]
	s_add_u32 m0, s22, 0xc000
	s_nop 0
	global_load_lds_dwordx4 v196, s[100:101]
	s_add_u32 m0, s22, 0x6400
	s_nop 0
	global_load_lds_dwordx4 v197, s[98:99]
	s_add_u32 m0, s22, 0xc400
	s_nop 0
	global_load_lds_dwordx4 v197, s[100:101]
	s_waitcnt lgkmcnt(2)
	s_setprio 1
	v_mfma_f32_32x32x16_bf16 v[112:127], v[152:155], v[144:147], v[112:127]
	v_mfma_f32_32x32x16_bf16 v[96:111], v[152:155], v[148:151], v[96:111]
	v_mfma_f32_32x32x16_bf16 v[80:95], v[156:159], v[144:147], v[80:95]
	v_mfma_f32_32x32x16_bf16 v[64:79], v[156:159], v[148:151], v[64:79]
	s_setprio 0
	ds_read_b128 v[168:171], v195 offset:0
	ds_read_b128 v[172:175], v195 offset:2048
	ds_read_b128 v[176:179], v193 offset:0
	ds_read_b128 v[180:183], v193 offset:2048
	s_add_u32 m0, s22, 0x6800
	s_nop 0
	global_load_lds_dwordx4 v198, s[98:99]
	s_add_u32 m0, s22, 0xc800
	s_nop 0
	global_load_lds_dwordx4 v198, s[100:101]
	s_add_u32 m0, s22, 0x6c00
	s_nop 0
	global_load_lds_dwordx4 v199, s[98:99]
	s_add_u32 m0, s22, 0xcc00
	s_nop 0
	global_load_lds_dwordx4 v199, s[100:101]
	s_waitcnt lgkmcnt(4)
	s_setprio 1
	v_mfma_f32_32x32x16_bf16 v[48:63], v[160:163], v[144:147], v[48:63]
	v_mfma_f32_32x32x16_bf16 v[32:47], v[160:163], v[148:151], v[32:47]
	v_mfma_f32_32x32x16_bf16 v[16:31], v[164:167], v[144:147], v[16:31]
	v_mfma_f32_32x32x16_bf16 v[0:15], v[164:167], v[148:151], v[0:15]
	s_setprio 0
	ds_read_b128 v[184:187], v193 offset:4096
	ds_read_b128 v[188:191], v193 offset:6144
	s_add_u32 m0, s23, 0x6000
	s_nop 0
	global_load_lds_dwordx4 v200, s[98:99]
	s_add_u32 m0, s23, 0xc000
	s_nop 0
	global_load_lds_dwordx4 v200, s[100:101]
	s_add_u32 m0, s23, 0x6400
	s_nop 0
	global_load_lds_dwordx4 v201, s[98:99]
	s_add_u32 m0, s23, 0xc400
	s_nop 0
	global_load_lds_dwordx4 v201, s[100:101]
	s_add_u32 s98, s98, 128
	s_addc_u32 s99, s99, 0
	s_add_u32 s100, s100, 128
	s_addc_u32 s101, s101, 0
	s_waitcnt lgkmcnt(2)
	s_setprio 1
	v_mfma_f32_32x32x16_bf16 v[112:127], v[176:179], v[168:171], v[112:127]
	v_mfma_f32_32x32x16_bf16 v[96:111], v[176:179], v[172:175], v[96:111]
	v_mfma_f32_32x32x16_bf16 v[80:95], v[180:183], v[168:171], v[80:95]
	v_mfma_f32_32x32x16_bf16 v[64:79], v[180:183], v[172:175], v[64:79]
	s_setprio 0
	s_waitcnt vmcnt(0) lgkmcnt(0)
	s_barrier
	ds_read_b128 v[144:147], v194 offset:24576
	ds_read_b128 v[148:151], v194 offset:26624
	ds_read_b128 v[152:155], v192 offset:24576
	ds_read_b128 v[156:159], v192 offset:26624
	ds_read_b128 v[160:163], v192 offset:28672
	ds_read_b128 v[164:167], v192 offset:30720
	s_setprio 1
	v_mfma_f32_32x32x16_bf16 v[48:63], v[184:187], v[168:171], v[48:63]
	v_mfma_f32_32x32x16_bf16 v[32:47], v[184:187], v[172:175], v[32:47]
	v_mfma_f32_32x32x16_bf16 v[16:31], v[188:191], v[168:171], v[16:31]
	v_mfma_f32_32x32x16_bf16 v[0:15], v[188:191], v[172:175], v[0:15]
	s_setprio 0
	s_waitcnt lgkmcnt(2)
	s_setprio 1
	v_mfma_f32_32x32x16_bf16 v[112:127], v[152:155], v[144:147], v[112:127]
	v_mfma_f32_32x32x16_bf16 v[96:111], v[152:155], v[148:151], v[96:111]
	v_mfma_f32_32x32x16_bf16 v[80:95], v[156:159], v[144:147], v[80:95]
	v_mfma_f32_32x32x16_bf16 v[64:79], v[156:159], v[148:151], v[64:79]
	s_setprio 0
	ds_read_b128 v[168:171], v195 offset:24576
	ds_read_b128 v[172:175], v195 offset:26624
	ds_read_b128 v[176:179], v193 offset:24576
	ds_read_b128 v[180:183], v193 offset:26624
	s_waitcnt lgkmcnt(4)
	s_setprio 1
	v_mfma_f32_32x32x16_bf16 v[48:63], v[160:163], v[144:147], v[48:63]
	v_mfma_f32_32x32x16_bf16 v[32:47], v[160:163], v[148:151], v[32:47]
	v_mfma_f32_32x32x16_bf16 v[16:31], v[164:167], v[144:147], v[16:31]
	v_mfma_f32_32x32x16_bf16 v[0:15], v[164:167], v[148:151], v[0:15]
	s_setprio 0
	ds_read_b128 v[184:187], v193 offset:28672
	ds_read_b128 v[188:191], v193 offset:30720
	s_waitcnt lgkmcnt(2)
	s_setprio 1
	v_mfma_f32_32x32x16_bf16 v[112:127], v[176:179], v[168:171], v[112:127]
	v_mfma_f32_32x32x16_bf16 v[96:111], v[176:179], v[172:175], v[96:111]
	v_mfma_f32_32x32x16_bf16 v[80:95], v[180:183], v[168:171], v[80:95]
	v_mfma_f32_32x32x16_bf16 v[64:79], v[180:183], v[172:175], v[64:79]
	s_setprio 0
	s_waitcnt vmcnt(0) lgkmcnt(0)
	s_barrier
	ds_read_b128 v[144:147], v194 offset:49152
	ds_read_b128 v[148:151], v194 offset:51200
	ds_read_b128 v[152:155], v192 offset:49152
	ds_read_b128 v[156:159], v192 offset:51200
	ds_read_b128 v[160:163], v192 offset:53248
	ds_read_b128 v[164:167], v192 offset:55296
	s_setprio 1
	v_mfma_f32_32x32x16_bf16 v[48:63], v[184:187], v[168:171], v[48:63]
	v_mfma_f32_32x32x16_bf16 v[32:47], v[184:187], v[172:175], v[32:47]
	v_mfma_f32_32x32x16_bf16 v[16:31], v[188:191], v[168:171], v[16:31]
	v_mfma_f32_32x32x16_bf16 v[0:15], v[188:191], v[172:175], v[0:15]
	s_setprio 0
	s_add_u32 m0, s22, 0x0
	s_nop 0
	global_load_lds_dwordx4 v196, s[98:99]
	s_add_u32 m0, s22, 0x6000
	s_nop 0
	global_load_lds_dwordx4 v196, s[100:101]
	s_add_u32 m0, s22, 0x400
	s_nop 0
	global_load_lds_dwordx4 v197, s[98:99]
	s_add_u32 m0, s22, 0x6400
	s_nop 0
	global_load_lds_dwordx4 v197, s[100:101]
	s_waitcnt lgkmcnt(2)
	s_setprio 1
	v_mfma_f32_32x32x16_bf16 v[112:127], v[152:155], v[144:147], v[112:127]
	v_mfma_f32_32x32x16_bf16 v[96:111], v[152:155], v[148:151], v[96:111]
	v_mfma_f32_32x32x16_bf16 v[80:95], v[156:159], v[144:147], v[80:95]
	v_mfma_f32_32x32x16_bf16 v[64:79], v[156:159], v[148:151], v[64:79]
	s_setprio 0
	ds_read_b128 v[168:171], v195 offset:49152
	ds_read_b128 v[172:175], v195 offset:51200
	ds_read_b128 v[176:179], v193 offset:49152
	ds_read_b128 v[180:183], v193 offset:51200
	s_add_u32 m0, s22, 0x800
	s_nop 0
	global_load_lds_dwordx4 v198, s[98:99]
	s_add_u32 m0, s22, 0x6800
	s_nop 0
	global_load_lds_dwordx4 v198, s[100:101]
	s_add_u32 m0, s22, 0xc00
	s_nop 0
	global_load_lds_dwordx4 v199, s[98:99]
	s_add_u32 m0, s22, 0x6c00
	s_nop 0
	global_load_lds_dwordx4 v199, s[100:101]
	s_waitcnt lgkmcnt(4)
	s_setprio 1
	v_mfma_f32_32x32x16_bf16 v[48:63], v[160:163], v[144:147], v[48:63]
	v_mfma_f32_32x32x16_bf16 v[32:47], v[160:163], v[148:151], v[32:47]
	v_mfma_f32_32x32x16_bf16 v[16:31], v[164:167], v[144:147], v[16:31]
	v_mfma_f32_32x32x16_bf16 v[0:15], v[164:167], v[148:151], v[0:15]
	s_setprio 0
	ds_read_b128 v[184:187], v193 offset:53248
	ds_read_b128 v[188:191], v193 offset:55296
	s_add_u32 m0, s23, 0x0
	s_nop 0
	global_load_lds_dwordx4 v200, s[98:99]
	s_add_u32 m0, s23, 0x6000
	s_nop 0
	global_load_lds_dwordx4 v200, s[100:101]
	s_add_u32 m0, s23, 0x400
	s_nop 0
	global_load_lds_dwordx4 v201, s[98:99]
	s_add_u32 m0, s23, 0x6400
	s_nop 0
	global_load_lds_dwordx4 v201, s[100:101]
	s_add_u32 s98, s98, 128
	s_addc_u32 s99, s99, 0
	s_add_u32 s100, s100, 128
	s_addc_u32 s101, s101, 0
	s_waitcnt lgkmcnt(2)
	s_setprio 1
	v_mfma_f32_32x32x16_bf16 v[112:127], v[176:179], v[168:171], v[112:127]
	v_mfma_f32_32x32x16_bf16 v[96:111], v[176:179], v[172:175], v[96:111]
	v_mfma_f32_32x32x16_bf16 v[80:95], v[180:183], v[168:171], v[80:95]
	v_mfma_f32_32x32x16_bf16 v[64:79], v[180:183], v[172:175], v[64:79]
	s_setprio 0
	s_waitcnt vmcnt(0) lgkmcnt(0)
	s_barrier
	ds_read_b128 v[144:147], v194 offset:0
	ds_read_b128 v[148:151], v194 offset:2048
	ds_read_b128 v[152:155], v192 offset:0
	ds_read_b128 v[156:159], v192 offset:2048
	ds_read_b128 v[160:163], v192 offset:4096
	ds_read_b128 v[164:167], v192 offset:6144
	s_setprio 1
	v_mfma_f32_32x32x16_bf16 v[48:63], v[184:187], v[168:171], v[48:63]
	v_mfma_f32_32x32x16_bf16 v[32:47], v[184:187], v[172:175], v[32:47]
	v_mfma_f32_32x32x16_bf16 v[16:31], v[188:191], v[168:171], v[16:31]
	v_mfma_f32_32x32x16_bf16 v[0:15], v[188:191], v[172:175], v[0:15]
	s_setprio 0
	s_waitcnt lgkmcnt(2)
	s_setprio 1
	v_mfma_f32_32x32x16_bf16 v[112:127], v[152:155], v[144:147], v[112:127]
	v_mfma_f32_32x32x16_bf16 v[96:111], v[152:155], v[148:151], v[96:111]
	v_mfma_f32_32x32x16_bf16 v[80:95], v[156:159], v[144:147], v[80:95]
	v_mfma_f32_32x32x16_bf16 v[64:79], v[156:159], v[148:151], v[64:79]
	s_setprio 0
	ds_read_b128 v[168:171], v195 offset:0
	ds_read_b128 v[172:175], v195 offset:2048
	ds_read_b128 v[176:179], v193 offset:0
	ds_read_b128 v[180:183], v193 offset:2048
	s_waitcnt lgkmcnt(4)
	s_setprio 1
	v_mfma_f32_32x32x16_bf16 v[48:63], v[160:163], v[144:147], v[48:63]
	v_mfma_f32_32x32x16_bf16 v[32:47], v[160:163], v[148:151], v[32:47]
	v_mfma_f32_32x32x16_bf16 v[16:31], v[164:167], v[144:147], v[16:31]
	v_mfma_f32_32x32x16_bf16 v[0:15], v[164:167], v[148:151], v[0:15]
	s_setprio 0
	ds_read_b128 v[184:187], v193 offset:4096
	ds_read_b128 v[188:191], v193 offset:6144
	s_waitcnt lgkmcnt(2)
	s_setprio 1
	v_mfma_f32_32x32x16_bf16 v[112:127], v[176:179], v[168:171], v[112:127]
	v_mfma_f32_32x32x16_bf16 v[96:111], v[176:179], v[172:175], v[96:111]
	v_mfma_f32_32x32x16_bf16 v[80:95], v[180:183], v[168:171], v[80:95]
	v_mfma_f32_32x32x16_bf16 v[64:79], v[180:183], v[172:175], v[64:79]
	s_setprio 0
	s_sub_u32 s33, s33, 1
	s_cmp_lg_u32 s33, 0
	s_cbranch_scc1 .Lp5m_kloop
	s_waitcnt vmcnt(0) lgkmcnt(0)
	s_barrier
	ds_read_b128 v[144:147], v194 offset:24576
	ds_read_b128 v[148:151], v194 offset:26624
	ds_read_b128 v[152:155], v192 offset:24576
	ds_read_b128 v[156:159], v192 offset:26624
	ds_read_b128 v[160:163], v192 offset:28672
	ds_read_b128 v[164:167], v192 offset:30720
	s_setprio 1
	v_mfma_f32_32x32x16_bf16 v[48:63], v[184:187], v[168:171], v[48:63]
	v_mfma_f32_32x32x16_bf16 v[32:47], v[184:187], v[172:175], v[32:47]
	v_mfma_f32_32x32x16_bf16 v[16:31], v[188:191], v[168:171], v[16:31]
	v_mfma_f32_32x32x16_bf16 v[0:15], v[188:191], v[172:175], v[0:15]
	s_setprio 0
	s_add_u32 m0, s22, 0xc000
	s_nop 0
	global_load_lds_dwordx4 v196, s[98:99]
	s_add_u32 m0, s22, 0x0
	s_nop 0
	global_load_lds_dwordx4 v196, s[100:101]
	s_add_u32 m0, s22, 0xc400
	s_nop 0
	global_load_lds_dwordx4 v197, s[98:99]
	s_add_u32 m0, s22, 0x400
	s_nop 0
	global_load_lds_dwordx4 v197, s[100:101]
	s_waitcnt lgkmcnt(2)
	s_setprio 1
	v_mfma_f32_32x32x16_bf16 v[112:127], v[152:155], v[144:147], v[112:127]
	v_mfma_f32_32x32x16_bf16 v[96:111], v[152:155], v[148:151], v[96:111]
	v_mfma_f32_32x32x16_bf16 v[80:95], v[156:159], v[144:147], v[80:95]
	v_mfma_f32_32x32x16_bf16 v[64:79], v[156:159], v[148:151], v[64:79]
	s_setprio 0
	ds_read_b128 v[168:171], v195 offset:24576
	ds_read_b128 v[172:175], v195 offset:26624
	ds_read_b128 v[176:179], v193 offset:24576
	ds_read_b128 v[180:183], v193 offset:26624
	s_add_u32 m0, s22, 0xc800
	s_nop 0
	global_load_lds_dwordx4 v198, s[98:99]
	s_add_u32 m0, s22, 0x800
	s_nop 0
	global_load_lds_dwordx4 v198, s[100:101]
	s_add_u32 m0, s22, 0xcc00
	s_nop 0
	global_load_lds_dwordx4 v199, s[98:99]
	s_add_u32 m0, s22, 0xc00
	s_nop 0
	global_load_lds_dwordx4 v199, s[100:101]
	s_waitcnt lgkmcnt(4)
	s_setprio 1
	v_mfma_f32_32x32x16_bf16 v[48:63], v[160:163], v[144:147], v[48:63]
	v_mfma_f32_32x32x16_bf16 v[32:47], v[160:163], v[148:151], v[32:47]
	v_mfma_f32_32x32x16_bf16 v[16:31], v[164:167], v[144:147], v[16:31]
	v_mfma_f32_32x32x16_bf16 v[0:15], v[164:167], v[148:151], v[0:15]
	s_setprio 0
	ds_read_b128 v[184:187], v193 offset:28672
	ds_read_b128 v[188:191], v193 offset:30720
	s_add_u32 m0, s23, 0xc000
	s_nop 0
	global_load_lds_dwordx4 v200, s[98:99]
	s_add_u32 m0, s23, 0x0
	s_nop 0
	global_load_lds_dwordx4 v200, s[100:101]
	s_add_u32 m0, s23, 0xc400
	s_nop 0
	global_load_lds_dwordx4 v201, s[98:99]
	s_add_u32 m0, s23, 0x400
	s_nop 0
	global_load_lds_dwordx4 v201, s[100:101]
	s_add_u32 s98, s98, 128
	s_addc_u32 s99, s99, 0
	s_add_u32 s100, s100, 128
	s_addc_u32 s101, s101, 0
	s_waitcnt lgkmcnt(2)
	s_setprio 1
	v_mfma_f32_32x32x16_bf16 v[112:127], v[176:179], v[168:171], v[112:127]
	v_mfma_f32_32x32x16_bf16 v[96:111], v[176:179], v[172:175], v[96:111]
	v_mfma_f32_32x32x16_bf16 v[80:95], v[180:183], v[168:171], v[80:95]
	v_mfma_f32_32x32x16_bf16 v[64:79], v[180:183], v[172:175], v[64:79]
	s_setprio 0
	s_waitcnt vmcnt(0) lgkmcnt(0)
	s_barrier
	ds_read_b128 v[144:147], v194 offset:49152
	ds_read_b128 v[148:151], v194 offset:51200
	ds_read_b128 v[152:155], v192 offset:49152
	ds_read_b128 v[156:159], v192 offset:51200
	ds_read_b128 v[160:163], v192 offset:53248
	ds_read_b128 v[164:167], v192 offset:55296
	s_setprio 1
	v_mfma_f32_32x32x16_bf16 v[48:63], v[184:187], v[168:171], v[48:63]
	v_mfma_f32_32x32x16_bf16 v[32:47], v[184:187], v[172:175], v[32:47]
	v_mfma_f32_32x32x16_bf16 v[16:31], v[188:191], v[168:171], v[16:31]
	v_mfma_f32_32x32x16_bf16 v[0:15], v[188:191], v[172:175], v[0:15]
	s_setprio 0
	s_waitcnt lgkmcnt(2)
	s_setprio 1
	v_mfma_f32_32x32x16_bf16 v[112:127], v[152:155], v[144:147], v[112:127]
	v_mfma_f32_32x32x16_bf16 v[96:111], v[152:155], v[148:151], v[96:111]
	v_mfma_f32_32x32x16_bf16 v[80:95], v[156:159], v[144:147], v[80:95]
	v_mfma_f32_32x32x16_bf16 v[64:79], v[156:159], v[148:151], v[64:79]
	s_setprio 0
	ds_read_b128 v[168:171], v195 offset:49152
	ds_read_b128 v[172:175], v195 offset:51200
	ds_read_b128 v[176:179], v193 offset:49152
	ds_read_b128 v[180:183], v193 offset:51200
	s_waitcnt lgkmcnt(4)
	s_setprio 1
	v_mfma_f32_32x32x16_bf16 v[48:63], v[160:163], v[144:147], v[48:63]
	v_mfma_f32_32x32x16_bf16 v[32:47], v[160:163], v[148:151], v[32:47]
	v_mfma_f32_32x32x16_bf16 v[16:31], v[164:167], v[144:147], v[16:31]
	v_mfma_f32_32x32x16_bf16 v[0:15], v[164:167], v[148:151], v[0:15]
	s_setprio 0
	ds_read_b128 v[184:187], v193 offset:53248
	ds_read_b128 v[188:191], v193 offset:55296
	s_waitcnt lgkmcnt(2)
	s_setprio 1
	v_mfma_f32_32x32x16_bf16 v[112:127], v[176:179], v[168:171], v[112:127]
	v_mfma_f32_32x32x16_bf16 v[96:111], v[176:179], v[172:175], v[96:111]
	v_mfma_f32_32x32x16_bf16 v[80:95], v[180:183], v[168:171], v[80:95]
	v_mfma_f32_32x32x16_bf16 v[64:79], v[180:183], v[172:175], v[64:79]
	s_setprio 0
	s_waitcnt vmcnt(0) lgkmcnt(0)
	s_barrier
	ds_read_b128 v[144:147], v194 offset:0
	ds_read_b128 v[148:151], v194 offset:2048
	ds_read_b128 v[152:155], v192 offset:0
	ds_read_b128 v[156:159], v192 offset:2048
	ds_read_b128 v[160:163], v192 offset:4096
	ds_read_b128 v[164:167], v192 offset:6144
	s_setprio 1
	v_mfma_f32_32x32x16_bf16 v[48:63], v[184:187], v[168:171], v[48:63]
	v_mfma_f32_32x32x16_bf16 v[32:47], v[184:187], v[172:175], v[32:47]
	v_mfma_f32_32x32x16_bf16 v[16:31], v[188:191], v[168:171], v[16:31]
	v_mfma_f32_32x32x16_bf16 v[0:15], v[188:191], v[172:175], v[0:15]
	s_setprio 0
	s_waitcnt lgkmcnt(2)
	s_setprio 1
	v_mfma_f32_32x32x16_bf16 v[112:127], v[152:155], v[144:147], v[112:127]
	v_mfma_f32_32x32x16_bf16 v[96:111], v[152:155], v[148:151], v[96:111]
	v_mfma_f32_32x32x16_bf16 v[80:95], v[156:159], v[144:147], v[80:95]
	v_mfma_f32_32x32x16_bf16 v[64:79], v[156:159], v[148:151], v[64:79]
	s_setprio 0
	ds_read_b128 v[168:171], v195 offset:0
	ds_read_b128 v[172:175], v195 offset:2048
	ds_read_b128 v[176:179], v193 offset:0
	ds_read_b128 v[180:183], v193 offset:2048
	s_waitcnt lgkmcnt(4)
	s_setprio 1
	v_mfma_f32_32x32x16_bf16 v[48:63], v[160:163], v[144:147], v[48:63]
	v_mfma_f32_32x32x16_bf16 v[32:47], v[160:163], v[148:151], v[32:47]
	v_mfma_f32_32x32x16_bf16 v[16:31], v[164:167], v[144:147], v[16:31]
	v_mfma_f32_32x32x16_bf16 v[0:15], v[164:167], v[148:151], v[0:15]
	s_setprio 0
	ds_read_b128 v[184:187], v193 offset:4096
	ds_read_b128 v[188:191], v193 offset:6144
	s_waitcnt lgkmcnt(2)
	s_setprio 1
	v_mfma_f32_32x32x16_bf16 v[112:127], v[176:179], v[168:171], v[112:127]
	v_mfma_f32_32x32x16_bf16 v[96:111], v[176:179], v[172:175], v[96:111]
	v_mfma_f32_32x32x16_bf16 v[80:95], v[180:183], v[168:171], v[80:95]
	v_mfma_f32_32x32x16_bf16 v[64:79], v[180:183], v[172:175], v[64:79]
	s_setprio 0
	s_waitcnt lgkmcnt(0)
	s_setprio 1
	v_mfma_f32_32x32x16_bf16 v[48:63], v[184:187], v[168:171], v[48:63]
	v_mfma_f32_32x32x16_bf16 v[32:47], v[184:187], v[172:175], v[32:47]
	v_mfma_f32_32x32x16_bf16 v[16:31], v[188:191], v[168:171], v[16:31]
	v_mfma_f32_32x32x16_bf16 v[0:15], v[188:191], v[172:175], v[0:15]
	s_setprio 0
	s_load_dwordx16 s[60:75], s[0:1], 0x0
	v_add_u32_e32 v128, 0xffffe000, v132
	v_lshlrev_b64 v[134:135], 2, v[130:131]
	v_lshlrev_b64 v[132:133], 13, v[128:129]
	v_cmp_gt_i32_e32 vcc, 32, v138
	s_waitcnt lgkmcnt(0)
	v_lshl_add_u64 v[136:137], s[60:61], 0, v[134:135]
	v_lshl_add_u64 v[132:133], s[62:63], 0, v[132:133]
	v_lshlrev_b64 v[130:131], 1, v[130:131]
	v_cndmask_b32_e32 v133, v133, v137, vcc
	v_cndmask_b32_e32 v132, v132, v136, vcc
	v_lshl_add_u64 v[136:137], s[8:9], 0, v[130:131]
	v_mov_b32_e32 v130, v204
	s_waitcnt vmcnt(0)
	s_barrier
	s_load_dwordx16 s[60:75], s[0:1], 0xc0
	s_lshl_b32 s40, s40, 7
	v_and_b32_e32 v131, 0x1fff80, v130
	v_and_b32_e32 v138, 0x5f, v130
	v_lshrrev_b32_e32 v130, 3, v130
	v_and_or_b32 v130, v130, 4, v131
	s_ashr_i32 s41, s40, 31
	v_lshl_or_b32 v130, v130, 11, v138
	s_lshl_b64 s[42:43], s[40:41], 2
	v_ashrrev_i32_e32 v131, 31, v130
	v_lshl_add_u64 v[132:133], v[132:133], 0, s[42:43]
	s_waitcnt lgkmcnt(0)
	s_add_u32 s22, s66, s42
	v_lshlrev_b64 v[140:141], 2, v[130:131]
	s_addc_u32 s23, s67, s43
	v_lshlrev_b32_e32 v128, 2, v138
	v_lshl_add_u64 v[138:139], v[132:133], 0, v[140:141]
	v_or_b32_e32 v188, 0x800, v130
	global_load_dword v209, v128, s[22:23]
	s_nop 0
	global_load_dword v128, v128, s[22:23] offset:128
	v_ashrrev_i32_e32 v189, 31, v188
	global_load_dword v142, v[138:139], off
	v_lshlrev_b64 v[202:203], 2, v[188:189]
	v_lshl_add_u64 v[144:145], v[132:133], 0, v[202:203]
	v_or_b32_e32 v184, 0x1000, v130
	global_load_dword v240, v[144:145], off
	v_ashrrev_i32_e32 v185, 31, v184
	v_lshlrev_b64 v[200:201], 2, v[184:185]
	v_lshl_add_u64 v[144:145], v[132:133], 0, v[200:201]
	v_or_b32_e32 v178, 0x1800, v130
	global_load_dword v239, v[144:145], off
	v_ashrrev_i32_e32 v179, 31, v178
	v_lshlrev_b64 v[198:199], 2, v[178:179]
	v_lshl_add_u64 v[144:145], v[132:133], 0, v[198:199]
	v_or_b32_e32 v174, 0x4000, v130
	global_load_dword v238, v[144:145], off
	v_ashrrev_i32_e32 v175, 31, v174
	v_lshlrev_b64 v[196:197], 2, v[174:175]
	v_lshl_add_u64 v[144:145], v[132:133], 0, v[196:197]
	v_or_b32_e32 v170, 0x4800, v130
	global_load_dword v237, v[144:145], off
	v_ashrrev_i32_e32 v171, 31, v170
	v_lshlrev_b64 v[194:195], 2, v[170:171]
	v_lshl_add_u64 v[144:145], v[132:133], 0, v[194:195]
	v_or_b32_e32 v166, 0x5000, v130
	global_load_dword v236, v[144:145], off
	v_ashrrev_i32_e32 v167, 31, v166
	v_lshlrev_b64 v[192:193], 2, v[166:167]
	v_lshl_add_u64 v[144:145], v[132:133], 0, v[192:193]
	v_or_b32_e32 v162, 0x5800, v130
	global_load_dword v235, v[144:145], off
	v_ashrrev_i32_e32 v163, 31, v162
	v_lshlrev_b64 v[190:191], 2, v[162:163]
	v_lshl_add_u64 v[144:145], v[132:133], 0, v[190:191]
	v_or_b32_e32 v158, 0x8000, v130
	global_load_dword v233, v[144:145], off
	v_ashrrev_i32_e32 v159, 31, v158
	v_lshlrev_b64 v[186:187], 2, v[158:159]
	v_lshl_add_u64 v[144:145], v[132:133], 0, v[186:187]
	v_or_b32_e32 v154, 0x8800, v130
	global_load_dword v232, v[144:145], off
	v_ashrrev_i32_e32 v155, 31, v154
	v_lshlrev_b64 v[180:181], 2, v[154:155]
	v_lshl_add_u64 v[144:145], v[132:133], 0, v[180:181]
	v_or_b32_e32 v152, 0x9000, v130
	global_load_dword v230, v[144:145], off
	v_ashrrev_i32_e32 v153, 31, v152
	v_lshlrev_b64 v[176:177], 2, v[152:153]
	v_lshl_add_u64 v[144:145], v[132:133], 0, v[176:177]
	v_or_b32_e32 v150, 0x9800, v130
	global_load_dword v229, v[144:145], off
	v_ashrrev_i32_e32 v151, 31, v150
	v_lshlrev_b64 v[172:173], 2, v[150:151]
	v_lshl_add_u64 v[144:145], v[132:133], 0, v[172:173]
	v_or_b32_e32 v148, 0xc000, v130
	global_load_dword v228, v[144:145], off
	v_ashrrev_i32_e32 v149, 31, v148
	v_or_b32_e32 v146, 0xc800, v130
	v_lshlrev_b64 v[168:169], 2, v[148:149]
	v_ashrrev_i32_e32 v147, 31, v146
	v_lshl_add_u64 v[144:145], v[132:133], 0, v[168:169]
	v_lshlrev_b64 v[164:165], 2, v[146:147]
	global_load_dword v227, v[144:145], off
	v_lshl_add_u64 v[144:145], v[132:133], 0, v[164:165]
	global_load_dword v226, v[144:145], off
	v_or_b32_e32 v144, 0xd000, v130
	v_ashrrev_i32_e32 v145, 31, v144
	v_lshlrev_b64 v[160:161], 2, v[144:145]
	v_lshl_add_u64 v[156:157], v[132:133], 0, v[160:161]
	global_load_dword v234, v[156:157], off
	v_or_b32_e32 v156, 0xd800, v130
	v_ashrrev_i32_e32 v157, 31, v156
	v_lshlrev_b64 v[182:183], 2, v[156:157]
	v_lshl_add_u64 v[210:211], v[132:133], 0, v[182:183]
	global_load_dword v231, v[210:211], off
	s_lshl_b64 s[22:23], s[40:41], 1
	v_lshl_add_u64 v[136:137], v[136:137], 0, s[22:23]
	s_movk_i32 s22, 0x2000
	v_add_co_u32_e32 v212, vcc, s22, v138
	s_movk_i32 s22, 0x4000
	s_nop 0
	v_addc_co_u32_e32 v213, vcc, 0, v139, vcc
	global_load_dword v210, v[138:139], off offset:128
	global_load_dword v211, v[212:213], off offset:128
	v_add_co_u32_e32 v212, vcc, s22, v138
	s_movk_i32 s22, 0x6000
	s_nop 0
	v_addc_co_u32_e32 v213, vcc, 0, v139, vcc
	v_add_co_u32_e32 v214, vcc, s22, v138
	s_mov_b32 s22, 0x10000
	s_nop 0
	v_addc_co_u32_e32 v215, vcc, 0, v139, vcc
	global_load_dword v212, v[212:213], off offset:128
	v_lshl_add_u64 v[134:135], s[92:93], 0, v[134:135]
	global_load_dword v213, v[214:215], off offset:128
	v_add_co_u32_e32 v214, vcc, s22, v138
	s_mov_b32 s22, 0x12000
	s_nop 0
	v_addc_co_u32_e32 v215, vcc, 0, v139, vcc
	v_add_co_u32_e32 v216, vcc, s22, v138
	s_mov_b32 s22, 0x14000
	s_nop 0
	v_addc_co_u32_e32 v217, vcc, 0, v139, vcc
	global_load_dword v214, v[214:215], off offset:128
	v_lshl_add_u64 v[134:135], v[134:135], 0, s[42:43]
	global_load_dword v215, v[216:217], off offset:128
	v_add_co_u32_e32 v216, vcc, s22, v138
	s_mov_b32 s22, 0x16000
	s_nop 0
	v_addc_co_u32_e32 v217, vcc, 0, v139, vcc
	v_add_co_u32_e32 v218, vcc, s22, v138
	s_mov_b32 s22, 0x20000
	s_nop 0
	v_addc_co_u32_e32 v219, vcc, 0, v139, vcc
	global_load_dword v216, v[216:217], off offset:128
	s_waitcnt vmcnt(22)
	v_add_f32_e32 v112, v112, v142
	global_load_dword v220, v[218:219], off offset:128
	v_add_co_u32_e32 v218, vcc, s22, v138
	s_mov_b32 s22, 0x22000
	s_nop 0
	v_addc_co_u32_e32 v219, vcc, 0, v139, vcc
	global_load_dword v221, v[218:219], off offset:128
	v_add_co_u32_e32 v218, vcc, s22, v138
	s_mov_b32 s22, 0x24000
	s_nop 0
	v_addc_co_u32_e32 v219, vcc, 0, v139, vcc
	global_load_dword v223, v[218:219], off offset:128
	v_add_co_u32_e32 v218, vcc, s22, v138
	s_mov_b32 s22, 0x26000
	s_nop 0
	v_addc_co_u32_e32 v219, vcc, 0, v139, vcc
	global_load_dword v224, v[218:219], off offset:128
	v_add_co_u32_e32 v218, vcc, s22, v138
	s_mov_b32 s22, 0x30000
	s_nop 0
	v_addc_co_u32_e32 v219, vcc, 0, v139, vcc
	global_load_dword v225, v[218:219], off offset:128
	v_add_co_u32_e32 v218, vcc, s22, v138
	s_mov_b32 s22, 0x32000
	s_nop 0
	v_addc_co_u32_e32 v219, vcc, 0, v139, vcc
	global_load_dword v222, v[218:219], off offset:128
	v_add_co_u32_e32 v218, vcc, s22, v138
	s_mov_b32 s22, 0x34000
	s_nop 0
	v_addc_co_u32_e32 v219, vcc, 0, v139, vcc
	v_add_co_u32_e32 v242, vcc, s22, v138
	s_mov_b32 s22, 0x36000
	s_nop 0
	v_addc_co_u32_e32 v243, vcc, 0, v139, vcc
	global_load_dword v218, v[218:219], off offset:128
	v_lshl_add_u64 v[140:141], v[134:135], 0, v[140:141]
	global_load_dword v217, v[242:243], off offset:128
	v_add_co_u32_e32 v242, vcc, s22, v138
	v_lshl_add_u64 v[142:143], v[130:131], 1, v[136:137]
	s_nop 0
	v_addc_co_u32_e32 v243, vcc, 0, v139, vcc
	global_load_dword v219, v[242:243], off offset:128
	s_waitcnt vmcnt(30)
	v_add_f32_e32 v131, v113, v240
	global_store_dword v[140:141], v112, off
	v_mul_f32_e32 v112, v209, v112
	v_cvt_pk_bf16_f32 v112, v112, s0
	global_store_short v[142:143], v112, off
	v_lshl_add_u64 v[112:113], v[134:135], 0, v[202:203]
	global_store_dword v[112:113], v131, off
	v_mul_f32_e32 v112, v209, v131
	v_cvt_pk_bf16_f32 v131, v112, s0
	v_lshl_add_u64 v[112:113], v[188:189], 1, v[136:137]
	global_store_short v[112:113], v131, off
	s_waitcnt vmcnt(33)
	v_add_f32_e32 v114, v114, v239
	v_lshl_add_u64 v[112:113], v[134:135], 0, v[200:201]
	global_store_dword v[112:113], v114, off
	v_mul_f32_e32 v112, v209, v114
	v_cvt_pk_bf16_f32 v114, v112, s0
	v_lshl_add_u64 v[112:113], v[184:185], 1, v[136:137]
	global_store_short v[112:113], v114, off
	s_waitcnt vmcnt(34)
	v_add_f32_e32 v114, v115, v238
	v_lshl_add_u64 v[112:113], v[134:135], 0, v[198:199]
	global_store_dword v[112:113], v114, off
	v_mul_f32_e32 v112, v209, v114
	v_cvt_pk_bf16_f32 v114, v112, s0
	v_lshl_add_u64 v[112:113], v[178:179], 1, v[136:137]
	global_store_short v[112:113], v114, off
	s_waitcnt vmcnt(35)
	v_add_f32_e32 v114, v116, v237
	v_lshl_add_u64 v[112:113], v[134:135], 0, v[196:197]
	global_store_dword v[112:113], v114, off
	v_mul_f32_e32 v112, v209, v114
	v_cvt_pk_bf16_f32 v114, v112, s0
	v_lshl_add_u64 v[112:113], v[174:175], 1, v[136:137]
	global_store_short v[112:113], v114, off
	s_waitcnt vmcnt(36)
	v_add_f32_e32 v114, v117, v236
	v_lshl_add_u64 v[112:113], v[134:135], 0, v[194:195]
	global_store_dword v[112:113], v114, off
	v_mul_f32_e32 v112, v209, v114
	v_cvt_pk_bf16_f32 v114, v112, s0
	v_lshl_add_u64 v[112:113], v[170:171], 1, v[136:137]
	global_store_short v[112:113], v114, off
	s_waitcnt vmcnt(37)
	v_add_f32_e32 v114, v118, v235
	v_lshl_add_u64 v[112:113], v[134:135], 0, v[192:193]
	global_store_dword v[112:113], v114, off
	v_mul_f32_e32 v112, v209, v114
	v_cvt_pk_bf16_f32 v114, v112, s0
	v_lshl_add_u64 v[112:113], v[166:167], 1, v[136:137]
	global_store_short v[112:113], v114, off
	s_waitcnt vmcnt(38)
	v_add_f32_e32 v114, v119, v233
	v_lshl_add_u64 v[112:113], v[134:135], 0, v[190:191]
	global_store_dword v[112:113], v114, off
	v_mul_f32_e32 v112, v209, v114
	v_cvt_pk_bf16_f32 v114, v112, s0
	v_lshl_add_u64 v[112:113], v[162:163], 1, v[136:137]
	global_store_short v[112:113], v114, off
	s_waitcnt vmcnt(39)
	v_add_f32_e32 v114, v120, v232
	v_lshl_add_u64 v[112:113], v[134:135], 0, v[186:187]
	global_store_dword v[112:113], v114, off
	v_mul_f32_e32 v112, v209, v114
	v_cvt_pk_bf16_f32 v114, v112, s0
	v_lshl_add_u64 v[112:113], v[158:159], 1, v[136:137]
	global_store_short v[112:113], v114, off
	s_waitcnt vmcnt(40)
	v_add_f32_e32 v114, v121, v230
	v_lshl_add_u64 v[112:113], v[134:135], 0, v[180:181]
	global_store_dword v[112:113], v114, off
	v_mul_f32_e32 v112, v209, v114
	v_cvt_pk_bf16_f32 v114, v112, s0
	v_lshl_add_u64 v[112:113], v[154:155], 1, v[136:137]
	global_store_short v[112:113], v114, off
	s_waitcnt vmcnt(41)
	v_add_f32_e32 v114, v122, v229
	v_lshl_add_u64 v[112:113], v[134:135], 0, v[176:177]
	global_store_dword v[112:113], v114, off
	v_mul_f32_e32 v112, v209, v114
	v_cvt_pk_bf16_f32 v114, v112, s0
	v_lshl_add_u64 v[112:113], v[152:153], 1, v[136:137]
	global_store_short v[112:113], v114, off
	s_waitcnt vmcnt(42)
	v_add_f32_e32 v114, v123, v228
	v_lshl_add_u64 v[112:113], v[134:135], 0, v[172:173]
	global_store_dword v[112:113], v114, off
	v_mul_f32_e32 v112, v209, v114
	v_cvt_pk_bf16_f32 v114, v112, s0
	v_lshl_add_u64 v[112:113], v[150:151], 1, v[136:137]
	global_store_short v[112:113], v114, off
	s_waitcnt vmcnt(43)
	v_add_f32_e32 v114, v124, v227
	v_lshl_add_u64 v[112:113], v[134:135], 0, v[168:169]
	global_store_dword v[112:113], v114, off
	v_mul_f32_e32 v112, v209, v114
	v_cvt_pk_bf16_f32 v114, v112, s0
	v_lshl_add_u64 v[112:113], v[148:149], 1, v[136:137]
	global_store_short v[112:113], v114, off
	s_waitcnt vmcnt(44)
	v_add_f32_e32 v114, v125, v226
	v_lshl_add_u64 v[112:113], v[134:135], 0, v[164:165]
	global_store_dword v[112:113], v114, off
	v_mul_f32_e32 v112, v209, v114
	v_cvt_pk_bf16_f32 v114, v112, s0
	v_lshl_add_u64 v[112:113], v[146:147], 1, v[136:137]
	global_store_short v[112:113], v114, off
	s_waitcnt vmcnt(45)
	v_add_f32_e32 v114, v126, v234
	v_lshl_add_u64 v[112:113], v[134:135], 0, v[160:161]
	global_store_dword v[112:113], v114, off
	v_mul_f32_e32 v112, v209, v114
	v_cvt_pk_bf16_f32 v114, v112, s0
	v_lshl_add_u64 v[112:113], v[144:145], 1, v[136:137]
	global_store_short v[112:113], v114, off
	s_waitcnt vmcnt(46)
	v_add_f32_e32 v114, v127, v231
	v_lshl_add_u64 v[112:113], v[134:135], 0, v[182:183]
	global_store_dword v[112:113], v114, off
	v_mul_f32_e32 v112, v209, v114
	v_cvt_pk_bf16_f32 v114, v112, s0
	v_lshl_add_u64 v[112:113], v[156:157], 1, v[136:137]
	s_mov_b32 s22, 0x40000
	global_store_short v[112:113], v114, off
	v_add_co_u32_e32 v112, vcc, s22, v138
	s_mov_b32 s22, 0x42000
	s_nop 0
	v_addc_co_u32_e32 v113, vcc, 0, v139, vcc
	global_load_dword v148, v[112:113], off
	v_add_co_u32_e32 v112, vcc, s22, v138
	s_mov_b32 s22, 0x44000
	s_nop 0
	v_addc_co_u32_e32 v113, vcc, 0, v139, vcc
	v_add_co_u32_e32 v114, vcc, s22, v138
	s_mov_b32 s22, 0x46000
	s_nop 0
	v_addc_co_u32_e32 v115, vcc, 0, v139, vcc
	v_add_co_u32_e32 v116, vcc, s22, v138
	s_mov_b32 s22, 0x50000
	s_nop 0
	v_addc_co_u32_e32 v117, vcc, 0, v139, vcc
	v_add_co_u32_e32 v118, vcc, s22, v138
	s_mov_b32 s22, 0x52000
	s_nop 0
	v_addc_co_u32_e32 v119, vcc, 0, v139, vcc
	v_add_co_u32_e32 v120, vcc, s22, v138
	s_mov_b32 s22, 0x54000
	s_nop 0
	v_addc_co_u32_e32 v121, vcc, 0, v139, vcc
	v_add_co_u32_e32 v122, vcc, s22, v138
	s_mov_b32 s22, 0x56000
	s_nop 0
	v_addc_co_u32_e32 v123, vcc, 0, v139, vcc
	v_add_co_u32_e32 v124, vcc, s22, v138
	s_mov_b32 s22, 0x60000
	s_nop 0
	v_addc_co_u32_e32 v125, vcc, 0, v139, vcc
	v_add_co_u32_e32 v126, vcc, s22, v138
	s_mov_b32 s22, 0x62000
	s_nop 0
	v_addc_co_u32_e32 v127, vcc, 0, v139, vcc
	v_add_co_u32_e32 v144, vcc, s22, v138
	s_mov_b32 s22, 0x64000
	s_nop 0
	v_addc_co_u32_e32 v145, vcc, 0, v139, vcc
	v_add_co_u32_e32 v146, vcc, s22, v138
	s_mov_b32 s22, 0x66000
	s_nop 0
	v_addc_co_u32_e32 v147, vcc, 0, v139, vcc
	v_add_co_u32_e32 v150, vcc, s22, v138
	s_mov_b32 s22, 0x70000
	s_nop 0
	v_addc_co_u32_e32 v151, vcc, 0, v139, vcc
	v_add_co_u32_e32 v152, vcc, s22, v138
	s_mov_b32 s22, 0x72000
	s_nop 0
	v_addc_co_u32_e32 v153, vcc, 0, v139, vcc
	v_add_co_u32_e32 v154, vcc, s22, v138
	s_mov_b32 s22, 0x74000
	s_nop 0
	v_addc_co_u32_e32 v155, vcc, 0, v139, vcc
	v_add_co_u32_e32 v156, vcc, s22, v138
	s_mov_b32 s22, 0x76000
	s_nop 0
	v_addc_co_u32_e32 v157, vcc, 0, v139, vcc
	v_add_co_u32_e32 v158, vcc, s22, v138
	s_waitcnt vmcnt(48)
	v_add_f32_e32 v96, v96, v210
	v_addc_co_u32_e32 v159, vcc, 0, v139, vcc
	global_load_dword v149, v[112:113], off
	global_load_dword v160, v[114:115], off
	global_load_dword v161, v[116:117], off
	global_load_dword v162, v[118:119], off
	global_load_dword v163, v[120:121], off
	global_load_dword v164, v[122:123], off
	global_load_dword v165, v[124:125], off
	global_load_dword v166, v[126:127], off
	global_load_dword v167, v[144:145], off
	global_load_dword v168, v[146:147], off
	global_load_dword v169, v[150:151], off
	global_load_dword v170, v[152:153], off
	global_load_dword v171, v[154:155], off
	global_load_dword v172, v[156:157], off
	global_load_dword v173, v[158:159], off
	s_waitcnt vmcnt(62)
	v_add_f32_e32 v131, v97, v211
	global_store_dword v[140:141], v96, off offset:128
	v_mul_f32_e32 v96, v128, v96
	v_cvt_pk_bf16_f32 v96, v96, s0
	global_store_short v[142:143], v96, off offset:64
	v_or_b32_e32 v96, 0x820, v130
	v_ashrrev_i32_e32 v97, 31, v96
	v_lshl_add_u64 v[140:141], v[96:97], 2, v[134:135]
	global_store_dword v[140:141], v131, off
	v_mul_f32_e32 v131, v128, v131
	v_cvt_pk_bf16_f32 v131, v131, s0
	v_lshl_add_u64 v[96:97], v[96:97], 1, v[136:137]
	global_store_short v[96:97], v131, off
	v_or_b32_e32 v96, 0x1020, v130
	v_ashrrev_i32_e32 v97, 31, v96
	s_waitcnt vmcnt(62)
	v_add_f32_e32 v98, v98, v212
	v_lshl_add_u64 v[140:141], v[96:97], 2, v[134:135]
	global_store_dword v[140:141], v98, off
	v_mul_f32_e32 v98, v128, v98
	v_cvt_pk_bf16_f32 v98, v98, s0
	v_lshl_add_u64 v[96:97], v[96:97], 1, v[136:137]
	global_store_short v[96:97], v98, off
	v_or_b32_e32 v96, 0x1820, v130
	v_ashrrev_i32_e32 v97, 31, v96
	v_add_f32_e32 v131, v99, v213
	v_lshl_add_u64 v[98:99], v[96:97], 2, v[134:135]
	global_store_dword v[98:99], v131, off
	v_mul_f32_e32 v98, v128, v131
	v_cvt_pk_bf16_f32 v98, v98, s0
	v_lshl_add_u64 v[96:97], v[96:97], 1, v[136:137]
	global_store_short v[96:97], v98, off
	v_or_b32_e32 v96, 0x4020, v130
	v_ashrrev_i32_e32 v97, 31, v96
	v_add_f32_e32 v100, v100, v214
	v_lshl_add_u64 v[98:99], v[96:97], 2, v[134:135]
	global_store_dword v[98:99], v100, off
	v_mul_f32_e32 v98, v128, v100
	v_cvt_pk_bf16_f32 v98, v98, s0
	v_lshl_add_u64 v[96:97], v[96:97], 1, v[136:137]
	global_store_short v[96:97], v98, off
	v_or_b32_e32 v96, 0x4820, v130
	v_ashrrev_i32_e32 v97, 31, v96
	v_add_f32_e32 v100, v101, v215
	v_lshl_add_u64 v[98:99], v[96:97], 2, v[134:135]
	global_store_dword v[98:99], v100, off
	v_mul_f32_e32 v98, v128, v100
	v_cvt_pk_bf16_f32 v98, v98, s0
	v_lshl_add_u64 v[96:97], v[96:97], 1, v[136:137]
	global_store_short v[96:97], v98, off
	v_or_b32_e32 v96, 0x5020, v130
	v_ashrrev_i32_e32 v97, 31, v96
	s_waitcnt vmcnt(62)
	v_add_f32_e32 v100, v102, v216
	v_lshl_add_u64 v[98:99], v[96:97], 2, v[134:135]
	global_store_dword v[98:99], v100, off
	v_mul_f32_e32 v98, v128, v100
	v_cvt_pk_bf16_f32 v98, v98, s0
	v_lshl_add_u64 v[96:97], v[96:97], 1, v[136:137]
	global_store_short v[96:97], v98, off
	v_or_b32_e32 v96, 0x5820, v130
	v_ashrrev_i32_e32 v97, 31, v96
	v_add_f32_e32 v100, v103, v220
	v_lshl_add_u64 v[98:99], v[96:97], 2, v[134:135]
	global_store_dword v[98:99], v100, off
	v_mul_f32_e32 v98, v128, v100
	v_cvt_pk_bf16_f32 v98, v98, s0
	v_lshl_add_u64 v[96:97], v[96:97], 1, v[136:137]
	global_store_short v[96:97], v98, off
	v_or_b32_e32 v96, 0x8020, v130
	v_ashrrev_i32_e32 v97, 31, v96
	v_add_f32_e32 v100, v104, v221
	v_lshl_add_u64 v[98:99], v[96:97], 2, v[134:135]
	global_store_dword v[98:99], v100, off
	v_mul_f32_e32 v98, v128, v100
	v_cvt_pk_bf16_f32 v98, v98, s0
	v_lshl_add_u64 v[96:97], v[96:97], 1, v[136:137]
	global_store_short v[96:97], v98, off
	v_or_b32_e32 v96, 0x8820, v130
	v_ashrrev_i32_e32 v97, 31, v96
	v_add_f32_e32 v100, v105, v223
	v_lshl_add_u64 v[98:99], v[96:97], 2, v[134:135]
	global_store_dword v[98:99], v100, off
	v_mul_f32_e32 v98, v128, v100
	v_cvt_pk_bf16_f32 v98, v98, s0
	v_lshl_add_u64 v[96:97], v[96:97], 1, v[136:137]
	global_store_short v[96:97], v98, off
	v_or_b32_e32 v96, 0x9020, v130
	v_ashrrev_i32_e32 v97, 31, v96
	v_add_f32_e32 v100, v106, v224
	v_lshl_add_u64 v[98:99], v[96:97], 2, v[134:135]
	global_store_dword v[98:99], v100, off
	v_mul_f32_e32 v98, v128, v100
	v_cvt_pk_bf16_f32 v98, v98, s0
	v_lshl_add_u64 v[96:97], v[96:97], 1, v[136:137]
	global_store_short v[96:97], v98, off
	v_or_b32_e32 v96, 0x9820, v130
	v_ashrrev_i32_e32 v97, 31, v96
	v_add_f32_e32 v100, v107, v225
	v_lshl_add_u64 v[98:99], v[96:97], 2, v[134:135]
	global_store_dword v[98:99], v100, off
	v_mul_f32_e32 v98, v128, v100
	v_cvt_pk_bf16_f32 v98, v98, s0
	v_lshl_add_u64 v[96:97], v[96:97], 1, v[136:137]
	global_store_short v[96:97], v98, off
	v_or_b32_e32 v96, 0xc020, v130
	v_ashrrev_i32_e32 v97, 31, v96
	v_add_f32_e32 v100, v108, v222
	v_lshl_add_u64 v[98:99], v[96:97], 2, v[134:135]
	global_store_dword v[98:99], v100, off
	v_mul_f32_e32 v98, v128, v100
	v_cvt_pk_bf16_f32 v98, v98, s0
	v_lshl_add_u64 v[96:97], v[96:97], 1, v[136:137]
	global_store_short v[96:97], v98, off
	v_or_b32_e32 v96, 0xc820, v130
	v_ashrrev_i32_e32 v97, 31, v96
	v_add_f32_e32 v100, v109, v218
	v_lshl_add_u64 v[98:99], v[96:97], 2, v[134:135]
	global_store_dword v[98:99], v100, off
	v_mul_f32_e32 v98, v128, v100
	v_cvt_pk_bf16_f32 v98, v98, s0
	v_lshl_add_u64 v[96:97], v[96:97], 1, v[136:137]
	global_store_short v[96:97], v98, off
	v_or_b32_e32 v96, 0xd020, v130
	v_ashrrev_i32_e32 v97, 31, v96
	s_waitcnt vmcnt(62)
	v_add_f32_e32 v100, v110, v217
	v_lshl_add_u64 v[98:99], v[96:97], 2, v[134:135]
	global_store_dword v[98:99], v100, off
	v_mul_f32_e32 v98, v128, v100
	v_cvt_pk_bf16_f32 v98, v98, s0
	v_lshl_add_u64 v[96:97], v[96:97], 1, v[136:137]
	global_store_short v[96:97], v98, off
	v_or_b32_e32 v96, 0xd820, v130
	v_ashrrev_i32_e32 v97, 31, v96
	v_add_f32_e32 v100, v111, v219
	v_lshl_add_u64 v[98:99], v[96:97], 2, v[134:135]
	global_store_dword v[98:99], v100, off
	v_mul_f32_e32 v98, v128, v100
	v_cvt_pk_bf16_f32 v98, v98, s0
	v_lshl_add_u64 v[96:97], v[96:97], 1, v[136:137]
	global_store_short v[96:97], v98, off
	v_or_b32_e32 v96, 0x10000, v130
	v_ashrrev_i32_e32 v97, 31, v96
	v_lshlrev_b64 v[140:141], 2, v[96:97]
	v_lshl_add_u64 v[98:99], v[132:133], 0, v[140:141]
	global_load_dword v131, v[98:99], off offset:128
	s_nop 0
	global_load_dword v112, v[112:113], off offset:128
	s_nop 0
	global_load_dword v111, v[114:115], off offset:128
	global_load_dword v110, v[116:117], off offset:128
	global_load_dword v109, v[118:119], off offset:128
	global_load_dword v108, v[120:121], off offset:128
	global_load_dword v107, v[122:123], off offset:128
	global_load_dword v106, v[124:125], off offset:128
	global_load_dword v105, v[126:127], off offset:128
	global_load_dword v104, v[144:145], off offset:128
	global_load_dword v103, v[146:147], off offset:128
	global_load_dword v102, v[150:151], off offset:128
	global_load_dword v101, v[152:153], off offset:128
	global_load_dword v100, v[154:155], off offset:128
	global_load_dword v99, v[156:157], off offset:128
	global_load_dword v98, v[158:159], off offset:128
	s_waitcnt vmcnt(62)
	v_add_f32_e32 v80, v80, v148
	v_lshl_add_u64 v[114:115], v[134:135], 0, v[140:141]
	global_store_dword v[114:115], v80, off
	v_mul_f32_e32 v80, v209, v80
	v_cvt_pk_bf16_f32 v80, v80, s0
	v_lshl_add_u64 v[96:97], v[96:97], 1, v[136:137]
	global_store_short v[96:97], v80, off
	v_or_b32_e32 v80, 0x10800, v130
	v_add_f32_e32 v113, v81, v149
	v_ashrrev_i32_e32 v81, 31, v80
	v_lshl_add_u64 v[96:97], v[80:81], 2, v[134:135]
	global_store_dword v[96:97], v113, off
	v_mul_f32_e32 v96, v209, v113
	v_cvt_pk_bf16_f32 v96, v96, s0
	v_lshl_add_u64 v[80:81], v[80:81], 1, v[136:137]
	global_store_short v[80:81], v96, off
	v_or_b32_e32 v80, 0x11000, v130
	v_ashrrev_i32_e32 v81, 31, v80
	s_waitcnt vmcnt(62)
	v_add_f32_e32 v82, v82, v160
	v_lshl_add_u64 v[96:97], v[80:81], 2, v[134:135]
	global_store_dword v[96:97], v82, off
	v_mul_f32_e32 v82, v209, v82
	v_cvt_pk_bf16_f32 v82, v82, s0
	v_lshl_add_u64 v[80:81], v[80:81], 1, v[136:137]
	global_store_short v[80:81], v82, off
	v_or_b32_e32 v80, 0x11800, v130
	v_ashrrev_i32_e32 v81, 31, v80
	v_add_f32_e32 v96, v83, v161
	v_lshl_add_u64 v[82:83], v[80:81], 2, v[134:135]
	global_store_dword v[82:83], v96, off
	v_mul_f32_e32 v82, v209, v96
	v_cvt_pk_bf16_f32 v82, v82, s0
	v_lshl_add_u64 v[80:81], v[80:81], 1, v[136:137]
	global_store_short v[80:81], v82, off
	v_or_b32_e32 v80, 0x14000, v130
	v_ashrrev_i32_e32 v81, 31, v80
	v_add_f32_e32 v84, v84, v162
	v_lshl_add_u64 v[82:83], v[80:81], 2, v[134:135]
	global_store_dword v[82:83], v84, off
	v_mul_f32_e32 v82, v209, v84
	v_cvt_pk_bf16_f32 v82, v82, s0
	v_lshl_add_u64 v[80:81], v[80:81], 1, v[136:137]
	global_store_short v[80:81], v82, off
	v_or_b32_e32 v80, 0x14800, v130
	v_ashrrev_i32_e32 v81, 31, v80
	v_add_f32_e32 v84, v85, v163
	v_lshl_add_u64 v[82:83], v[80:81], 2, v[134:135]
	global_store_dword v[82:83], v84, off
	v_mul_f32_e32 v82, v209, v84
	v_cvt_pk_bf16_f32 v82, v82, s0
	v_lshl_add_u64 v[80:81], v[80:81], 1, v[136:137]
	global_store_short v[80:81], v82, off
	v_or_b32_e32 v80, 0x15000, v130
	v_ashrrev_i32_e32 v81, 31, v80
	s_waitcnt vmcnt(62)
	v_add_f32_e32 v84, v86, v164
	v_lshl_add_u64 v[82:83], v[80:81], 2, v[134:135]
	global_store_dword v[82:83], v84, off
	v_mul_f32_e32 v82, v209, v84
	v_cvt_pk_bf16_f32 v82, v82, s0
	v_lshl_add_u64 v[80:81], v[80:81], 1, v[136:137]
	global_store_short v[80:81], v82, off
	v_or_b32_e32 v80, 0x15800, v130
	v_ashrrev_i32_e32 v81, 31, v80
	v_add_f32_e32 v84, v87, v165
	v_lshl_add_u64 v[82:83], v[80:81], 2, v[134:135]
	global_store_dword v[82:83], v84, off
	v_mul_f32_e32 v82, v209, v84
	v_cvt_pk_bf16_f32 v82, v82, s0
	v_lshl_add_u64 v[80:81], v[80:81], 1, v[136:137]
	global_store_short v[80:81], v82, off
	v_or_b32_e32 v80, 0x18000, v130
	v_ashrrev_i32_e32 v81, 31, v80
	v_add_f32_e32 v84, v88, v166
	v_lshl_add_u64 v[82:83], v[80:81], 2, v[134:135]
	global_store_dword v[82:83], v84, off
	v_mul_f32_e32 v82, v209, v84
	v_cvt_pk_bf16_f32 v82, v82, s0
	v_lshl_add_u64 v[80:81], v[80:81], 1, v[136:137]
	global_store_short v[80:81], v82, off
	v_or_b32_e32 v80, 0x18800, v130
	v_ashrrev_i32_e32 v81, 31, v80
	v_add_f32_e32 v84, v89, v167
	v_lshl_add_u64 v[82:83], v[80:81], 2, v[134:135]
	global_store_dword v[82:83], v84, off
	v_mul_f32_e32 v82, v209, v84
	v_cvt_pk_bf16_f32 v82, v82, s0
	v_lshl_add_u64 v[80:81], v[80:81], 1, v[136:137]
	global_store_short v[80:81], v82, off
	v_or_b32_e32 v80, 0x19000, v130
	v_ashrrev_i32_e32 v81, 31, v80
	v_add_f32_e32 v84, v90, v168
	v_lshl_add_u64 v[82:83], v[80:81], 2, v[134:135]
	global_store_dword v[82:83], v84, off
	v_mul_f32_e32 v82, v209, v84
	v_cvt_pk_bf16_f32 v82, v82, s0
	v_lshl_add_u64 v[80:81], v[80:81], 1, v[136:137]
	global_store_short v[80:81], v82, off
	v_or_b32_e32 v80, 0x19800, v130
	v_ashrrev_i32_e32 v81, 31, v80
	v_add_f32_e32 v84, v91, v169
	v_lshl_add_u64 v[82:83], v[80:81], 2, v[134:135]
	global_store_dword v[82:83], v84, off
	v_mul_f32_e32 v82, v209, v84
	v_cvt_pk_bf16_f32 v82, v82, s0
	v_lshl_add_u64 v[80:81], v[80:81], 1, v[136:137]
	global_store_short v[80:81], v82, off
	v_or_b32_e32 v80, 0x1c000, v130
	v_ashrrev_i32_e32 v81, 31, v80
	v_add_f32_e32 v84, v92, v170
	v_lshl_add_u64 v[82:83], v[80:81], 2, v[134:135]
	global_store_dword v[82:83], v84, off
	v_mul_f32_e32 v82, v209, v84
	v_cvt_pk_bf16_f32 v82, v82, s0
	v_lshl_add_u64 v[80:81], v[80:81], 1, v[136:137]
	global_store_short v[80:81], v82, off
	v_or_b32_e32 v80, 0x1c800, v130
	v_ashrrev_i32_e32 v81, 31, v80
	v_add_f32_e32 v84, v93, v171
	v_lshl_add_u64 v[82:83], v[80:81], 2, v[134:135]
	global_store_dword v[82:83], v84, off
	v_mul_f32_e32 v82, v209, v84
	v_cvt_pk_bf16_f32 v82, v82, s0
	v_lshl_add_u64 v[80:81], v[80:81], 1, v[136:137]
	global_store_short v[80:81], v82, off
	v_or_b32_e32 v80, 0x1d000, v130
	v_ashrrev_i32_e32 v81, 31, v80
	s_waitcnt vmcnt(62)
	v_add_f32_e32 v84, v94, v172
	v_lshl_add_u64 v[82:83], v[80:81], 2, v[134:135]
	global_store_dword v[82:83], v84, off
	v_mul_f32_e32 v82, v209, v84
	v_cvt_pk_bf16_f32 v82, v82, s0
	v_lshl_add_u64 v[80:81], v[80:81], 1, v[136:137]
	global_store_short v[80:81], v82, off
	v_or_b32_e32 v80, 0x1d800, v130
	v_ashrrev_i32_e32 v81, 31, v80
	v_add_f32_e32 v84, v95, v173
	v_lshl_add_u64 v[82:83], v[80:81], 2, v[134:135]
	global_store_dword v[82:83], v84, off
	v_mul_f32_e32 v82, v209, v84
	v_cvt_pk_bf16_f32 v82, v82, s0
	v_lshl_add_u64 v[80:81], v[80:81], 1, v[136:137]
	global_store_short v[80:81], v82, off
	v_add_co_u32_e32 v80, vcc, s50, v138
	s_mov_b32 s22, 0xb4000
	s_nop 0
	v_addc_co_u32_e32 v81, vcc, 0, v139, vcc
	global_load_dword v142, v[80:81], off
	v_add_co_u32_e32 v80, vcc, s2, v138
	v_or_b32_e32 v126, 0x10020, v130
	s_nop 0
	v_addc_co_u32_e32 v81, vcc, 0, v139, vcc
	v_add_co_u32_e32 v82, vcc, s36, v138
	v_ashrrev_i32_e32 v127, 31, v126
	s_nop 0
	v_addc_co_u32_e32 v83, vcc, 0, v139, vcc
	v_add_co_u32_e32 v84, vcc, s37, v138
	s_waitcnt vmcnt(48)
	v_add_f32_e32 v64, v64, v131
	v_addc_co_u32_e32 v85, vcc, 0, v139, vcc
	v_add_co_u32_e32 v86, vcc, s38, v138
	v_lshl_add_u64 v[140:141], v[126:127], 2, v[134:135]
	s_nop 0
	v_addc_co_u32_e32 v87, vcc, 0, v139, vcc
	v_add_co_u32_e32 v88, vcc, s39, v138
	global_load_dword v143, v[80:81], off
	global_load_dword v144, v[82:83], off
	global_load_dword v145, v[84:85], off
	global_load_dword v146, v[86:87], off
	v_addc_co_u32_e32 v89, vcc, 0, v139, vcc
	v_add_co_u32_e32 v90, vcc, s96, v138
	global_load_dword v147, v[88:89], off
	s_nop 0
	v_addc_co_u32_e32 v91, vcc, 0, v139, vcc
	v_add_co_u32_e32 v92, vcc, s97, v138
	global_load_dword v148, v[90:91], off
	s_nop 0
	v_addc_co_u32_e32 v93, vcc, 0, v139, vcc
	v_add_co_u32_e32 v94, vcc, s3, v138
	global_load_dword v149, v[92:93], off
	s_nop 0
	v_addc_co_u32_e32 v95, vcc, 0, v139, vcc
	v_add_co_u32_e32 v96, vcc, s4, v138
	global_load_dword v150, v[94:95], off
	s_nop 0
	v_addc_co_u32_e32 v97, vcc, 0, v139, vcc
	v_add_co_u32_e32 v114, vcc, s5, v138
	global_load_dword v151, v[96:97], off
	s_nop 0
	v_addc_co_u32_e32 v115, vcc, 0, v139, vcc
	v_add_co_u32_e32 v116, vcc, s45, v138
	global_load_dword v152, v[114:115], off
	s_nop 0
	v_addc_co_u32_e32 v117, vcc, 0, v139, vcc
	v_add_co_u32_e32 v118, vcc, s54, v138
	global_load_dword v153, v[116:117], off
	s_nop 0
	v_addc_co_u32_e32 v119, vcc, 0, v139, vcc
	v_add_co_u32_e32 v120, vcc, s55, v138
	global_load_dword v154, v[118:119], off
	s_nop 0
	v_addc_co_u32_e32 v121, vcc, 0, v139, vcc
	v_add_co_u32_e32 v122, vcc, s22, v138
	s_mov_b32 s22, 0xb6000
	s_nop 0
	v_addc_co_u32_e32 v123, vcc, 0, v139, vcc
	v_add_co_u32_e32 v124, vcc, s22, v138
	global_load_dword v155, v[120:121], off
	global_load_dword v156, v[122:123], off
	v_addc_co_u32_e32 v125, vcc, 0, v139, vcc
	global_load_dword v157, v[124:125], off
	v_lshl_add_u64 v[126:127], v[126:127], 1, v[136:137]
	global_store_dword v[140:141], v64, off
	v_mul_f32_e32 v64, v128, v64
	v_cvt_pk_bf16_f32 v64, v64, s0
	global_store_short v[126:127], v64, off
	v_or_b32_e32 v64, 0x10820, v130
	s_waitcnt vmcnt(62)
	v_add_f32_e32 v126, v65, v112
	v_ashrrev_i32_e32 v65, 31, v64
	v_lshl_add_u64 v[112:113], v[64:65], 2, v[134:135]
	global_store_dword v[112:113], v126, off
	v_mul_f32_e32 v112, v128, v126
	v_cvt_pk_bf16_f32 v112, v112, s0
	v_lshl_add_u64 v[64:65], v[64:65], 1, v[136:137]
	global_store_short v[64:65], v112, off
	v_or_b32_e32 v64, 0x11020, v130
	v_ashrrev_i32_e32 v65, 31, v64
	v_add_f32_e32 v66, v66, v111
	v_lshl_add_u64 v[112:113], v[64:65], 2, v[134:135]
	global_store_dword v[112:113], v66, off
	v_mul_f32_e32 v66, v128, v66
	v_cvt_pk_bf16_f32 v66, v66, s0
	v_lshl_add_u64 v[64:65], v[64:65], 1, v[136:137]
	global_store_short v[64:65], v66, off
	v_or_b32_e32 v64, 0x11820, v130
	v_ashrrev_i32_e32 v65, 31, v64
	v_add_f32_e32 v110, v67, v110
	v_lshl_add_u64 v[66:67], v[64:65], 2, v[134:135]
	global_store_dword v[66:67], v110, off
	v_mul_f32_e32 v66, v128, v110
	v_cvt_pk_bf16_f32 v66, v66, s0
	v_lshl_add_u64 v[64:65], v[64:65], 1, v[136:137]
	global_store_short v[64:65], v66, off
	v_or_b32_e32 v64, 0x14020, v130
	v_ashrrev_i32_e32 v65, 31, v64
	s_waitcnt vmcnt(62)
	v_add_f32_e32 v68, v68, v109
	v_lshl_add_u64 v[66:67], v[64:65], 2, v[134:135]
	global_store_dword v[66:67], v68, off
	v_mul_f32_e32 v66, v128, v68
	v_cvt_pk_bf16_f32 v66, v66, s0
	v_lshl_add_u64 v[64:65], v[64:65], 1, v[136:137]
	global_store_short v[64:65], v66, off
	v_or_b32_e32 v64, 0x14820, v130
	v_ashrrev_i32_e32 v65, 31, v64
	v_add_f32_e32 v68, v69, v108
	v_lshl_add_u64 v[66:67], v[64:65], 2, v[134:135]
	global_store_dword v[66:67], v68, off
	v_mul_f32_e32 v66, v128, v68
	v_cvt_pk_bf16_f32 v66, v66, s0
	v_lshl_add_u64 v[64:65], v[64:65], 1, v[136:137]
	global_store_short v[64:65], v66, off
	v_or_b32_e32 v64, 0x15020, v130
	v_ashrrev_i32_e32 v65, 31, v64
	v_add_f32_e32 v68, v70, v107
	v_lshl_add_u64 v[66:67], v[64:65], 2, v[134:135]
	global_store_dword v[66:67], v68, off
	v_mul_f32_e32 v66, v128, v68
	v_cvt_pk_bf16_f32 v66, v66, s0
	v_lshl_add_u64 v[64:65], v[64:65], 1, v[136:137]
	global_store_short v[64:65], v66, off
	v_or_b32_e32 v64, 0x15820, v130
	v_ashrrev_i32_e32 v65, 31, v64
	v_add_f32_e32 v68, v71, v106
	v_lshl_add_u64 v[66:67], v[64:65], 2, v[134:135]
	global_store_dword v[66:67], v68, off
	v_mul_f32_e32 v66, v128, v68
	v_cvt_pk_bf16_f32 v66, v66, s0
	v_lshl_add_u64 v[64:65], v[64:65], 1, v[136:137]
	global_store_short v[64:65], v66, off
	v_or_b32_e32 v64, 0x18020, v130
	v_ashrrev_i32_e32 v65, 31, v64
	v_add_f32_e32 v68, v72, v105
	v_lshl_add_u64 v[66:67], v[64:65], 2, v[134:135]
	global_store_dword v[66:67], v68, off
	v_mul_f32_e32 v66, v128, v68
	v_cvt_pk_bf16_f32 v66, v66, s0
	v_lshl_add_u64 v[64:65], v[64:65], 1, v[136:137]
	global_store_short v[64:65], v66, off
	v_or_b32_e32 v64, 0x18820, v130
	v_ashrrev_i32_e32 v65, 31, v64
	v_add_f32_e32 v68, v73, v104
	v_lshl_add_u64 v[66:67], v[64:65], 2, v[134:135]
	global_store_dword v[66:67], v68, off
	v_mul_f32_e32 v66, v128, v68
	v_cvt_pk_bf16_f32 v66, v66, s0
	v_lshl_add_u64 v[64:65], v[64:65], 1, v[136:137]
	global_store_short v[64:65], v66, off
	v_or_b32_e32 v64, 0x19020, v130
	v_ashrrev_i32_e32 v65, 31, v64
	s_waitcnt vmcnt(62)
	v_add_f32_e32 v68, v74, v103
	v_lshl_add_u64 v[66:67], v[64:65], 2, v[134:135]
	global_store_dword v[66:67], v68, off
	v_mul_f32_e32 v66, v128, v68
	v_cvt_pk_bf16_f32 v66, v66, s0
	v_lshl_add_u64 v[64:65], v[64:65], 1, v[136:137]
	global_store_short v[64:65], v66, off
	v_or_b32_e32 v64, 0x19820, v130
	v_ashrrev_i32_e32 v65, 31, v64
	v_add_f32_e32 v68, v75, v102
	v_lshl_add_u64 v[66:67], v[64:65], 2, v[134:135]
	global_store_dword v[66:67], v68, off
	v_mul_f32_e32 v66, v128, v68
	v_cvt_pk_bf16_f32 v66, v66, s0
	v_lshl_add_u64 v[64:65], v[64:65], 1, v[136:137]
	global_store_short v[64:65], v66, off
	v_or_b32_e32 v64, 0x1c020, v130
	v_ashrrev_i32_e32 v65, 31, v64
	v_add_f32_e32 v68, v76, v101
	v_lshl_add_u64 v[66:67], v[64:65], 2, v[134:135]
	global_store_dword v[66:67], v68, off
	v_mul_f32_e32 v66, v128, v68
	v_cvt_pk_bf16_f32 v66, v66, s0
	v_lshl_add_u64 v[64:65], v[64:65], 1, v[136:137]
	global_store_short v[64:65], v66, off
	v_or_b32_e32 v64, 0x1c820, v130
	v_ashrrev_i32_e32 v65, 31, v64
	v_add_f32_e32 v68, v77, v100
	v_lshl_add_u64 v[66:67], v[64:65], 2, v[134:135]
	global_store_dword v[66:67], v68, off
	v_mul_f32_e32 v66, v128, v68
	v_cvt_pk_bf16_f32 v66, v66, s0
	v_lshl_add_u64 v[64:65], v[64:65], 1, v[136:137]
	global_store_short v[64:65], v66, off
	v_or_b32_e32 v64, 0x1d020, v130
	v_ashrrev_i32_e32 v65, 31, v64
	v_add_f32_e32 v68, v78, v99
	v_lshl_add_u64 v[66:67], v[64:65], 2, v[134:135]
	global_store_dword v[66:67], v68, off
	v_mul_f32_e32 v66, v128, v68
	v_cvt_pk_bf16_f32 v66, v66, s0
	v_lshl_add_u64 v[64:65], v[64:65], 1, v[136:137]
	global_store_short v[64:65], v66, off
	v_or_b32_e32 v64, 0x1d820, v130
	v_ashrrev_i32_e32 v65, 31, v64
	v_add_f32_e32 v68, v79, v98
	v_lshl_add_u64 v[66:67], v[64:65], 2, v[134:135]
	global_store_dword v[66:67], v68, off
	v_mul_f32_e32 v66, v128, v68
	v_cvt_pk_bf16_f32 v66, v66, s0
	v_lshl_add_u64 v[64:65], v[64:65], 1, v[136:137]
	global_store_short v[64:65], v66, off
	v_or_b32_e32 v64, 0x20000, v130
	v_ashrrev_i32_e32 v65, 31, v64
	v_lshlrev_b64 v[66:67], 2, v[64:65]
	v_lshl_add_u64 v[68:69], v[132:133], 0, v[66:67]
	s_waitcnt vmcnt(47)
	v_add_f32_e32 v48, v48, v142
	v_lshl_add_u64 v[66:67], v[134:135], 0, v[66:67]
	global_load_dword v102, v[68:69], off offset:128
	global_load_dword v101, v[80:81], off offset:128
	global_load_dword v100, v[82:83], off offset:128
	global_load_dword v99, v[84:85], off offset:128
	global_load_dword v98, v[86:87], off offset:128
	s_nop 0
	global_load_dword v88, v[88:89], off offset:128
	s_nop 0
	global_load_dword v87, v[90:91], off offset:128
	global_load_dword v86, v[92:93], off offset:128
	global_load_dword v85, v[94:95], off offset:128
	global_load_dword v84, v[96:97], off offset:128
	global_load_dword v83, v[114:115], off offset:128
	global_load_dword v82, v[116:117], off offset:128
	global_load_dword v81, v[118:119], off offset:128
	global_load_dword v80, v[120:121], off offset:128
	global_load_dword v79, v[122:123], off offset:128
	global_load_dword v78, v[124:125], off offset:128
	v_lshl_add_u64 v[64:65], v[64:65], 1, v[136:137]
	global_store_dword v[66:67], v48, off
	v_mul_f32_e32 v48, v209, v48
	v_cvt_pk_bf16_f32 v48, v48, s0
	global_store_short v[64:65], v48, off
	v_or_b32_e32 v48, 0x20800, v130
	s_waitcnt vmcnt(62)
	v_add_f32_e32 v66, v49, v143
	v_ashrrev_i32_e32 v49, 31, v48
	v_lshl_add_u64 v[64:65], v[48:49], 2, v[134:135]
	global_store_dword v[64:65], v66, off
	v_mul_f32_e32 v64, v209, v66
	v_cvt_pk_bf16_f32 v64, v64, s0
	v_lshl_add_u64 v[48:49], v[48:49], 1, v[136:137]
	global_store_short v[48:49], v64, off
	v_or_b32_e32 v48, 0x21000, v130
	v_ashrrev_i32_e32 v49, 31, v48
	v_add_f32_e32 v50, v50, v144
	v_lshl_add_u64 v[64:65], v[48:49], 2, v[134:135]
	global_store_dword v[64:65], v50, off
	v_mul_f32_e32 v50, v209, v50
	v_cvt_pk_bf16_f32 v50, v50, s0
	v_lshl_add_u64 v[48:49], v[48:49], 1, v[136:137]
	global_store_short v[48:49], v50, off
	v_or_b32_e32 v48, 0x21800, v130
	v_ashrrev_i32_e32 v49, 31, v48
	v_add_f32_e32 v64, v51, v145
	v_lshl_add_u64 v[50:51], v[48:49], 2, v[134:135]
	global_store_dword v[50:51], v64, off
	v_mul_f32_e32 v50, v209, v64
	v_cvt_pk_bf16_f32 v50, v50, s0
	v_lshl_add_u64 v[48:49], v[48:49], 1, v[136:137]
	global_store_short v[48:49], v50, off
	v_or_b32_e32 v48, 0x24000, v130
	v_ashrrev_i32_e32 v49, 31, v48
	s_waitcnt vmcnt(62)
	v_add_f32_e32 v52, v52, v146
	v_lshl_add_u64 v[50:51], v[48:49], 2, v[134:135]
	global_store_dword v[50:51], v52, off
	v_mul_f32_e32 v50, v209, v52
	v_cvt_pk_bf16_f32 v50, v50, s0
	v_lshl_add_u64 v[48:49], v[48:49], 1, v[136:137]
	global_store_short v[48:49], v50, off
	v_or_b32_e32 v48, 0x24800, v130
	v_ashrrev_i32_e32 v49, 31, v48
	v_add_f32_e32 v52, v53, v147
	v_lshl_add_u64 v[50:51], v[48:49], 2, v[134:135]
	global_store_dword v[50:51], v52, off
	v_mul_f32_e32 v50, v209, v52
	v_cvt_pk_bf16_f32 v50, v50, s0
	v_lshl_add_u64 v[48:49], v[48:49], 1, v[136:137]
	global_store_short v[48:49], v50, off
	v_or_b32_e32 v48, 0x25000, v130
	v_ashrrev_i32_e32 v49, 31, v48
	v_add_f32_e32 v52, v54, v148
	v_lshl_add_u64 v[50:51], v[48:49], 2, v[134:135]
	global_store_dword v[50:51], v52, off
	v_mul_f32_e32 v50, v209, v52
	v_cvt_pk_bf16_f32 v50, v50, s0
	v_lshl_add_u64 v[48:49], v[48:49], 1, v[136:137]
	global_store_short v[48:49], v50, off
	v_or_b32_e32 v48, 0x25800, v130
	v_ashrrev_i32_e32 v49, 31, v48
	v_add_f32_e32 v52, v55, v149
	v_lshl_add_u64 v[50:51], v[48:49], 2, v[134:135]
	global_store_dword v[50:51], v52, off
	v_mul_f32_e32 v50, v209, v52
	v_cvt_pk_bf16_f32 v50, v50, s0
	v_lshl_add_u64 v[48:49], v[48:49], 1, v[136:137]
	global_store_short v[48:49], v50, off
	v_or_b32_e32 v48, 0x28000, v130
	v_ashrrev_i32_e32 v49, 31, v48
	v_add_f32_e32 v52, v56, v150
	v_lshl_add_u64 v[50:51], v[48:49], 2, v[134:135]
	global_store_dword v[50:51], v52, off
	v_mul_f32_e32 v50, v209, v52
	v_cvt_pk_bf16_f32 v50, v50, s0
	v_lshl_add_u64 v[48:49], v[48:49], 1, v[136:137]
	global_store_short v[48:49], v50, off
	v_or_b32_e32 v48, 0x28800, v130
	v_ashrrev_i32_e32 v49, 31, v48
	v_add_f32_e32 v52, v57, v151
	v_lshl_add_u64 v[50:51], v[48:49], 2, v[134:135]
	global_store_dword v[50:51], v52, off
	v_mul_f32_e32 v50, v209, v52
	v_cvt_pk_bf16_f32 v50, v50, s0
	v_lshl_add_u64 v[48:49], v[48:49], 1, v[136:137]
	global_store_short v[48:49], v50, off
	v_or_b32_e32 v48, 0x29000, v130
	v_ashrrev_i32_e32 v49, 31, v48
	s_waitcnt vmcnt(62)
	v_add_f32_e32 v52, v58, v152
	v_lshl_add_u64 v[50:51], v[48:49], 2, v[134:135]
	global_store_dword v[50:51], v52, off
	v_mul_f32_e32 v50, v209, v52
	v_cvt_pk_bf16_f32 v50, v50, s0
	v_lshl_add_u64 v[48:49], v[48:49], 1, v[136:137]
	global_store_short v[48:49], v50, off
	v_or_b32_e32 v48, 0x29800, v130
	v_ashrrev_i32_e32 v49, 31, v48
	v_add_f32_e32 v52, v59, v153
	v_lshl_add_u64 v[50:51], v[48:49], 2, v[134:135]
	global_store_dword v[50:51], v52, off
	v_mul_f32_e32 v50, v209, v52
	v_cvt_pk_bf16_f32 v50, v50, s0
	v_lshl_add_u64 v[48:49], v[48:49], 1, v[136:137]
	global_store_short v[48:49], v50, off
	v_or_b32_e32 v48, 0x2c000, v130
	v_ashrrev_i32_e32 v49, 31, v48
	v_add_f32_e32 v52, v60, v154
	v_lshl_add_u64 v[50:51], v[48:49], 2, v[134:135]
	global_store_dword v[50:51], v52, off
	v_mul_f32_e32 v50, v209, v52
	v_cvt_pk_bf16_f32 v50, v50, s0
	v_lshl_add_u64 v[48:49], v[48:49], 1, v[136:137]
	global_store_short v[48:49], v50, off
	v_or_b32_e32 v48, 0x2c800, v130
	v_ashrrev_i32_e32 v49, 31, v48
	v_add_f32_e32 v52, v61, v155
	v_lshl_add_u64 v[50:51], v[48:49], 2, v[134:135]
	global_store_dword v[50:51], v52, off
	v_mul_f32_e32 v50, v209, v52
	v_cvt_pk_bf16_f32 v50, v50, s0
	v_lshl_add_u64 v[48:49], v[48:49], 1, v[136:137]
	global_store_short v[48:49], v50, off
	v_or_b32_e32 v48, 0x2d000, v130
	v_ashrrev_i32_e32 v49, 31, v48
	v_add_f32_e32 v52, v62, v156
	v_lshl_add_u64 v[50:51], v[48:49], 2, v[134:135]
	global_store_dword v[50:51], v52, off
	v_mul_f32_e32 v50, v209, v52
	v_cvt_pk_bf16_f32 v50, v50, s0
	v_lshl_add_u64 v[48:49], v[48:49], 1, v[136:137]
	global_store_short v[48:49], v50, off
	v_or_b32_e32 v48, 0x2d800, v130
	v_ashrrev_i32_e32 v49, 31, v48
	v_add_f32_e32 v52, v63, v157
	v_lshl_add_u64 v[50:51], v[48:49], 2, v[134:135]
	global_store_dword v[50:51], v52, off
	v_mul_f32_e32 v50, v209, v52
	v_cvt_pk_bf16_f32 v50, v50, s0
	v_lshl_add_u64 v[48:49], v[48:49], 1, v[136:137]
	s_mov_b32 s22, 0xc0000
	global_store_short v[48:49], v50, off
	v_add_co_u32_e32 v48, vcc, s22, v138
	s_mov_b32 s22, 0xc2000
	s_nop 0
	v_addc_co_u32_e32 v49, vcc, 0, v139, vcc
	global_load_dword v89, v[48:49], off
	v_add_co_u32_e32 v48, vcc, s22, v138
	v_or_b32_e32 v110, 0x20020, v130
	s_nop 0
	v_addc_co_u32_e32 v49, vcc, 0, v139, vcc
	v_add_co_u32_e32 v50, vcc, s76, v138
	v_ashrrev_i32_e32 v111, 31, v110
	s_nop 0
	v_addc_co_u32_e32 v51, vcc, 0, v139, vcc
	v_add_co_u32_e32 v52, vcc, s77, v138
	s_waitcnt vmcnt(48)
	v_add_f32_e32 v32, v32, v102
	v_addc_co_u32_e32 v53, vcc, 0, v139, vcc
	v_add_co_u32_e32 v54, vcc, s78, v138
	v_lshl_add_u64 v[112:113], v[110:111], 2, v[134:135]
	s_nop 0
	v_addc_co_u32_e32 v55, vcc, 0, v139, vcc
	v_add_co_u32_e32 v56, vcc, s79, v138
	global_load_dword v90, v[48:49], off
	global_load_dword v91, v[50:51], off
	global_load_dword v92, v[52:53], off
	global_load_dword v93, v[54:55], off
	v_addc_co_u32_e32 v57, vcc, 0, v139, vcc
	v_add_co_u32_e32 v58, vcc, s80, v138
	global_load_dword v94, v[56:57], off
	s_nop 0
	v_addc_co_u32_e32 v59, vcc, 0, v139, vcc
	v_add_co_u32_e32 v60, vcc, s81, v138
	global_load_dword v95, v[58:59], off
	s_nop 0
	v_addc_co_u32_e32 v61, vcc, 0, v139, vcc
	v_add_co_u32_e32 v62, vcc, s82, v138
	global_load_dword v96, v[60:61], off
	s_nop 0
	v_addc_co_u32_e32 v63, vcc, 0, v139, vcc
	v_add_co_u32_e32 v64, vcc, s83, v138
	global_load_dword v97, v[62:63], off
	s_nop 0
	v_addc_co_u32_e32 v65, vcc, 0, v139, vcc
	v_add_co_u32_e32 v66, vcc, s84, v138
	global_load_dword v103, v[64:65], off
	s_nop 0
	v_addc_co_u32_e32 v67, vcc, 0, v139, vcc
	v_add_co_u32_e32 v68, vcc, s85, v138
	global_load_dword v104, v[66:67], off
	s_nop 0
	v_addc_co_u32_e32 v69, vcc, 0, v139, vcc
	v_add_co_u32_e32 v70, vcc, s86, v138
	global_load_dword v105, v[68:69], off
	s_nop 0
	v_addc_co_u32_e32 v71, vcc, 0, v139, vcc
	v_add_co_u32_e32 v72, vcc, s87, v138
	global_load_dword v106, v[70:71], off
	s_nop 0
	v_addc_co_u32_e32 v73, vcc, 0, v139, vcc
	v_add_co_u32_e32 v74, vcc, s88, v138
	global_load_dword v107, v[72:73], off
	s_nop 0
	v_addc_co_u32_e32 v75, vcc, 0, v139, vcc
	v_add_co_u32_e32 v76, vcc, s89, v138
	global_load_dword v108, v[74:75], off
	s_nop 0
	v_addc_co_u32_e32 v77, vcc, 0, v139, vcc
	global_load_dword v109, v[76:77], off
	v_lshl_add_u64 v[110:111], v[110:111], 1, v[136:137]
	global_store_dword v[112:113], v32, off
	v_mul_f32_e32 v32, v128, v32
	v_cvt_pk_bf16_f32 v32, v32, s0
	global_store_short v[110:111], v32, off
	v_or_b32_e32 v32, 0x20820, v130
	s_waitcnt vmcnt(62)
	v_add_f32_e32 v101, v33, v101
	v_ashrrev_i32_e32 v33, 31, v32
	v_lshl_add_u64 v[110:111], v[32:33], 2, v[134:135]
	global_store_dword v[110:111], v101, off
	v_mul_f32_e32 v101, v128, v101
	v_cvt_pk_bf16_f32 v101, v101, s0
	v_lshl_add_u64 v[32:33], v[32:33], 1, v[136:137]
	global_store_short v[32:33], v101, off
	v_or_b32_e32 v32, 0x21020, v130
	v_ashrrev_i32_e32 v33, 31, v32
	v_add_f32_e32 v34, v34, v100
	v_lshl_add_u64 v[100:101], v[32:33], 2, v[134:135]
	global_store_dword v[100:101], v34, off
	v_mul_f32_e32 v34, v128, v34
	v_cvt_pk_bf16_f32 v34, v34, s0
	v_lshl_add_u64 v[32:33], v[32:33], 1, v[136:137]
	global_store_short v[32:33], v34, off
	v_or_b32_e32 v32, 0x21820, v130
	v_ashrrev_i32_e32 v33, 31, v32
	v_add_f32_e32 v99, v35, v99
	v_lshl_add_u64 v[34:35], v[32:33], 2, v[134:135]
	global_store_dword v[34:35], v99, off
	v_mul_f32_e32 v34, v128, v99
	v_cvt_pk_bf16_f32 v34, v34, s0
	v_lshl_add_u64 v[32:33], v[32:33], 1, v[136:137]
	global_store_short v[32:33], v34, off
	v_or_b32_e32 v32, 0x24020, v130
	v_ashrrev_i32_e32 v33, 31, v32
	s_waitcnt vmcnt(62)
	v_add_f32_e32 v36, v36, v98
	v_lshl_add_u64 v[34:35], v[32:33], 2, v[134:135]
	global_store_dword v[34:35], v36, off
	v_mul_f32_e32 v34, v128, v36
	v_cvt_pk_bf16_f32 v34, v34, s0
	v_lshl_add_u64 v[32:33], v[32:33], 1, v[136:137]
	global_store_short v[32:33], v34, off
	v_or_b32_e32 v32, 0x24820, v130
	v_ashrrev_i32_e32 v33, 31, v32
	v_add_f32_e32 v36, v37, v88
	v_lshl_add_u64 v[34:35], v[32:33], 2, v[134:135]
	global_store_dword v[34:35], v36, off
	v_mul_f32_e32 v34, v128, v36
	v_cvt_pk_bf16_f32 v34, v34, s0
	v_lshl_add_u64 v[32:33], v[32:33], 1, v[136:137]
	global_store_short v[32:33], v34, off
	v_or_b32_e32 v32, 0x25020, v130
	v_ashrrev_i32_e32 v33, 31, v32
	v_add_f32_e32 v36, v38, v87
	v_lshl_add_u64 v[34:35], v[32:33], 2, v[134:135]
	global_store_dword v[34:35], v36, off
	v_mul_f32_e32 v34, v128, v36
	v_cvt_pk_bf16_f32 v34, v34, s0
	v_lshl_add_u64 v[32:33], v[32:33], 1, v[136:137]
	global_store_short v[32:33], v34, off
	v_or_b32_e32 v32, 0x25820, v130
	v_ashrrev_i32_e32 v33, 31, v32
	v_add_f32_e32 v36, v39, v86
	v_lshl_add_u64 v[34:35], v[32:33], 2, v[134:135]
	global_store_dword v[34:35], v36, off
	v_mul_f32_e32 v34, v128, v36
	v_cvt_pk_bf16_f32 v34, v34, s0
	v_lshl_add_u64 v[32:33], v[32:33], 1, v[136:137]
	global_store_short v[32:33], v34, off
	v_or_b32_e32 v32, 0x28020, v130
	v_ashrrev_i32_e32 v33, 31, v32
	v_add_f32_e32 v36, v40, v85
	v_lshl_add_u64 v[34:35], v[32:33], 2, v[134:135]
	global_store_dword v[34:35], v36, off
	v_mul_f32_e32 v34, v128, v36
	v_cvt_pk_bf16_f32 v34, v34, s0
	v_lshl_add_u64 v[32:33], v[32:33], 1, v[136:137]
	global_store_short v[32:33], v34, off
	v_or_b32_e32 v32, 0x28820, v130
	v_ashrrev_i32_e32 v33, 31, v32
	v_add_f32_e32 v36, v41, v84
	v_lshl_add_u64 v[34:35], v[32:33], 2, v[134:135]
	global_store_dword v[34:35], v36, off
	v_mul_f32_e32 v34, v128, v36
	v_cvt_pk_bf16_f32 v34, v34, s0
	v_lshl_add_u64 v[32:33], v[32:33], 1, v[136:137]
	global_store_short v[32:33], v34, off
	v_or_b32_e32 v32, 0x29020, v130
	v_ashrrev_i32_e32 v33, 31, v32
	s_waitcnt vmcnt(62)
	v_add_f32_e32 v36, v42, v83
	v_lshl_add_u64 v[34:35], v[32:33], 2, v[134:135]
	global_store_dword v[34:35], v36, off
	v_mul_f32_e32 v34, v128, v36
	v_cvt_pk_bf16_f32 v34, v34, s0
	v_lshl_add_u64 v[32:33], v[32:33], 1, v[136:137]
	global_store_short v[32:33], v34, off
	v_or_b32_e32 v32, 0x29820, v130
	v_ashrrev_i32_e32 v33, 31, v32
	v_add_f32_e32 v36, v43, v82
	v_lshl_add_u64 v[34:35], v[32:33], 2, v[134:135]
	global_store_dword v[34:35], v36, off
	v_mul_f32_e32 v34, v128, v36
	v_cvt_pk_bf16_f32 v34, v34, s0
	v_lshl_add_u64 v[32:33], v[32:33], 1, v[136:137]
	global_store_short v[32:33], v34, off
	v_or_b32_e32 v32, 0x2c020, v130
	v_ashrrev_i32_e32 v33, 31, v32
	v_add_f32_e32 v36, v44, v81
	v_lshl_add_u64 v[34:35], v[32:33], 2, v[134:135]
	global_store_dword v[34:35], v36, off
	v_mul_f32_e32 v34, v128, v36
	v_cvt_pk_bf16_f32 v34, v34, s0
	v_lshl_add_u64 v[32:33], v[32:33], 1, v[136:137]
	global_store_short v[32:33], v34, off
	v_or_b32_e32 v32, 0x2c820, v130
	v_ashrrev_i32_e32 v33, 31, v32
	v_add_f32_e32 v36, v45, v80
	v_lshl_add_u64 v[34:35], v[32:33], 2, v[134:135]
	global_store_dword v[34:35], v36, off
	v_mul_f32_e32 v34, v128, v36
	v_cvt_pk_bf16_f32 v34, v34, s0
	v_lshl_add_u64 v[32:33], v[32:33], 1, v[136:137]
	global_store_short v[32:33], v34, off
	v_or_b32_e32 v32, 0x2d020, v130
	v_ashrrev_i32_e32 v33, 31, v32
	v_add_f32_e32 v36, v46, v79
	v_lshl_add_u64 v[34:35], v[32:33], 2, v[134:135]
	global_store_dword v[34:35], v36, off
	v_mul_f32_e32 v34, v128, v36
	v_cvt_pk_bf16_f32 v34, v34, s0
	v_lshl_add_u64 v[32:33], v[32:33], 1, v[136:137]
	global_store_short v[32:33], v34, off
	v_or_b32_e32 v32, 0x2d820, v130
	v_ashrrev_i32_e32 v33, 31, v32
	v_add_f32_e32 v36, v47, v78
	v_lshl_add_u64 v[34:35], v[32:33], 2, v[134:135]
	global_store_dword v[34:35], v36, off
	v_mul_f32_e32 v34, v128, v36
	v_cvt_pk_bf16_f32 v34, v34, s0
	v_lshl_add_u64 v[32:33], v[32:33], 1, v[136:137]
	global_store_short v[32:33], v34, off
	v_or_b32_e32 v32, 0x30000, v130
	v_ashrrev_i32_e32 v33, 31, v32
	v_lshlrev_b64 v[34:35], 2, v[32:33]
	v_lshl_add_u64 v[36:37], v[132:133], 0, v[34:35]
	s_waitcnt vmcnt(47)
	v_add_f32_e32 v16, v16, v89
	v_lshl_add_u64 v[34:35], v[134:135], 0, v[34:35]
	global_load_dword v36, v[36:37], off offset:128
	s_nop 0
	global_load_dword v37, v[48:49], off offset:128
	global_load_dword v38, v[50:51], off offset:128
	global_load_dword v39, v[52:53], off offset:128
	global_load_dword v40, v[54:55], off offset:128
	global_load_dword v41, v[56:57], off offset:128
	global_load_dword v42, v[58:59], off offset:128
	global_load_dword v43, v[60:61], off offset:128
	global_load_dword v44, v[62:63], off offset:128
	global_load_dword v45, v[64:65], off offset:128
	global_load_dword v46, v[66:67], off offset:128
	global_load_dword v47, v[68:69], off offset:128
	global_load_dword v48, v[70:71], off offset:128
	global_load_dword v49, v[72:73], off offset:128
	global_load_dword v50, v[74:75], off offset:128
	global_load_dword v51, v[76:77], off offset:128
	v_lshl_add_u64 v[32:33], v[32:33], 1, v[136:137]
	global_store_dword v[34:35], v16, off
	v_mul_f32_e32 v16, v209, v16
	v_cvt_pk_bf16_f32 v16, v16, s0
	global_store_short v[32:33], v16, off
	v_or_b32_e32 v16, 0x30800, v130
	s_waitcnt vmcnt(62)
	v_add_f32_e32 v34, v17, v90
	v_ashrrev_i32_e32 v17, 31, v16
	v_lshl_add_u64 v[32:33], v[16:17], 2, v[134:135]
	global_store_dword v[32:33], v34, off
	v_mul_f32_e32 v32, v209, v34
	v_cvt_pk_bf16_f32 v32, v32, s0
	v_lshl_add_u64 v[16:17], v[16:17], 1, v[136:137]
	global_store_short v[16:17], v32, off
	v_or_b32_e32 v16, 0x31000, v130
	v_ashrrev_i32_e32 v17, 31, v16
	v_add_f32_e32 v18, v18, v91
	v_lshl_add_u64 v[32:33], v[16:17], 2, v[134:135]
	global_store_dword v[32:33], v18, off
	v_mul_f32_e32 v18, v209, v18
	v_cvt_pk_bf16_f32 v18, v18, s0
	v_lshl_add_u64 v[16:17], v[16:17], 1, v[136:137]
	global_store_short v[16:17], v18, off
	v_or_b32_e32 v16, 0x31800, v130
	v_ashrrev_i32_e32 v17, 31, v16
	v_add_f32_e32 v32, v19, v92
	v_lshl_add_u64 v[18:19], v[16:17], 2, v[134:135]
	global_store_dword v[18:19], v32, off
	v_mul_f32_e32 v18, v209, v32
	v_cvt_pk_bf16_f32 v18, v18, s0
	v_lshl_add_u64 v[16:17], v[16:17], 1, v[136:137]
	global_store_short v[16:17], v18, off
	v_or_b32_e32 v16, 0x34000, v130
	v_ashrrev_i32_e32 v17, 31, v16
	s_waitcnt vmcnt(62)
	v_add_f32_e32 v20, v20, v93
	v_lshl_add_u64 v[18:19], v[16:17], 2, v[134:135]
	global_store_dword v[18:19], v20, off
	v_mul_f32_e32 v18, v209, v20
	v_cvt_pk_bf16_f32 v18, v18, s0
	v_lshl_add_u64 v[16:17], v[16:17], 1, v[136:137]
	global_store_short v[16:17], v18, off
	v_or_b32_e32 v16, 0x34800, v130
	v_ashrrev_i32_e32 v17, 31, v16
	v_add_f32_e32 v20, v21, v94
	v_lshl_add_u64 v[18:19], v[16:17], 2, v[134:135]
	global_store_dword v[18:19], v20, off
	v_mul_f32_e32 v18, v209, v20
	v_cvt_pk_bf16_f32 v18, v18, s0
	v_lshl_add_u64 v[16:17], v[16:17], 1, v[136:137]
	global_store_short v[16:17], v18, off
	v_or_b32_e32 v16, 0x35000, v130
	v_ashrrev_i32_e32 v17, 31, v16
	v_add_f32_e32 v20, v22, v95
	v_lshl_add_u64 v[18:19], v[16:17], 2, v[134:135]
	global_store_dword v[18:19], v20, off
	v_mul_f32_e32 v18, v209, v20
	v_cvt_pk_bf16_f32 v18, v18, s0
	v_lshl_add_u64 v[16:17], v[16:17], 1, v[136:137]
	global_store_short v[16:17], v18, off
	v_or_b32_e32 v16, 0x35800, v130
	v_ashrrev_i32_e32 v17, 31, v16
	v_add_f32_e32 v20, v23, v96
	v_lshl_add_u64 v[18:19], v[16:17], 2, v[134:135]
	global_store_dword v[18:19], v20, off
	v_mul_f32_e32 v18, v209, v20
	v_cvt_pk_bf16_f32 v18, v18, s0
	v_lshl_add_u64 v[16:17], v[16:17], 1, v[136:137]
	global_store_short v[16:17], v18, off
	v_or_b32_e32 v16, 0x38000, v130
	v_ashrrev_i32_e32 v17, 31, v16
	v_add_f32_e32 v20, v24, v97
	v_lshl_add_u64 v[18:19], v[16:17], 2, v[134:135]
	global_store_dword v[18:19], v20, off
	v_mul_f32_e32 v18, v209, v20
	v_cvt_pk_bf16_f32 v18, v18, s0
	v_lshl_add_u64 v[16:17], v[16:17], 1, v[136:137]
	global_store_short v[16:17], v18, off
	v_or_b32_e32 v16, 0x38800, v130
	v_ashrrev_i32_e32 v17, 31, v16
	v_add_f32_e32 v20, v25, v103
	v_lshl_add_u64 v[18:19], v[16:17], 2, v[134:135]
	global_store_dword v[18:19], v20, off
	v_mul_f32_e32 v18, v209, v20
	v_cvt_pk_bf16_f32 v18, v18, s0
	v_lshl_add_u64 v[16:17], v[16:17], 1, v[136:137]
	global_store_short v[16:17], v18, off
	v_or_b32_e32 v16, 0x39000, v130
	v_ashrrev_i32_e32 v17, 31, v16
	s_waitcnt vmcnt(62)
	v_add_f32_e32 v20, v26, v104
	v_lshl_add_u64 v[18:19], v[16:17], 2, v[134:135]
	global_store_dword v[18:19], v20, off
	v_mul_f32_e32 v18, v209, v20
	v_cvt_pk_bf16_f32 v18, v18, s0
	v_lshl_add_u64 v[16:17], v[16:17], 1, v[136:137]
	global_store_short v[16:17], v18, off
	v_or_b32_e32 v16, 0x39800, v130
	v_ashrrev_i32_e32 v17, 31, v16
	v_add_f32_e32 v20, v27, v105
	v_lshl_add_u64 v[18:19], v[16:17], 2, v[134:135]
	global_store_dword v[18:19], v20, off
	v_mul_f32_e32 v18, v209, v20
	v_cvt_pk_bf16_f32 v18, v18, s0
	v_lshl_add_u64 v[16:17], v[16:17], 1, v[136:137]
	global_store_short v[16:17], v18, off
	v_or_b32_e32 v16, 0x3c000, v130
	v_ashrrev_i32_e32 v17, 31, v16
	v_add_f32_e32 v20, v28, v106
	v_lshl_add_u64 v[18:19], v[16:17], 2, v[134:135]
	global_store_dword v[18:19], v20, off
	v_mul_f32_e32 v18, v209, v20
	v_cvt_pk_bf16_f32 v18, v18, s0
	v_lshl_add_u64 v[16:17], v[16:17], 1, v[136:137]
	global_store_short v[16:17], v18, off
	v_or_b32_e32 v16, 0x3c800, v130
	v_ashrrev_i32_e32 v17, 31, v16
	v_add_f32_e32 v20, v29, v107
	v_lshl_add_u64 v[18:19], v[16:17], 2, v[134:135]
	global_store_dword v[18:19], v20, off
	v_mul_f32_e32 v18, v209, v20
	v_cvt_pk_bf16_f32 v18, v18, s0
	v_lshl_add_u64 v[16:17], v[16:17], 1, v[136:137]
	global_store_short v[16:17], v18, off
	v_or_b32_e32 v16, 0x3d000, v130
	v_ashrrev_i32_e32 v17, 31, v16
	v_add_f32_e32 v20, v30, v108
	v_lshl_add_u64 v[18:19], v[16:17], 2, v[134:135]
	global_store_dword v[18:19], v20, off
	v_mul_f32_e32 v18, v209, v20
	v_cvt_pk_bf16_f32 v18, v18, s0
	v_lshl_add_u64 v[16:17], v[16:17], 1, v[136:137]
	global_store_short v[16:17], v18, off
	v_or_b32_e32 v16, 0x3d800, v130
	v_ashrrev_i32_e32 v17, 31, v16
	v_add_f32_e32 v20, v31, v109
	v_lshl_add_u64 v[18:19], v[16:17], 2, v[134:135]
	global_store_dword v[18:19], v20, off
	v_mul_f32_e32 v18, v209, v20
	v_cvt_pk_bf16_f32 v18, v18, s0
	v_lshl_add_u64 v[16:17], v[16:17], 1, v[136:137]
	global_store_short v[16:17], v18, off
	v_or_b32_e32 v16, 0x30020, v130
	v_ashrrev_i32_e32 v17, 31, v16
	s_waitcnt vmcnt(47)
	v_add_f32_e32 v0, v0, v36
	v_lshl_add_u64 v[18:19], v[16:17], 2, v[134:135]
	global_store_dword v[18:19], v0, off
	v_mul_f32_e32 v0, v128, v0
	v_cvt_pk_bf16_f32 v0, v0, s0
	v_lshl_add_u64 v[16:17], v[16:17], 1, v[136:137]
	global_store_short v[16:17], v0, off
	v_or_b32_e32 v0, 0x30820, v130
	s_waitcnt vmcnt(48)
	v_add_f32_e32 v18, v1, v37
	v_ashrrev_i32_e32 v1, 31, v0
	v_lshl_add_u64 v[16:17], v[0:1], 2, v[134:135]
	global_store_dword v[16:17], v18, off
	v_mul_f32_e32 v16, v128, v18
	v_cvt_pk_bf16_f32 v16, v16, s0
	v_lshl_add_u64 v[0:1], v[0:1], 1, v[136:137]
	global_store_short v[0:1], v16, off
	v_or_b32_e32 v0, 0x31020, v130
	v_ashrrev_i32_e32 v1, 31, v0
	s_waitcnt vmcnt(49)
	v_add_f32_e32 v2, v2, v38
	v_lshl_add_u64 v[16:17], v[0:1], 2, v[134:135]
	global_store_dword v[16:17], v2, off
	v_mul_f32_e32 v2, v128, v2
	v_cvt_pk_bf16_f32 v2, v2, s0
	v_lshl_add_u64 v[0:1], v[0:1], 1, v[136:137]
	global_store_short v[0:1], v2, off
	v_or_b32_e32 v0, 0x31820, v130
	v_ashrrev_i32_e32 v1, 31, v0
	s_waitcnt vmcnt(50)
	v_add_f32_e32 v16, v3, v39
	v_lshl_add_u64 v[2:3], v[0:1], 2, v[134:135]
	global_store_dword v[2:3], v16, off
	v_mul_f32_e32 v2, v128, v16
	v_cvt_pk_bf16_f32 v2, v2, s0
	v_lshl_add_u64 v[0:1], v[0:1], 1, v[136:137]
	global_store_short v[0:1], v2, off
	v_or_b32_e32 v0, 0x34020, v130
	v_ashrrev_i32_e32 v1, 31, v0
	s_waitcnt vmcnt(51)
	v_add_f32_e32 v4, v4, v40
	v_lshl_add_u64 v[2:3], v[0:1], 2, v[134:135]
	global_store_dword v[2:3], v4, off
	v_mul_f32_e32 v2, v128, v4
	v_cvt_pk_bf16_f32 v2, v2, s0
	v_lshl_add_u64 v[0:1], v[0:1], 1, v[136:137]
	global_store_short v[0:1], v2, off
	v_or_b32_e32 v0, 0x34820, v130
	v_ashrrev_i32_e32 v1, 31, v0
	s_waitcnt vmcnt(52)
	v_add_f32_e32 v4, v5, v41
	v_lshl_add_u64 v[2:3], v[0:1], 2, v[134:135]
	global_store_dword v[2:3], v4, off
	v_mul_f32_e32 v2, v128, v4
	v_cvt_pk_bf16_f32 v2, v2, s0
	v_lshl_add_u64 v[0:1], v[0:1], 1, v[136:137]
	global_store_short v[0:1], v2, off
	v_or_b32_e32 v0, 0x35020, v130
	v_ashrrev_i32_e32 v1, 31, v0
	s_waitcnt vmcnt(53)
	v_add_f32_e32 v4, v6, v42
	v_lshl_add_u64 v[2:3], v[0:1], 2, v[134:135]
	global_store_dword v[2:3], v4, off
	v_mul_f32_e32 v2, v128, v4
	v_cvt_pk_bf16_f32 v2, v2, s0
	v_lshl_add_u64 v[0:1], v[0:1], 1, v[136:137]
	global_store_short v[0:1], v2, off
	v_or_b32_e32 v0, 0x35820, v130
	v_ashrrev_i32_e32 v1, 31, v0
	s_waitcnt vmcnt(54)
	v_add_f32_e32 v4, v7, v43
	v_lshl_add_u64 v[2:3], v[0:1], 2, v[134:135]
	global_store_dword v[2:3], v4, off
	v_mul_f32_e32 v2, v128, v4
	v_cvt_pk_bf16_f32 v2, v2, s0
	v_lshl_add_u64 v[0:1], v[0:1], 1, v[136:137]
	global_store_short v[0:1], v2, off
	v_or_b32_e32 v0, 0x38020, v130
	v_ashrrev_i32_e32 v1, 31, v0
	s_waitcnt vmcnt(55)
	v_add_f32_e32 v4, v8, v44
	v_lshl_add_u64 v[2:3], v[0:1], 2, v[134:135]
	global_store_dword v[2:3], v4, off
	v_mul_f32_e32 v2, v128, v4
	v_cvt_pk_bf16_f32 v2, v2, s0
	v_lshl_add_u64 v[0:1], v[0:1], 1, v[136:137]
	global_store_short v[0:1], v2, off
	v_or_b32_e32 v0, 0x38820, v130
	v_ashrrev_i32_e32 v1, 31, v0
	s_waitcnt vmcnt(56)
	v_add_f32_e32 v4, v9, v45
	v_lshl_add_u64 v[2:3], v[0:1], 2, v[134:135]
	global_store_dword v[2:3], v4, off
	v_mul_f32_e32 v2, v128, v4
	v_cvt_pk_bf16_f32 v2, v2, s0
	v_lshl_add_u64 v[0:1], v[0:1], 1, v[136:137]
	global_store_short v[0:1], v2, off
	v_or_b32_e32 v0, 0x39020, v130
	v_ashrrev_i32_e32 v1, 31, v0
	s_waitcnt vmcnt(57)
	v_add_f32_e32 v4, v10, v46
	v_lshl_add_u64 v[2:3], v[0:1], 2, v[134:135]
	global_store_dword v[2:3], v4, off
	v_mul_f32_e32 v2, v128, v4
	v_cvt_pk_bf16_f32 v2, v2, s0
	v_lshl_add_u64 v[0:1], v[0:1], 1, v[136:137]
	global_store_short v[0:1], v2, off
	v_or_b32_e32 v0, 0x39820, v130
	v_ashrrev_i32_e32 v1, 31, v0
	s_waitcnt vmcnt(58)
	v_add_f32_e32 v4, v11, v47
	v_lshl_add_u64 v[2:3], v[0:1], 2, v[134:135]
	global_store_dword v[2:3], v4, off
	v_mul_f32_e32 v2, v128, v4
	v_cvt_pk_bf16_f32 v2, v2, s0
	v_lshl_add_u64 v[0:1], v[0:1], 1, v[136:137]
	global_store_short v[0:1], v2, off
	v_or_b32_e32 v0, 0x3c020, v130
	v_ashrrev_i32_e32 v1, 31, v0
	s_waitcnt vmcnt(59)
	v_add_f32_e32 v4, v12, v48
	v_lshl_add_u64 v[2:3], v[0:1], 2, v[134:135]
	global_store_dword v[2:3], v4, off
	v_mul_f32_e32 v2, v128, v4
	v_cvt_pk_bf16_f32 v2, v2, s0
	v_lshl_add_u64 v[0:1], v[0:1], 1, v[136:137]
	global_store_short v[0:1], v2, off
	v_or_b32_e32 v0, 0x3c820, v130
	v_ashrrev_i32_e32 v1, 31, v0
	s_waitcnt vmcnt(60)
	v_add_f32_e32 v4, v13, v49
	v_lshl_add_u64 v[2:3], v[0:1], 2, v[134:135]
	global_store_dword v[2:3], v4, off
	v_mul_f32_e32 v2, v128, v4
	v_cvt_pk_bf16_f32 v2, v2, s0
	v_lshl_add_u64 v[0:1], v[0:1], 1, v[136:137]
	global_store_short v[0:1], v2, off
	v_or_b32_e32 v0, 0x3d020, v130
	v_ashrrev_i32_e32 v1, 31, v0
	s_waitcnt vmcnt(61)
	v_add_f32_e32 v4, v14, v50
	v_lshl_add_u64 v[2:3], v[0:1], 2, v[134:135]
	global_store_dword v[2:3], v4, off
	v_mul_f32_e32 v2, v128, v4
	v_cvt_pk_bf16_f32 v2, v2, s0
	v_lshl_add_u64 v[0:1], v[0:1], 1, v[136:137]
	global_store_short v[0:1], v2, off
	v_or_b32_e32 v0, 0x3d820, v130
	v_ashrrev_i32_e32 v1, 31, v0
	s_waitcnt vmcnt(62)
	v_add_f32_e32 v4, v15, v51
	v_lshl_add_u64 v[2:3], v[0:1], 2, v[134:135]
	global_store_dword v[2:3], v4, off
	v_mul_f32_e32 v2, v128, v4
	v_cvt_pk_bf16_f32 v2, v2, s0
	v_lshl_add_u64 v[0:1], v[0:1], 1, v[136:137]
	global_store_short v[0:1], v2, off
	v_add_u32_e32 v206, s46, v206
	v_add_u32_e32 v208, s46, v208
	v_cmp_le_i32_e64 s[40:41], s51, v206
	s_and_b64 vcc, exec, s[40:41]
	s_cbranch_vccz .LBB0_707

.LBB0_920:
	v_mov_b32_e32 v92, 0x7fffffff
	v_cndmask_b32_e64 v100, v173, v92, s[12:13]
	v_cndmask_b32_e64 v101, v173, v92, s[16:17]
	v_cndmask_b32_e64 v102, v173, v92, s[18:19]
	v_cndmask_b32_e64 v103, v173, v92, s[22:23]
	v_cndmask_b32_e64 v104, v173, v92, s[24:25]
	v_cndmask_b32_e64 v105, v173, v92, s[26:27]
	v_cndmask_b32_e64 v106, v173, v92, s[30:31]
	v_cndmask_b32_e64 v107, v173, v92, s[34:35]
	v_cndmask_b32_e64 v108, v173, v92, s[36:37]
	v_cndmask_b32_e64 v109, v173, v92, s[38:39]
	v_cndmask_b32_e64 v110, v173, v92, s[42:43]
	v_cndmask_b32_e64 v111, v173, v92, s[44:45]
	v_cndmask_b32_e64 v112, v173, v92, s[46:47]
	v_cndmask_b32_e64 v113, v173, v92, s[48:49]
	v_cndmask_b32_e64 v114, v173, v92, s[50:51]
	v_cndmask_b32_e64 v115, v92, v173, s[40:41]
	v_cndmask_b32_e64 v116, v173, v92, s[40:41]
	v_cndmask_b32_e64 v117, v173, v92, s[6:7]
	v_cndmask_b32_e64 v118, v92, v173, s[6:7]
	v_cndmask_b32_e64 v119, v173, v92, s[28:29]
	v_cndmask_b32_e64 v120, v92, v173, s[28:29]
	v_cndmask_b32_e64 v121, v173, v92, s[20:21]
	v_cndmask_b32_e64 v122, v92, v173, s[20:21]
	v_cndmask_b32_e64 v123, v173, v92, s[14:15]
	v_cndmask_b32_e64 v124, v92, v173, s[14:15]
	v_cndmask_b32_e64 v125, v173, v92, s[10:11]
	v_cndmask_b32_e64 v126, v92, v173, s[10:11]
	v_cndmask_b32_e64 v127, v173, v92, s[52:53]
	v_ashrrev_i32_e32 v5, 31, v4
	v_lshlrev_b64 v[0:1], 13, v[4:5]
	v_lshl_add_u64 v[18:19], v[14:15], 0, v[0:1]
	global_load_dwordx4 v[24:27], v[18:19], off offset:16
	global_load_dwordx4 v[28:31], v[18:19], off
	global_load_dwordx4 v[32:35], v[18:19], off offset:48
	global_load_dwordx4 v[60:63], v[18:19], off offset:32
	v_lshlrev_b64 v[2:3], 12, v[4:5]
	v_add_co_u32_e32 v20, vcc, s80, v18
	v_lshl_add_u64 v[2:3], v[8:9], 0, v[2:3]
	s_nop 0
	v_addc_co_u32_e32 v21, vcc, 0, v19, vcc
	global_load_dwordx4 v[36:39], v[2:3], off
	global_load_dwordx4 v[64:67], v[2:3], off offset:16
	global_load_dwordx4 v[68:71], v[2:3], off offset:2048
	v_lshl_add_u64 v[22:23], v[18:19], 0, s[62:63]
	global_load_dwordx4 v[72:75], v[20:21], off
	global_load_dwordx4 v[76:79], v[22:23], off offset:16
	global_load_dwordx4 v[80:83], v[22:23], off offset:32
	global_load_dwordx4 v[84:87], v[22:23], off offset:48
	global_load_dwordx4 v[88:91], v[2:3], off offset:2064
	v_lshl_add_u64 v[0:1], v[16:17], 0, v[0:1]
	s_mov_b64 s[64:65], 0
	s_waitcnt vmcnt(11)
	v_mul_f32_e32 v40, v25, v25
	s_waitcnt vmcnt(10)
	v_mul_f32_e32 v5, v29, v29
	v_fmac_f32_e32 v5, v28, v28
	s_waitcnt vmcnt(8)
	v_mul_f32_e32 v42, v61, v61
	v_fmac_f32_e32 v40, v24, v24
	v_mul_f32_e32 v44, v33, v33
	v_fmac_f32_e32 v42, v60, v60
	v_fmac_f32_e32 v5, v30, v30
	v_fmac_f32_e32 v40, v26, v26
	s_waitcnt vmcnt(3)
	v_mov_b32_e32 v3, v76
	v_mov_b32_e32 v76, v73
	v_fmac_f32_e32 v44, v32, v32
	v_mov_b32_e32 v2, v72
	v_fmac_f32_e32 v42, v62, v62
	v_pk_mul_f32 v[60:61], v[76:77], v[76:77]
	v_fmac_f32_e32 v5, v31, v31
	v_fmac_f32_e32 v40, v27, v27
	v_mov_b32_e32 v24, v74
	v_mov_b32_e32 v25, v78
	s_waitcnt vmcnt(1)
	v_mov_b32_e32 v29, v84
	v_mov_b32_e32 v84, v81
	v_fmac_f32_e32 v44, v34, v34
	v_fmac_f32_e32 v42, v63, v63
	v_pk_fma_f32 v[2:3], v[2:3], v[2:3], v[60:61]
	v_add_f32_e32 v5, v5, v40
	v_lshlrev_b32_e32 v50, 16, v64
	v_and_b32_e32 v49, 0xffff0000, v64
	v_lshlrev_b32_e32 v48, 16, v65
	v_and_b32_e32 v47, 0xffff0000, v65
	v_mov_b32_e32 v78, v75
	v_mov_b32_e32 v28, v80
	v_pk_mul_f32 v[64:65], v[84:85], v[84:85]
	v_fmac_f32_e32 v44, v35, v35
	v_pk_fma_f32 v[2:3], v[24:25], v[24:25], v[2:3]
	v_add_f32_e32 v5, v5, v42
	v_mov_b32_e32 v32, v82
	v_mov_b32_e32 v33, v86
	v_pk_fma_f32 v[26:27], v[28:29], v[28:29], v[64:65]
	v_pk_fma_f32 v[2:3], v[78:79], v[78:79], v[2:3]
	v_add_f32_e32 v5, v5, v44
	v_mov_b32_e32 v86, v83
	v_pk_fma_f32 v[24:25], v[32:33], v[32:33], v[26:27]
	v_add_f32_e32 v2, v5, v2
	v_pk_fma_f32 v[24:25], v[86:87], v[86:87], v[24:25]
	v_add_f32_e32 v2, v2, v3
	v_add_f32_e32 v2, v2, v24
	v_add_f32_e32 v2, v2, v25
	v_mov_b32_e32 v3, v2
	v_mov_b32_e32 v5, v2
	s_nop 1
	v_permlane32_swap_b32_e32 v3, v5
	v_cndmask_b32_e64 v3, v3, v5, s[8:9]
	v_add_f32_e32 v2, v2, v3
	v_mov_b32_e32 v3, v2
	v_mov_b32_e32 v5, v2
	s_nop 1
	v_permlane16_swap_b32_e32 v3, v5
	v_cndmask_b32_e64 v3, v3, v5, s[6:7]
	v_add_f32_e32 v2, v2, v3
	v_lshlrev_b32_e32 v58, 16, v36
	v_and_b32_e32 v57, 0xffff0000, v36
	v_add_f32_dpp v2, v2, v2 row_ror:8 row_mask:0xf bank_mask:0xf bound_ctrl:1
	v_lshlrev_b32_e32 v56, 16, v37
	v_and_b32_e32 v55, 0xffff0000, v37
	v_mov_b32_dpp v3, v2 row_half_mirror row_mask:0xf bank_mask:0xf bound_ctrl:1
	v_max3_f32 v36, |v58|, 0, |v57|
	v_lshlrev_b32_e32 v54, 16, v38
	v_add_f32_dpp v2, v3, v2 quad_perm:[3,2,1,0] row_mask:0xf bank_mask:0xf bound_ctrl:1
	v_and_b32_e32 v53, 0xffff0000, v38
	v_max3_f32 v30, v36, |v56|, |v55|
	v_add_f32_dpp v2, v2, v2 quad_perm:[2,3,0,1] row_mask:0xf bank_mask:0xf bound_ctrl:1
	v_lshlrev_b32_e32 v52, 16, v39
	v_and_b32_e32 v51, 0xffff0000, v39
	v_max3_f32 v28, v30, |v54|, |v53|
	v_add_f32_dpp v2, v2, v2 quad_perm:[1,0,3,2] row_mask:0xf bank_mask:0xf bound_ctrl:1
	v_max3_f32 v26, v28, |v52|, |v51|
	v_fmamk_f32 v2, v2, 0x3a000000, v171
	v_max3_f32 v26, v26, |v50|, |v49|
	v_mul_f32_e32 v3, 0x4b800000, v2
	v_cmp_gt_f32_e32 vcc, s81, v2
	v_lshlrev_b32_e32 v46, 16, v66
	v_and_b32_e32 v45, 0xffff0000, v66
	v_cndmask_b32_e32 v2, v2, v3, vcc
	v_max3_f32 v3, v26, |v48|, |v47|
	v_lshlrev_b32_e32 v43, 16, v67
	v_and_b32_e32 v41, 0xffff0000, v67
	v_max3_f32 v3, v3, |v46|, |v45|
	v_lshlrev_b32_e32 v39, 16, v68
	v_and_b32_e32 v37, 0xffff0000, v68
	v_max3_f32 v3, v3, |v43|, |v41|
	v_lshlrev_b32_e32 v44, 16, v69
	v_and_b32_e32 v42, 0xffff0000, v69
	v_max3_f32 v3, v3, |v39|, |v37|
	v_lshlrev_b32_e32 v40, 16, v70
	v_and_b32_e32 v38, 0xffff0000, v70
	v_max3_f32 v3, v3, |v44|, |v42|
	v_lshlrev_b32_e32 v36, 16, v71
	v_and_b32_e32 v35, 0xffff0000, v71
	v_max3_f32 v3, v3, |v40|, |v38|
	s_waitcnt vmcnt(0)
	v_lshlrev_b32_e32 v34, 16, v88
	v_and_b32_e32 v33, 0xffff0000, v88
	v_max3_f32 v3, v3, |v36|, |v35|
	v_lshlrev_b32_e32 v32, 16, v89
	v_and_b32_e32 v31, 0xffff0000, v89
	v_max3_f32 v3, v3, |v34|, |v33|
	v_lshlrev_b32_e32 v30, 16, v90
	v_and_b32_e32 v29, 0xffff0000, v90
	v_max3_f32 v3, v3, |v32|, |v31|
	v_lshlrev_b32_e32 v25, 16, v91
	v_and_b32_e32 v5, 0xffff0000, v91
	v_max3_f32 v3, v3, |v30|, |v29|
	v_max3_f32 v3, v3, |v25|, |v5|
	v_mov_b32_e32 v26, v3
	v_mov_b32_e32 v27, v3
	s_nop 1
	v_permlane32_swap_b32_e32 v26, v27
	v_cndmask_b32_e64 v26, v26, v27, s[8:9]
	v_max_f32_e32 v26, v26, v26
	v_max_f32_e32 v3, v3, v26
	v_mov_b32_e32 v26, v3
	v_mov_b32_e32 v27, v3
	s_nop 1
	v_permlane16_swap_b32_e32 v26, v27
	v_cndmask_b32_e64 v26, v26, v27, s[6:7]
	v_max_f32_e32 v26, v26, v26
	v_max_f32_e32 v3, v3, v26
	v_rsq_f32_e32 v2, v2
	v_mov_b32_e32 v28, v170
	v_mov_b32_dpp v26, v3 row_ror:8 row_mask:0xf bank_mask:0xf bound_ctrl:1
	v_max_f32_e32 v26, v26, v26
	v_max_f32_e32 v3, v3, v26
	v_mul_f32_e32 v24, 0x45800000, v2
	v_cndmask_b32_e32 v24, v2, v24, vcc
	v_mov_b32_dpp v26, v3 row_half_mirror row_mask:0xf bank_mask:0xf bound_ctrl:1
	s_nop 1
	v_mov_b32_dpp v26, v26 quad_perm:[3,2,1,0] row_mask:0xf bank_mask:0xf bound_ctrl:1
	v_max_f32_e32 v26, v26, v26
	v_max_f32_e32 v3, v3, v26
	s_nop 1
	v_mov_b32_dpp v26, v3 quad_perm:[2,3,0,1] row_mask:0xf bank_mask:0xf bound_ctrl:1
	v_max_f32_e32 v26, v26, v26
	v_max_f32_e32 v26, v3, v26
	s_nop 1
	v_mov_b32_dpp v27, v26 quad_perm:[1,0,3,2] row_mask:0xf bank_mask:0xf bound_ctrl:1
	s_branch .LBB0_922

.LBB0_922:
	s_waitcnt lgkmcnt(0)
	v_lshl_add_u64 v[2:3], v[0:1], 0, s[64:65]
	v_add_co_u32_e32 v60, vcc, 0x8008000, v2
	s_nop 1
	v_addc_co_u32_e32 v61, vcc, 0, v3, vcc
	global_load_dword v59, v[60:61], off
	global_load_dword v62, v[60:61], off offset:256
	global_load_dword v63, v[60:61], off offset:512
	s_nop 0
	global_load_dword v60, v[60:61], off offset:768
	s_waitcnt vmcnt(3)
	v_ashrrev_i32_e32 v61, 31, v59
	v_and_b32_e32 v64, 0xffffff80, v59
	s_waitcnt vmcnt(2)
	v_ashrrev_i32_e32 v65, 31, v62
	s_waitcnt vmcnt(1)
	v_ashrrev_i32_e32 v67, 31, v63
	v_and_b32_e32 v61, 0x7fffff80, v61
	v_and_b32_e32 v66, 0xffffff80, v62
	v_and_b32_e32 v68, 0xffffff80, v63
	v_and_b32_e32 v65, 0x7fffff80, v65
	v_and_b32_e32 v67, 0x7fffff80, v67
	v_bitop3_b32 v61, v61, v164, v64 bitop3:0xde
	v_bitop3_b32 v64, v65, v165, v66 bitop3:0xde
	v_bitop3_b32 v65, v67, v164, v68 bitop3:0xde
	v_mov_b32_dpp v67, v61 quad_perm:[1,0,3,2] row_mask:0xf bank_mask:0xf bound_ctrl:1
	v_mov_b32_dpp v68, v64 quad_perm:[1,0,3,2] row_mask:0xf bank_mask:0xf bound_ctrl:1
	v_med3_i32 v61, v61, v67, v100
	v_med3_i32 v64, v64, v68, v100
	s_waitcnt vmcnt(0)
	v_ashrrev_i32_e32 v69, 31, v60
	v_mov_b32_dpp v67, v61 quad_perm:[2,3,0,1] row_mask:0xf bank_mask:0xf bound_ctrl:1
	v_mov_b32_dpp v68, v64 quad_perm:[2,3,0,1] row_mask:0xf bank_mask:0xf bound_ctrl:1
	v_med3_i32 v61, v61, v67, v101
	v_med3_i32 v64, v64, v68, v101
	v_and_b32_e32 v70, 0xffffff80, v60
	v_mov_b32_dpp v67, v61 quad_perm:[1,0,3,2] row_mask:0xf bank_mask:0xf bound_ctrl:1
	v_mov_b32_dpp v68, v64 quad_perm:[1,0,3,2] row_mask:0xf bank_mask:0xf bound_ctrl:1
	v_med3_i32 v61, v61, v67, v102
	v_and_b32_e32 v69, 0x7fffff80, v69
	v_med3_i32 v64, v64, v68, v102
	v_mov_b32_dpp v67, v61 row_half_mirror row_mask:0xf bank_mask:0xf bound_ctrl:1
	v_bitop3_b32 v66, v69, v165, v70 bitop3:0xde
	v_mov_b32_dpp v68, v64 row_half_mirror row_mask:0xf bank_mask:0xf bound_ctrl:1
	v_mov_b32_dpp v69, v67 quad_perm:[3,2,1,0] row_mask:0xf bank_mask:0xf bound_ctrl:1
	s_nop 0
	v_mov_b32_dpp v67, v68 quad_perm:[3,2,1,0] row_mask:0xf bank_mask:0xf bound_ctrl:1
	v_med3_i32 v61, v61, v69, v103
	v_med3_i32 v64, v64, v67, v103
	s_nop 0
	v_mov_b32_dpp v67, v61 quad_perm:[2,3,0,1] row_mask:0xf bank_mask:0xf bound_ctrl:1
	v_mov_b32_dpp v68, v64 quad_perm:[2,3,0,1] row_mask:0xf bank_mask:0xf bound_ctrl:1
	v_med3_i32 v61, v61, v67, v104
	v_med3_i32 v64, v64, v68, v104
	s_nop 0
	v_mov_b32_dpp v67, v61 quad_perm:[1,0,3,2] row_mask:0xf bank_mask:0xf bound_ctrl:1
	v_mov_b32_dpp v68, v64 quad_perm:[1,0,3,2] row_mask:0xf bank_mask:0xf bound_ctrl:1
	v_med3_i32 v61, v61, v67, v105
	v_med3_i32 v64, v64, v68, v105
	s_nop 0
	v_mov_b32_dpp v67, v61 row_ror:8 row_mask:0xf bank_mask:0xf bound_ctrl:1
	v_mov_b32_dpp v68, v64 row_ror:8 row_mask:0xf bank_mask:0xf bound_ctrl:1
	v_med3_i32 v61, v61, v67, v106
	v_med3_i32 v64, v64, v68, v106
	s_nop 0
	v_mov_b32_dpp v67, v61 row_half_mirror row_mask:0xf bank_mask:0xf bound_ctrl:1
	v_mov_b32_dpp v68, v64 row_half_mirror row_mask:0xf bank_mask:0xf bound_ctrl:1
	s_nop 0
	v_mov_b32_dpp v69, v67 quad_perm:[3,2,1,0] row_mask:0xf bank_mask:0xf bound_ctrl:1
	v_mov_b32_dpp v67, v68 quad_perm:[3,2,1,0] row_mask:0xf bank_mask:0xf bound_ctrl:1
	v_med3_i32 v61, v61, v69, v107
	v_med3_i32 v64, v64, v67, v107
	s_nop 0
	v_mov_b32_dpp v67, v61 quad_perm:[2,3,0,1] row_mask:0xf bank_mask:0xf bound_ctrl:1
	v_mov_b32_dpp v68, v64 quad_perm:[2,3,0,1] row_mask:0xf bank_mask:0xf bound_ctrl:1
	v_med3_i32 v61, v61, v67, v108
	v_med3_i32 v64, v64, v68, v108
	s_nop 0
	v_mov_b32_dpp v67, v61 quad_perm:[1,0,3,2] row_mask:0xf bank_mask:0xf bound_ctrl:1
	v_mov_b32_dpp v68, v64 quad_perm:[1,0,3,2] row_mask:0xf bank_mask:0xf bound_ctrl:1
	v_med3_i32 v61, v61, v67, v109
	v_med3_i32 v64, v64, v68, v109
	v_mov_b32_e32 v67, v61
	v_mov_b32_e32 v68, v61
	v_mov_b32_e32 v69, v64
	v_mov_b32_e32 v70, v64
	v_permlane16_swap_b32_e32 v67, v68
	s_nop 0
	v_permlane16_swap_b32_e32 v69, v70
	v_cndmask_b32_e64 v67, v67, v68, s[6:7]
	v_cndmask_b32_e64 v68, v69, v70, s[6:7]
	v_max_i32_e32 v69, v61, v67
	v_min_i32_e32 v61, v61, v67
	v_cndmask_b32_e64 v61, v61, v69, s[42:43]
	v_med3_i32 v64, v64, v68, v110
	s_nop 0
	v_mov_b32_dpp v67, v61 row_ror:8 row_mask:0xf bank_mask:0xf bound_ctrl:1
	v_mov_b32_dpp v68, v64 row_ror:8 row_mask:0xf bank_mask:0xf bound_ctrl:1
	v_med3_i32 v61, v61, v67, v111
	v_med3_i32 v64, v64, v68, v111
	s_nop 0
	v_mov_b32_dpp v67, v61 row_half_mirror row_mask:0xf bank_mask:0xf bound_ctrl:1
	v_mov_b32_dpp v68, v64 row_half_mirror row_mask:0xf bank_mask:0xf bound_ctrl:1
	s_nop 0
	v_mov_b32_dpp v69, v67 quad_perm:[3,2,1,0] row_mask:0xf bank_mask:0xf bound_ctrl:1
	v_mov_b32_dpp v67, v68 quad_perm:[3,2,1,0] row_mask:0xf bank_mask:0xf bound_ctrl:1
	v_med3_i32 v61, v61, v69, v112
	v_med3_i32 v64, v64, v67, v112
	s_nop 0
	v_mov_b32_dpp v67, v61 quad_perm:[2,3,0,1] row_mask:0xf bank_mask:0xf bound_ctrl:1
	v_med3_i32 v61, v61, v67, v113
	v_mov_b32_dpp v67, v64 quad_perm:[2,3,0,1] row_mask:0xf bank_mask:0xf bound_ctrl:1
	v_med3_i32 v64, v64, v67, v113
	v_mov_b32_dpp v67, v61 quad_perm:[1,0,3,2] row_mask:0xf bank_mask:0xf bound_ctrl:1
	v_med3_i32 v61, v61, v67, v114
	v_mov_b32_dpp v67, v64 quad_perm:[1,0,3,2] row_mask:0xf bank_mask:0xf bound_ctrl:1
	v_med3_i32 v64, v64, v67, v114
	v_mov_b32_e32 v67, v61
	v_mov_b32_e32 v68, v61
	s_nop 1
	v_permlane32_swap_b32_e32 v67, v68
	v_cndmask_b32_e64 v67, v67, v68, s[8:9]
	v_mov_b32_e32 v68, v64
	v_mov_b32_e32 v69, v64
	s_nop 1
	v_permlane32_swap_b32_e32 v68, v69
	v_cndmask_b32_e64 v68, v68, v69, s[8:9]
	v_med3_i32 v61, v61, v67, v115
	v_med3_i32 v64, v64, v68, v116
	v_mov_b32_e32 v67, v61
	v_mov_b32_e32 v68, v61
	s_nop 1
	v_permlane16_swap_b32_e32 v67, v68
	v_cndmask_b32_e64 v67, v67, v68, s[6:7]
	v_mov_b32_e32 v68, v64
	v_mov_b32_e32 v69, v64
	s_nop 1
	v_permlane16_swap_b32_e32 v68, v69
	v_cndmask_b32_e64 v68, v68, v69, s[6:7]
	v_med3_i32 v61, v61, v67, v117
	v_med3_i32 v64, v64, v68, v118
	s_nop 0
	v_mov_b32_dpp v67, v61 row_ror:8 row_mask:0xf bank_mask:0xf bound_ctrl:1
	v_med3_i32 v61, v61, v67, v119
	v_mov_b32_dpp v67, v64 row_ror:8 row_mask:0xf bank_mask:0xf bound_ctrl:1
	v_med3_i32 v64, v64, v67, v120
	v_mov_b32_dpp v67, v61 row_half_mirror row_mask:0xf bank_mask:0xf bound_ctrl:1
	s_nop 0
	v_mov_b32_dpp v68, v64 row_half_mirror row_mask:0xf bank_mask:0xf bound_ctrl:1
	v_mov_b32_dpp v69, v67 quad_perm:[3,2,1,0] row_mask:0xf bank_mask:0xf bound_ctrl:1
	v_med3_i32 v61, v61, v69, v121
	v_mov_b32_dpp v67, v68 quad_perm:[3,2,1,0] row_mask:0xf bank_mask:0xf bound_ctrl:1
	v_med3_i32 v64, v64, v67, v122
	v_mov_b32_dpp v67, v61 quad_perm:[2,3,0,1] row_mask:0xf bank_mask:0xf bound_ctrl:1
	v_med3_i32 v61, v61, v67, v123
	v_mov_b32_dpp v67, v64 quad_perm:[2,3,0,1] row_mask:0xf bank_mask:0xf bound_ctrl:1
	v_med3_i32 v64, v64, v67, v124
	v_mov_b32_dpp v67, v61 quad_perm:[1,0,3,2] row_mask:0xf bank_mask:0xf bound_ctrl:1
	v_med3_i32 v61, v61, v67, v125
	v_mov_b32_dpp v67, v64 quad_perm:[1,0,3,2] row_mask:0xf bank_mask:0xf bound_ctrl:1
	v_med3_i32 v64, v64, v67, v126
	v_max_i32_e32 v61, v61, v64
	v_mov_b32_e32 v64, v61
	v_mov_b32_e32 v67, v61
	s_nop 1
	v_permlane32_swap_b32_e32 v64, v67
	v_cndmask_b32_e64 v64, v64, v67, s[8:9]
	v_med3_i32 v61, v61, v64, v127
	v_mov_b32_e32 v64, v61
	v_mov_b32_e32 v67, v61
	s_nop 1
	v_permlane16_swap_b32_e32 v64, v67
	v_cndmask_b32_e64 v64, v64, v67, s[6:7]
	v_med3_i32 v61, v61, v64, v117
	s_nop 1
	v_mov_b32_dpp v64, v61 row_ror:8 row_mask:0xf bank_mask:0xf bound_ctrl:1
	v_med3_i32 v61, v61, v64, v119
	s_nop 1
	v_mov_b32_dpp v64, v61 row_half_mirror row_mask:0xf bank_mask:0xf bound_ctrl:1
	s_nop 1
	v_mov_b32_dpp v67, v64 quad_perm:[3,2,1,0] row_mask:0xf bank_mask:0xf bound_ctrl:1
	v_med3_i32 v61, v61, v67, v121
	s_nop 1
	v_mov_b32_dpp v64, v61 quad_perm:[2,3,0,1] row_mask:0xf bank_mask:0xf bound_ctrl:1
	v_med3_i32 v61, v61, v64, v123
	s_nop 1
	v_mov_b32_dpp v64, v61 quad_perm:[1,0,3,2] row_mask:0xf bank_mask:0xf bound_ctrl:1
	v_med3_i32 v61, v61, v64, v125
	v_max_i32_dpp v64, v65, v65 quad_perm:[1,0,3,2] row_mask:0xf bank_mask:0xf bound_ctrl:1
	v_min_i32_dpp v65, v65, v65 quad_perm:[1,0,3,2] row_mask:0xf bank_mask:0xf bound_ctrl:1
	v_cndmask_b32_e64 v64, v65, v64, s[12:13]
	s_nop 0
	v_max_i32_dpp v65, v66, v66 quad_perm:[1,0,3,2] row_mask:0xf bank_mask:0xf bound_ctrl:1
	v_min_i32_dpp v66, v66, v66 quad_perm:[1,0,3,2] row_mask:0xf bank_mask:0xf bound_ctrl:1
	v_cndmask_b32_e64 v65, v66, v65, s[12:13]
	s_nop 0
	v_mov_b32_dpp v66, v64 quad_perm:[2,3,0,1] row_mask:0xf bank_mask:0xf bound_ctrl:1
	v_med3_i32 v64, v64, v66, v101
	v_mov_b32_dpp v66, v65 quad_perm:[2,3,0,1] row_mask:0xf bank_mask:0xf bound_ctrl:1
	v_med3_i32 v65, v65, v66, v101
	v_mov_b32_dpp v66, v64 quad_perm:[1,0,3,2] row_mask:0xf bank_mask:0xf bound_ctrl:1
	v_med3_i32 v64, v64, v66, v102
	v_mov_b32_dpp v66, v65 quad_perm:[1,0,3,2] row_mask:0xf bank_mask:0xf bound_ctrl:1
	v_med3_i32 v65, v65, v66, v102
	v_mov_b32_dpp v66, v64 row_half_mirror row_mask:0xf bank_mask:0xf bound_ctrl:1
	s_nop 0
	v_mov_b32_dpp v67, v65 row_half_mirror row_mask:0xf bank_mask:0xf bound_ctrl:1
	v_mov_b32_dpp v68, v66 quad_perm:[3,2,1,0] row_mask:0xf bank_mask:0xf bound_ctrl:1
	v_med3_i32 v64, v64, v68, v103
	v_mov_b32_dpp v66, v67 quad_perm:[3,2,1,0] row_mask:0xf bank_mask:0xf bound_ctrl:1
	v_med3_i32 v65, v65, v66, v103
	v_mov_b32_dpp v66, v64 quad_perm:[2,3,0,1] row_mask:0xf bank_mask:0xf bound_ctrl:1
	v_med3_i32 v64, v64, v66, v104
	v_mov_b32_dpp v66, v65 quad_perm:[2,3,0,1] row_mask:0xf bank_mask:0xf bound_ctrl:1
	v_med3_i32 v65, v65, v66, v104
	v_mov_b32_dpp v66, v64 quad_perm:[1,0,3,2] row_mask:0xf bank_mask:0xf bound_ctrl:1
	v_med3_i32 v64, v64, v66, v105
	v_mov_b32_dpp v66, v65 quad_perm:[1,0,3,2] row_mask:0xf bank_mask:0xf bound_ctrl:1
	v_med3_i32 v65, v65, v66, v105
	v_mov_b32_dpp v66, v64 row_ror:8 row_mask:0xf bank_mask:0xf bound_ctrl:1
	v_med3_i32 v64, v64, v66, v106
	v_mov_b32_dpp v66, v65 row_ror:8 row_mask:0xf bank_mask:0xf bound_ctrl:1
	v_med3_i32 v65, v65, v66, v106
	v_mov_b32_dpp v66, v64 row_half_mirror row_mask:0xf bank_mask:0xf bound_ctrl:1
	s_nop 0
	v_mov_b32_dpp v67, v65 row_half_mirror row_mask:0xf bank_mask:0xf bound_ctrl:1
	v_mov_b32_dpp v68, v66 quad_perm:[3,2,1,0] row_mask:0xf bank_mask:0xf bound_ctrl:1
	v_med3_i32 v64, v64, v68, v107
	v_mov_b32_dpp v66, v67 quad_perm:[3,2,1,0] row_mask:0xf bank_mask:0xf bound_ctrl:1
	v_med3_i32 v65, v65, v66, v107
	v_mov_b32_dpp v66, v64 quad_perm:[2,3,0,1] row_mask:0xf bank_mask:0xf bound_ctrl:1
	v_med3_i32 v64, v64, v66, v108
	v_mov_b32_dpp v66, v65 quad_perm:[2,3,0,1] row_mask:0xf bank_mask:0xf bound_ctrl:1
	v_med3_i32 v65, v65, v66, v108
	v_mov_b32_dpp v66, v64 quad_perm:[1,0,3,2] row_mask:0xf bank_mask:0xf bound_ctrl:1
	v_med3_i32 v64, v64, v66, v109
	v_mov_b32_dpp v66, v65 quad_perm:[1,0,3,2] row_mask:0xf bank_mask:0xf bound_ctrl:1
	v_med3_i32 v65, v65, v66, v109
	v_mov_b32_e32 v66, v64
	v_mov_b32_e32 v67, v64
	s_nop 1
	v_permlane16_swap_b32_e32 v66, v67
	v_cndmask_b32_e64 v66, v66, v67, s[6:7]
	v_mov_b32_e32 v67, v65
	v_mov_b32_e32 v68, v65
	s_nop 1
	v_permlane16_swap_b32_e32 v67, v68
	v_cndmask_b32_e64 v67, v67, v68, s[6:7]
	v_med3_i32 v64, v64, v66, v110
	v_med3_i32 v65, v65, v67, v110
	s_nop 0
	v_mov_b32_dpp v66, v64 row_ror:8 row_mask:0xf bank_mask:0xf bound_ctrl:1
	v_med3_i32 v64, v64, v66, v111
	v_mov_b32_dpp v66, v65 row_ror:8 row_mask:0xf bank_mask:0xf bound_ctrl:1
	v_med3_i32 v65, v65, v66, v111
	v_mov_b32_dpp v66, v64 row_half_mirror row_mask:0xf bank_mask:0xf bound_ctrl:1
	s_nop 0
	v_mov_b32_dpp v67, v65 row_half_mirror row_mask:0xf bank_mask:0xf bound_ctrl:1
	v_mov_b32_dpp v68, v66 quad_perm:[3,2,1,0] row_mask:0xf bank_mask:0xf bound_ctrl:1
	v_med3_i32 v64, v64, v68, v112
	v_mov_b32_dpp v66, v67 quad_perm:[3,2,1,0] row_mask:0xf bank_mask:0xf bound_ctrl:1
	v_med3_i32 v65, v65, v66, v112
	v_mov_b32_dpp v66, v64 quad_perm:[2,3,0,1] row_mask:0xf bank_mask:0xf bound_ctrl:1
	v_med3_i32 v64, v64, v66, v113
	v_mov_b32_dpp v66, v65 quad_perm:[2,3,0,1] row_mask:0xf bank_mask:0xf bound_ctrl:1
	v_med3_i32 v65, v65, v66, v113
	v_mov_b32_dpp v66, v64 quad_perm:[1,0,3,2] row_mask:0xf bank_mask:0xf bound_ctrl:1
	v_med3_i32 v64, v64, v66, v114
	v_mov_b32_dpp v66, v65 quad_perm:[1,0,3,2] row_mask:0xf bank_mask:0xf bound_ctrl:1
	v_med3_i32 v65, v65, v66, v114
	v_mov_b32_e32 v66, v64
	v_mov_b32_e32 v67, v64
	s_nop 1
	v_permlane32_swap_b32_e32 v66, v67
	v_cndmask_b32_e64 v66, v66, v67, s[8:9]
	v_mov_b32_e32 v67, v65
	v_mov_b32_e32 v68, v65
	s_nop 1
	v_permlane32_swap_b32_e32 v67, v68
	v_cndmask_b32_e64 v67, v67, v68, s[8:9]
	v_med3_i32 v64, v64, v66, v115
	v_med3_i32 v65, v65, v67, v116
	v_mov_b32_e32 v66, v64
	v_mov_b32_e32 v67, v64
	s_nop 1
	v_permlane16_swap_b32_e32 v66, v67
	v_cndmask_b32_e64 v66, v66, v67, s[6:7]
	v_mov_b32_e32 v67, v65
	v_mov_b32_e32 v68, v65
	s_nop 1
	v_permlane16_swap_b32_e32 v67, v68
	v_cndmask_b32_e64 v67, v67, v68, s[6:7]
	v_med3_i32 v64, v64, v66, v117
	v_med3_i32 v65, v65, v67, v118
	s_nop 0
	v_mov_b32_dpp v66, v64 row_ror:8 row_mask:0xf bank_mask:0xf bound_ctrl:1
	v_med3_i32 v64, v64, v66, v119
	v_mov_b32_dpp v66, v65 row_ror:8 row_mask:0xf bank_mask:0xf bound_ctrl:1
	v_med3_i32 v65, v65, v66, v120
	v_mov_b32_dpp v66, v64 row_half_mirror row_mask:0xf bank_mask:0xf bound_ctrl:1
	s_nop 0
	v_mov_b32_dpp v67, v65 row_half_mirror row_mask:0xf bank_mask:0xf bound_ctrl:1
	v_mov_b32_dpp v68, v66 quad_perm:[3,2,1,0] row_mask:0xf bank_mask:0xf bound_ctrl:1
	v_med3_i32 v64, v64, v68, v121
	v_mov_b32_dpp v66, v67 quad_perm:[3,2,1,0] row_mask:0xf bank_mask:0xf bound_ctrl:1
	v_med3_i32 v65, v65, v66, v122
	v_mov_b32_dpp v66, v64 quad_perm:[2,3,0,1] row_mask:0xf bank_mask:0xf bound_ctrl:1
	v_med3_i32 v64, v64, v66, v123
	v_mov_b32_dpp v66, v65 quad_perm:[2,3,0,1] row_mask:0xf bank_mask:0xf bound_ctrl:1
	v_med3_i32 v65, v65, v66, v124
	v_mov_b32_dpp v66, v64 quad_perm:[1,0,3,2] row_mask:0xf bank_mask:0xf bound_ctrl:1
	v_med3_i32 v64, v64, v66, v125
	v_mov_b32_dpp v66, v65 quad_perm:[1,0,3,2] row_mask:0xf bank_mask:0xf bound_ctrl:1
	v_med3_i32 v65, v65, v66, v126
	v_max_i32_e32 v64, v64, v65
	v_mov_b32_e32 v65, v64
	v_mov_b32_e32 v66, v64
	s_nop 1
	v_permlane32_swap_b32_e32 v65, v66
	v_cndmask_b32_e64 v65, v65, v66, s[8:9]
	v_med3_i32 v64, v64, v65, v127
	v_mov_b32_e32 v65, v64
	v_mov_b32_e32 v66, v64
	s_nop 1
	v_permlane16_swap_b32_e32 v65, v66
	v_cndmask_b32_e64 v65, v65, v66, s[6:7]
	v_med3_i32 v64, v64, v65, v117
	s_nop 1
	v_mov_b32_dpp v65, v64 row_ror:8 row_mask:0xf bank_mask:0xf bound_ctrl:1
	v_med3_i32 v64, v64, v65, v119
	s_nop 1
	v_mov_b32_dpp v65, v64 row_half_mirror row_mask:0xf bank_mask:0xf bound_ctrl:1
	s_nop 1
	v_mov_b32_dpp v66, v65 quad_perm:[3,2,1,0] row_mask:0xf bank_mask:0xf bound_ctrl:1
	v_med3_i32 v64, v64, v66, v121
	s_nop 1
	v_mov_b32_dpp v65, v64 quad_perm:[2,3,0,1] row_mask:0xf bank_mask:0xf bound_ctrl:1
	v_med3_i32 v64, v64, v65, v123
	s_nop 1
	v_mov_b32_dpp v65, v64 quad_perm:[1,0,3,2] row_mask:0xf bank_mask:0xf bound_ctrl:1
	v_med3_i32 v64, v64, v65, v125
	v_bitop3_b32 v65, v61, s78, v61 bitop3:0xc
	v_bitop3_b32 v61, v61, v166, 63 bitop3:0xce
	v_lshlrev_b32_e32 v61, 2, v61
	ds_bpermute_b32 v59, v61, v59
	ds_bpermute_b32 v61, v61, v62
	v_bitop3_b32 v62, v64, v166, 63 bitop3:0xce
	v_lshlrev_b32_e32 v62, 2, v62
	ds_bpermute_b32 v63, v62, v63
	ds_bpermute_b32 v60, v62, v60
	v_bitop3_b32 v62, v64, s78, v64 bitop3:0xc
	v_cmp_gt_u32_e32 vcc, 64, v65
	s_waitcnt lgkmcnt(2)
	s_nop 0
	v_cndmask_b32_e32 v59, v61, v59, vcc
	v_cmp_gt_u32_e32 vcc, 64, v62
	ds_bpermute_b32 v59, v167, v59
	ds_bpermute_b32 v62, v168, v62
	s_waitcnt lgkmcnt(2)
	v_cndmask_b32_e32 v60, v60, v63, vcc
	ds_bpermute_b32 v60, v168, v60
	s_waitcnt lgkmcnt(0)
	v_add_f32_e32 v59, v59, v60
	v_ashrrev_i32_e32 v60, 31, v59
	v_and_b32_e32 v60, 0x7fffffc0, v60
	v_and_b32_e32 v61, 0xffffffc0, v59
	v_bitop3_b32 v60, v60, v165, v61 bitop3:0xde
	v_cndmask_b32_e64 v60, v60, v173, s[4:5]
	s_nop 1
	v_mov_b32_dpp v61, v60 quad_perm:[1,0,3,2] row_mask:0xf bank_mask:0xf bound_ctrl:1
	v_med3_i32 v60, v60, v61, v100
	s_nop 1
	v_mov_b32_dpp v61, v60 quad_perm:[2,3,0,1] row_mask:0xf bank_mask:0xf bound_ctrl:1
	v_med3_i32 v60, v60, v61, v101
	s_nop 1
	v_mov_b32_dpp v61, v60 quad_perm:[1,0,3,2] row_mask:0xf bank_mask:0xf bound_ctrl:1
	v_med3_i32 v60, v60, v61, v102
	s_nop 1
	v_mov_b32_dpp v61, v60 row_half_mirror row_mask:0xf bank_mask:0xf bound_ctrl:1
	s_nop 1
	v_mov_b32_dpp v63, v61 quad_perm:[3,2,1,0] row_mask:0xf bank_mask:0xf bound_ctrl:1
	v_med3_i32 v60, v60, v63, v103
	s_nop 1
	v_mov_b32_dpp v61, v60 quad_perm:[2,3,0,1] row_mask:0xf bank_mask:0xf bound_ctrl:1
	v_med3_i32 v60, v60, v61, v104
	s_nop 1
	v_mov_b32_dpp v61, v60 quad_perm:[1,0,3,2] row_mask:0xf bank_mask:0xf bound_ctrl:1
	v_med3_i32 v60, v60, v61, v105
	s_nop 1
	v_mov_b32_dpp v61, v60 row_ror:8 row_mask:0xf bank_mask:0xf bound_ctrl:1
	v_med3_i32 v60, v60, v61, v106
	s_nop 1
	v_mov_b32_dpp v61, v60 row_half_mirror row_mask:0xf bank_mask:0xf bound_ctrl:1
	s_nop 1
	v_mov_b32_dpp v63, v61 quad_perm:[3,2,1,0] row_mask:0xf bank_mask:0xf bound_ctrl:1
	v_med3_i32 v60, v60, v63, v107
	s_nop 1
	v_mov_b32_dpp v61, v60 quad_perm:[2,3,0,1] row_mask:0xf bank_mask:0xf bound_ctrl:1
	v_med3_i32 v60, v60, v61, v108
	s_nop 1
	v_mov_b32_dpp v61, v60 quad_perm:[1,0,3,2] row_mask:0xf bank_mask:0xf bound_ctrl:1
	v_med3_i32 v60, v60, v61, v109
	v_mov_b32_e32 v61, v60
	v_mov_b32_e32 v63, v60
	s_nop 1
	v_permlane16_swap_b32_e32 v61, v63
	v_cndmask_b32_e64 v61, v61, v63, s[6:7]
	v_med3_i32 v60, v60, v61, v110
	s_nop 1
	v_mov_b32_dpp v61, v60 row_ror:8 row_mask:0xf bank_mask:0xf bound_ctrl:1
	v_med3_i32 v60, v60, v61, v111
	s_nop 1
	v_mov_b32_dpp v61, v60 row_half_mirror row_mask:0xf bank_mask:0xf bound_ctrl:1
	s_nop 1
	v_mov_b32_dpp v63, v61 quad_perm:[3,2,1,0] row_mask:0xf bank_mask:0xf bound_ctrl:1
	v_med3_i32 v60, v60, v63, v112
	s_nop 1
	v_mov_b32_dpp v61, v60 quad_perm:[2,3,0,1] row_mask:0xf bank_mask:0xf bound_ctrl:1
	v_med3_i32 v60, v60, v61, v113
	s_nop 1
	v_mov_b32_dpp v61, v60 quad_perm:[1,0,3,2] row_mask:0xf bank_mask:0xf bound_ctrl:1
	v_med3_i32 v60, v60, v61, v114
	v_mov_b32_e32 v61, v60
	v_mov_b32_e32 v63, v60
	s_nop 1
	v_permlane32_swap_b32_e32 v61, v63
	v_cndmask_b32_e64 v61, v61, v63, s[8:9]
	v_med3_i32 v60, v60, v61, v127
	v_mov_b32_e32 v61, v60
	v_mov_b32_e32 v63, v60
	s_nop 1
	v_permlane16_swap_b32_e32 v61, v63
	v_cndmask_b32_e64 v61, v61, v63, s[6:7]
	v_med3_i32 v60, v60, v61, v117
	s_nop 1
	v_mov_b32_dpp v61, v60 row_ror:8 row_mask:0xf bank_mask:0xf bound_ctrl:1
	v_med3_i32 v60, v60, v61, v119
	s_nop 1
	v_mov_b32_dpp v61, v60 row_half_mirror row_mask:0xf bank_mask:0xf bound_ctrl:1
	s_nop 1
	v_mov_b32_dpp v63, v61 quad_perm:[3,2,1,0] row_mask:0xf bank_mask:0xf bound_ctrl:1
	v_med3_i32 v60, v60, v63, v121
	s_nop 1
	v_mov_b32_dpp v61, v60 quad_perm:[2,3,0,1] row_mask:0xf bank_mask:0xf bound_ctrl:1
	v_med3_i32 v60, v60, v61, v123
	s_nop 1
	v_mov_b32_dpp v61, v60 quad_perm:[1,0,3,2] row_mask:0xf bank_mask:0xf bound_ctrl:1
	v_med3_i32 v60, v60, v61, v125
	v_and_or_b32 v60, v60, 63, v166
	v_lshlrev_b32_e32 v60, 2, v60
	v_xor_b32_e32 v60, 0xfc, v60
	ds_bpermute_b32 v59, v60, v59
	ds_bpermute_b32 v61, v167, v65
	s_waitcnt lgkmcnt(1)
	v_readlane_b32 s33, v59, 0
	s_nop 1
	v_subrev_f32_e32 v59, s33, v59
	v_mul_f32_e32 v59, v24, v59
	v_mul_f32_e32 v59, 0x3fb8aa3b, v59
	v_exp_f32_e32 v59, v59
	s_waitcnt lgkmcnt(0)
	v_lshl_add_u32 v61, v61, 7, v62
	ds_bpermute_b32 v60, v60, v61
	v_cndmask_b32_e64 v61, 0, v59, s[54:55]
	s_nop 1
	v_add_f32_dpp v61, v61, v61 row_ror:8 row_mask:0xf bank_mask:0xf bound_ctrl:1
	s_nop 1
	v_mov_b32_dpp v62, v61 row_half_mirror row_mask:0xf bank_mask:0xf bound_ctrl:1
	s_nop 1
	v_add_f32_dpp v61, v62, v61 quad_perm:[3,2,1,0] row_mask:0xf bank_mask:0xf bound_ctrl:1
	s_nop 1
	v_add_f32_dpp v61, v61, v61 quad_perm:[2,3,0,1] row_mask:0xf bank_mask:0xf bound_ctrl:1
	s_nop 1
	v_mov_b32_dpp v62, v61 quad_perm:[1,0,3,2] row_mask:0xf bank_mask:0xf bound_ctrl:1
	s_and_saveexec_b64 s[66:67], s[54:55]
	s_cbranch_execz .LBB0_924
	v_add_f32_e32 v61, v61, v62
	v_div_scale_f32 v62, s[68:69], v61, v61, v59
	v_rcp_f32_e32 v63, v62
	v_div_scale_f32 v64, vcc, v59, v61, v59
	v_fma_f32 v65, -v62, v63, 1.0
	v_fmac_f32_e32 v63, v65, v63
	v_mul_f32_e32 v65, v64, v63
	v_fma_f32 v66, -v62, v65, v64
	v_fmac_f32_e32 v65, v66, v63
	v_fma_f32 v62, -v62, v65, v64
	v_div_fmas_f32 v62, v62, v63, v65
	v_div_fixup_f32 v59, v62, v61, v59
	s_waitcnt lgkmcnt(0)
	ds_write2st64_b32 v28, v60, v59 offset1:2
.LBB0_924:
	s_or_b64 exec, exec, s[66:67]
	v_add_co_u32_e32 v2, vcc, 0x8008000, v2
	s_nop 1
	v_addc_co_u32_e32 v3, vcc, 0, v3, vcc
	global_load_dword v59, v[2:3], off offset:1024
	s_waitcnt lgkmcnt(0)
	global_load_dword v60, v[2:3], off offset:1280
	global_load_dword v61, v[2:3], off offset:1536
	s_nop 0
	global_load_dword v2, v[2:3], off offset:1792
	s_waitcnt vmcnt(3)
	v_ashrrev_i32_e32 v3, 31, v59
	v_and_b32_e32 v62, 0xffffff80, v59
	s_waitcnt vmcnt(2)
	v_ashrrev_i32_e32 v63, 31, v60
	s_waitcnt vmcnt(1)
	v_ashrrev_i32_e32 v65, 31, v61
	v_and_b32_e32 v3, 0x7fffff80, v3
	v_and_b32_e32 v64, 0xffffff80, v60
	v_and_b32_e32 v66, 0xffffff80, v61
	v_and_b32_e32 v63, 0x7fffff80, v63
	v_and_b32_e32 v65, 0x7fffff80, v65
	v_bitop3_b32 v3, v3, v164, v62 bitop3:0xde
	v_bitop3_b32 v62, v63, v165, v64 bitop3:0xde
	v_bitop3_b32 v63, v65, v164, v66 bitop3:0xde
	v_mov_b32_dpp v65, v3 quad_perm:[1,0,3,2] row_mask:0xf bank_mask:0xf bound_ctrl:1
	v_mov_b32_dpp v66, v62 quad_perm:[1,0,3,2] row_mask:0xf bank_mask:0xf bound_ctrl:1
	v_med3_i32 v3, v3, v65, v100
	v_med3_i32 v62, v62, v66, v100
	s_waitcnt vmcnt(0)
	v_ashrrev_i32_e32 v67, 31, v2
	v_mov_b32_dpp v65, v3 quad_perm:[2,3,0,1] row_mask:0xf bank_mask:0xf bound_ctrl:1
	v_mov_b32_dpp v66, v62 quad_perm:[2,3,0,1] row_mask:0xf bank_mask:0xf bound_ctrl:1
	v_med3_i32 v3, v3, v65, v101
	v_med3_i32 v62, v62, v66, v101
	v_and_b32_e32 v68, 0xffffff80, v2
	v_mov_b32_dpp v65, v3 quad_perm:[1,0,3,2] row_mask:0xf bank_mask:0xf bound_ctrl:1
	v_mov_b32_dpp v66, v62 quad_perm:[1,0,3,2] row_mask:0xf bank_mask:0xf bound_ctrl:1
	v_med3_i32 v3, v3, v65, v102
	v_and_b32_e32 v67, 0x7fffff80, v67
	v_med3_i32 v62, v62, v66, v102
	v_mov_b32_dpp v65, v3 row_half_mirror row_mask:0xf bank_mask:0xf bound_ctrl:1
	v_bitop3_b32 v64, v67, v165, v68 bitop3:0xde
	v_mov_b32_dpp v66, v62 row_half_mirror row_mask:0xf bank_mask:0xf bound_ctrl:1
	v_mov_b32_dpp v67, v65 quad_perm:[3,2,1,0] row_mask:0xf bank_mask:0xf bound_ctrl:1
	s_nop 0
	v_mov_b32_dpp v65, v66 quad_perm:[3,2,1,0] row_mask:0xf bank_mask:0xf bound_ctrl:1
	v_med3_i32 v3, v3, v67, v103
	v_med3_i32 v62, v62, v65, v103
	s_nop 0
	v_mov_b32_dpp v65, v3 quad_perm:[2,3,0,1] row_mask:0xf bank_mask:0xf bound_ctrl:1
	v_mov_b32_dpp v66, v62 quad_perm:[2,3,0,1] row_mask:0xf bank_mask:0xf bound_ctrl:1
	v_med3_i32 v3, v3, v65, v104
	v_med3_i32 v62, v62, v66, v104
	s_nop 0
	v_mov_b32_dpp v65, v3 quad_perm:[1,0,3,2] row_mask:0xf bank_mask:0xf bound_ctrl:1
	v_mov_b32_dpp v66, v62 quad_perm:[1,0,3,2] row_mask:0xf bank_mask:0xf bound_ctrl:1
	v_med3_i32 v3, v3, v65, v105
	v_med3_i32 v62, v62, v66, v105
	s_nop 0
	v_mov_b32_dpp v65, v3 row_ror:8 row_mask:0xf bank_mask:0xf bound_ctrl:1
	v_mov_b32_dpp v66, v62 row_ror:8 row_mask:0xf bank_mask:0xf bound_ctrl:1
	v_med3_i32 v3, v3, v65, v106
	v_med3_i32 v62, v62, v66, v106
	s_nop 0
	v_mov_b32_dpp v65, v3 row_half_mirror row_mask:0xf bank_mask:0xf bound_ctrl:1
	v_mov_b32_dpp v66, v62 row_half_mirror row_mask:0xf bank_mask:0xf bound_ctrl:1
	s_nop 0
	v_mov_b32_dpp v67, v65 quad_perm:[3,2,1,0] row_mask:0xf bank_mask:0xf bound_ctrl:1
	v_mov_b32_dpp v65, v66 quad_perm:[3,2,1,0] row_mask:0xf bank_mask:0xf bound_ctrl:1
	v_med3_i32 v3, v3, v67, v107
	v_med3_i32 v62, v62, v65, v107
	s_nop 0
	v_mov_b32_dpp v65, v3 quad_perm:[2,3,0,1] row_mask:0xf bank_mask:0xf bound_ctrl:1
	v_mov_b32_dpp v66, v62 quad_perm:[2,3,0,1] row_mask:0xf bank_mask:0xf bound_ctrl:1
	v_med3_i32 v3, v3, v65, v108
	v_med3_i32 v62, v62, v66, v108
	s_nop 0
	v_mov_b32_dpp v65, v3 quad_perm:[1,0,3,2] row_mask:0xf bank_mask:0xf bound_ctrl:1
	v_mov_b32_dpp v66, v62 quad_perm:[1,0,3,2] row_mask:0xf bank_mask:0xf bound_ctrl:1
	v_med3_i32 v3, v3, v65, v109
	v_med3_i32 v62, v62, v66, v109
	v_mov_b32_e32 v65, v3
	v_mov_b32_e32 v66, v3
	v_mov_b32_e32 v67, v62
	v_mov_b32_e32 v68, v62
	v_permlane16_swap_b32_e32 v65, v66
	s_nop 0
	v_permlane16_swap_b32_e32 v67, v68
	v_cndmask_b32_e64 v65, v65, v66, s[6:7]
	v_cndmask_b32_e64 v66, v67, v68, s[6:7]
	v_max_i32_e32 v67, v3, v65
	v_min_i32_e32 v3, v3, v65
	v_cndmask_b32_e64 v3, v3, v67, s[42:43]
	v_med3_i32 v62, v62, v66, v110
	s_nop 0
	v_mov_b32_dpp v65, v3 row_ror:8 row_mask:0xf bank_mask:0xf bound_ctrl:1
	v_mov_b32_dpp v66, v62 row_ror:8 row_mask:0xf bank_mask:0xf bound_ctrl:1
	v_med3_i32 v3, v3, v65, v111
	v_med3_i32 v62, v62, v66, v111
	s_nop 0
	v_mov_b32_dpp v65, v3 row_half_mirror row_mask:0xf bank_mask:0xf bound_ctrl:1
	v_mov_b32_dpp v66, v62 row_half_mirror row_mask:0xf bank_mask:0xf bound_ctrl:1
	s_nop 0
	v_mov_b32_dpp v67, v65 quad_perm:[3,2,1,0] row_mask:0xf bank_mask:0xf bound_ctrl:1
	v_mov_b32_dpp v65, v66 quad_perm:[3,2,1,0] row_mask:0xf bank_mask:0xf bound_ctrl:1
	v_med3_i32 v3, v3, v67, v112
	v_med3_i32 v62, v62, v65, v112
	s_nop 0
	v_mov_b32_dpp v65, v3 quad_perm:[2,3,0,1] row_mask:0xf bank_mask:0xf bound_ctrl:1
	v_med3_i32 v3, v3, v65, v113
	v_mov_b32_dpp v65, v62 quad_perm:[2,3,0,1] row_mask:0xf bank_mask:0xf bound_ctrl:1
	v_med3_i32 v62, v62, v65, v113
	v_mov_b32_dpp v65, v3 quad_perm:[1,0,3,2] row_mask:0xf bank_mask:0xf bound_ctrl:1
	v_med3_i32 v3, v3, v65, v114
	v_mov_b32_dpp v65, v62 quad_perm:[1,0,3,2] row_mask:0xf bank_mask:0xf bound_ctrl:1
	v_med3_i32 v62, v62, v65, v114
	v_mov_b32_e32 v65, v3
	v_mov_b32_e32 v66, v3
	s_nop 1
	v_permlane32_swap_b32_e32 v65, v66
	v_cndmask_b32_e64 v65, v65, v66, s[8:9]
	v_mov_b32_e32 v66, v62
	v_mov_b32_e32 v67, v62
	s_nop 1
	v_permlane32_swap_b32_e32 v66, v67
	v_cndmask_b32_e64 v66, v66, v67, s[8:9]
	v_med3_i32 v3, v3, v65, v115
	v_med3_i32 v62, v62, v66, v116
	v_mov_b32_e32 v65, v3
	v_mov_b32_e32 v66, v3
	s_nop 1
	v_permlane16_swap_b32_e32 v65, v66
	v_cndmask_b32_e64 v65, v65, v66, s[6:7]
	v_mov_b32_e32 v66, v62
	v_mov_b32_e32 v67, v62
	s_nop 1
	v_permlane16_swap_b32_e32 v66, v67
	v_cndmask_b32_e64 v66, v66, v67, s[6:7]
	v_med3_i32 v3, v3, v65, v117
	v_med3_i32 v62, v62, v66, v118
	s_nop 0
	v_mov_b32_dpp v65, v3 row_ror:8 row_mask:0xf bank_mask:0xf bound_ctrl:1
	v_med3_i32 v3, v3, v65, v119
	v_mov_b32_dpp v65, v62 row_ror:8 row_mask:0xf bank_mask:0xf bound_ctrl:1
	v_med3_i32 v62, v62, v65, v120
	v_mov_b32_dpp v65, v3 row_half_mirror row_mask:0xf bank_mask:0xf bound_ctrl:1
	s_nop 0
	v_mov_b32_dpp v66, v62 row_half_mirror row_mask:0xf bank_mask:0xf bound_ctrl:1
	v_mov_b32_dpp v67, v65 quad_perm:[3,2,1,0] row_mask:0xf bank_mask:0xf bound_ctrl:1
	v_med3_i32 v3, v3, v67, v121
	v_mov_b32_dpp v65, v66 quad_perm:[3,2,1,0] row_mask:0xf bank_mask:0xf bound_ctrl:1
	v_med3_i32 v62, v62, v65, v122
	v_mov_b32_dpp v65, v3 quad_perm:[2,3,0,1] row_mask:0xf bank_mask:0xf bound_ctrl:1
	v_med3_i32 v3, v3, v65, v123
	v_mov_b32_dpp v65, v62 quad_perm:[2,3,0,1] row_mask:0xf bank_mask:0xf bound_ctrl:1
	v_med3_i32 v62, v62, v65, v124
	v_mov_b32_dpp v65, v3 quad_perm:[1,0,3,2] row_mask:0xf bank_mask:0xf bound_ctrl:1
	v_med3_i32 v3, v3, v65, v125
	v_mov_b32_dpp v65, v62 quad_perm:[1,0,3,2] row_mask:0xf bank_mask:0xf bound_ctrl:1
	v_med3_i32 v62, v62, v65, v126
	v_max_i32_e32 v3, v3, v62
	v_mov_b32_e32 v62, v3
	v_mov_b32_e32 v65, v3
	s_nop 1
	v_permlane32_swap_b32_e32 v62, v65
	v_cndmask_b32_e64 v62, v62, v65, s[8:9]
	v_med3_i32 v3, v3, v62, v127
	v_mov_b32_e32 v62, v3
	v_mov_b32_e32 v65, v3
	s_nop 1
	v_permlane16_swap_b32_e32 v62, v65
	v_cndmask_b32_e64 v62, v62, v65, s[6:7]
	v_med3_i32 v3, v3, v62, v117
	s_nop 1
	v_mov_b32_dpp v62, v3 row_ror:8 row_mask:0xf bank_mask:0xf bound_ctrl:1
	v_med3_i32 v3, v3, v62, v119
	s_nop 1
	v_mov_b32_dpp v62, v3 row_half_mirror row_mask:0xf bank_mask:0xf bound_ctrl:1
	s_nop 1
	v_mov_b32_dpp v65, v62 quad_perm:[3,2,1,0] row_mask:0xf bank_mask:0xf bound_ctrl:1
	v_med3_i32 v3, v3, v65, v121
	s_nop 1
	v_mov_b32_dpp v62, v3 quad_perm:[2,3,0,1] row_mask:0xf bank_mask:0xf bound_ctrl:1
	v_med3_i32 v3, v3, v62, v123
	s_nop 1
	v_mov_b32_dpp v62, v3 quad_perm:[1,0,3,2] row_mask:0xf bank_mask:0xf bound_ctrl:1
	v_med3_i32 v3, v3, v62, v125
	v_max_i32_dpp v62, v63, v63 quad_perm:[1,0,3,2] row_mask:0xf bank_mask:0xf bound_ctrl:1
	v_min_i32_dpp v63, v63, v63 quad_perm:[1,0,3,2] row_mask:0xf bank_mask:0xf bound_ctrl:1
	v_cndmask_b32_e64 v62, v63, v62, s[12:13]
	s_nop 0
	v_max_i32_dpp v63, v64, v64 quad_perm:[1,0,3,2] row_mask:0xf bank_mask:0xf bound_ctrl:1
	v_min_i32_dpp v64, v64, v64 quad_perm:[1,0,3,2] row_mask:0xf bank_mask:0xf bound_ctrl:1
	v_cndmask_b32_e64 v63, v64, v63, s[12:13]
	s_nop 0
	v_mov_b32_dpp v64, v62 quad_perm:[2,3,0,1] row_mask:0xf bank_mask:0xf bound_ctrl:1
	v_med3_i32 v62, v62, v64, v101
	v_mov_b32_dpp v64, v63 quad_perm:[2,3,0,1] row_mask:0xf bank_mask:0xf bound_ctrl:1
	v_med3_i32 v63, v63, v64, v101
	v_mov_b32_dpp v64, v62 quad_perm:[1,0,3,2] row_mask:0xf bank_mask:0xf bound_ctrl:1
	v_med3_i32 v62, v62, v64, v102
	v_mov_b32_dpp v64, v63 quad_perm:[1,0,3,2] row_mask:0xf bank_mask:0xf bound_ctrl:1
	v_med3_i32 v63, v63, v64, v102
	v_mov_b32_dpp v64, v62 row_half_mirror row_mask:0xf bank_mask:0xf bound_ctrl:1
	s_nop 0
	v_mov_b32_dpp v65, v63 row_half_mirror row_mask:0xf bank_mask:0xf bound_ctrl:1
	v_mov_b32_dpp v66, v64 quad_perm:[3,2,1,0] row_mask:0xf bank_mask:0xf bound_ctrl:1
	v_med3_i32 v62, v62, v66, v103
	v_mov_b32_dpp v64, v65 quad_perm:[3,2,1,0] row_mask:0xf bank_mask:0xf bound_ctrl:1
	v_med3_i32 v63, v63, v64, v103
	v_mov_b32_dpp v64, v62 quad_perm:[2,3,0,1] row_mask:0xf bank_mask:0xf bound_ctrl:1
	v_med3_i32 v62, v62, v64, v104
	v_mov_b32_dpp v64, v63 quad_perm:[2,3,0,1] row_mask:0xf bank_mask:0xf bound_ctrl:1
	v_med3_i32 v63, v63, v64, v104
	v_mov_b32_dpp v64, v62 quad_perm:[1,0,3,2] row_mask:0xf bank_mask:0xf bound_ctrl:1
	v_med3_i32 v62, v62, v64, v105
	v_mov_b32_dpp v64, v63 quad_perm:[1,0,3,2] row_mask:0xf bank_mask:0xf bound_ctrl:1
	v_med3_i32 v63, v63, v64, v105
	v_mov_b32_dpp v64, v62 row_ror:8 row_mask:0xf bank_mask:0xf bound_ctrl:1
	v_med3_i32 v62, v62, v64, v106
	v_mov_b32_dpp v64, v63 row_ror:8 row_mask:0xf bank_mask:0xf bound_ctrl:1
	v_med3_i32 v63, v63, v64, v106
	v_mov_b32_dpp v64, v62 row_half_mirror row_mask:0xf bank_mask:0xf bound_ctrl:1
	s_nop 0
	v_mov_b32_dpp v65, v63 row_half_mirror row_mask:0xf bank_mask:0xf bound_ctrl:1
	v_mov_b32_dpp v66, v64 quad_perm:[3,2,1,0] row_mask:0xf bank_mask:0xf bound_ctrl:1
	v_med3_i32 v62, v62, v66, v107
	v_mov_b32_dpp v64, v65 quad_perm:[3,2,1,0] row_mask:0xf bank_mask:0xf bound_ctrl:1
	v_med3_i32 v63, v63, v64, v107
	v_mov_b32_dpp v64, v62 quad_perm:[2,3,0,1] row_mask:0xf bank_mask:0xf bound_ctrl:1
	v_med3_i32 v62, v62, v64, v108
	v_mov_b32_dpp v64, v63 quad_perm:[2,3,0,1] row_mask:0xf bank_mask:0xf bound_ctrl:1
	v_med3_i32 v63, v63, v64, v108
	v_mov_b32_dpp v64, v62 quad_perm:[1,0,3,2] row_mask:0xf bank_mask:0xf bound_ctrl:1
	v_med3_i32 v62, v62, v64, v109
	v_mov_b32_dpp v64, v63 quad_perm:[1,0,3,2] row_mask:0xf bank_mask:0xf bound_ctrl:1
	v_med3_i32 v63, v63, v64, v109
	v_mov_b32_e32 v64, v62
	v_mov_b32_e32 v65, v62
	s_nop 1
	v_permlane16_swap_b32_e32 v64, v65
	v_cndmask_b32_e64 v64, v64, v65, s[6:7]
	v_mov_b32_e32 v65, v63
	v_mov_b32_e32 v66, v63
	s_nop 1
	v_permlane16_swap_b32_e32 v65, v66
	v_cndmask_b32_e64 v65, v65, v66, s[6:7]
	v_med3_i32 v62, v62, v64, v110
	v_med3_i32 v63, v63, v65, v110
	s_nop 0
	v_mov_b32_dpp v64, v62 row_ror:8 row_mask:0xf bank_mask:0xf bound_ctrl:1
	v_med3_i32 v62, v62, v64, v111
	v_mov_b32_dpp v64, v63 row_ror:8 row_mask:0xf bank_mask:0xf bound_ctrl:1
	v_med3_i32 v63, v63, v64, v111
	v_mov_b32_dpp v64, v62 row_half_mirror row_mask:0xf bank_mask:0xf bound_ctrl:1
	s_nop 0
	v_mov_b32_dpp v65, v63 row_half_mirror row_mask:0xf bank_mask:0xf bound_ctrl:1
	v_mov_b32_dpp v66, v64 quad_perm:[3,2,1,0] row_mask:0xf bank_mask:0xf bound_ctrl:1
	v_med3_i32 v62, v62, v66, v112
	v_mov_b32_dpp v64, v65 quad_perm:[3,2,1,0] row_mask:0xf bank_mask:0xf bound_ctrl:1
	v_med3_i32 v63, v63, v64, v112
	v_mov_b32_dpp v64, v62 quad_perm:[2,3,0,1] row_mask:0xf bank_mask:0xf bound_ctrl:1
	v_med3_i32 v62, v62, v64, v113
	v_mov_b32_dpp v64, v63 quad_perm:[2,3,0,1] row_mask:0xf bank_mask:0xf bound_ctrl:1
	v_med3_i32 v63, v63, v64, v113
	v_mov_b32_dpp v64, v62 quad_perm:[1,0,3,2] row_mask:0xf bank_mask:0xf bound_ctrl:1
	v_med3_i32 v62, v62, v64, v114
	v_mov_b32_dpp v64, v63 quad_perm:[1,0,3,2] row_mask:0xf bank_mask:0xf bound_ctrl:1
	v_med3_i32 v63, v63, v64, v114
	v_mov_b32_e32 v64, v62
	v_mov_b32_e32 v65, v62
	s_nop 1
	v_permlane32_swap_b32_e32 v64, v65
	v_cndmask_b32_e64 v64, v64, v65, s[8:9]
	v_mov_b32_e32 v65, v63
	v_mov_b32_e32 v66, v63
	s_nop 1
	v_permlane32_swap_b32_e32 v65, v66
	v_cndmask_b32_e64 v65, v65, v66, s[8:9]
	v_med3_i32 v62, v62, v64, v115
	v_med3_i32 v63, v63, v65, v116
	v_mov_b32_e32 v64, v62
	v_mov_b32_e32 v65, v62
	s_nop 1
	v_permlane16_swap_b32_e32 v64, v65
	v_cndmask_b32_e64 v64, v64, v65, s[6:7]
	v_mov_b32_e32 v65, v63
	v_mov_b32_e32 v66, v63
	s_nop 1
	v_permlane16_swap_b32_e32 v65, v66
	v_cndmask_b32_e64 v65, v65, v66, s[6:7]
	v_med3_i32 v62, v62, v64, v117
	v_med3_i32 v63, v63, v65, v118
	s_nop 0
	v_mov_b32_dpp v64, v62 row_ror:8 row_mask:0xf bank_mask:0xf bound_ctrl:1
	v_med3_i32 v62, v62, v64, v119
	v_mov_b32_dpp v64, v63 row_ror:8 row_mask:0xf bank_mask:0xf bound_ctrl:1
	v_med3_i32 v63, v63, v64, v120
	v_mov_b32_dpp v64, v62 row_half_mirror row_mask:0xf bank_mask:0xf bound_ctrl:1
	s_nop 0
	v_mov_b32_dpp v65, v63 row_half_mirror row_mask:0xf bank_mask:0xf bound_ctrl:1
	v_mov_b32_dpp v66, v64 quad_perm:[3,2,1,0] row_mask:0xf bank_mask:0xf bound_ctrl:1
	v_med3_i32 v62, v62, v66, v121
	v_mov_b32_dpp v64, v65 quad_perm:[3,2,1,0] row_mask:0xf bank_mask:0xf bound_ctrl:1
	v_med3_i32 v63, v63, v64, v122
	v_mov_b32_dpp v64, v62 quad_perm:[2,3,0,1] row_mask:0xf bank_mask:0xf bound_ctrl:1
	v_med3_i32 v62, v62, v64, v123
	v_mov_b32_dpp v64, v63 quad_perm:[2,3,0,1] row_mask:0xf bank_mask:0xf bound_ctrl:1
	v_med3_i32 v63, v63, v64, v124
	v_mov_b32_dpp v64, v62 quad_perm:[1,0,3,2] row_mask:0xf bank_mask:0xf bound_ctrl:1
	v_med3_i32 v62, v62, v64, v125
	v_mov_b32_dpp v64, v63 quad_perm:[1,0,3,2] row_mask:0xf bank_mask:0xf bound_ctrl:1
	v_med3_i32 v63, v63, v64, v126
	v_max_i32_e32 v62, v62, v63
	v_mov_b32_e32 v63, v62
	v_mov_b32_e32 v64, v62
	s_nop 1
	v_permlane32_swap_b32_e32 v63, v64
	v_cndmask_b32_e64 v63, v63, v64, s[8:9]
	v_med3_i32 v62, v62, v63, v127
	v_mov_b32_e32 v63, v62
	v_mov_b32_e32 v64, v62
	s_nop 1
	v_permlane16_swap_b32_e32 v63, v64
	v_cndmask_b32_e64 v63, v63, v64, s[6:7]
	v_med3_i32 v62, v62, v63, v117
	s_nop 1
	v_mov_b32_dpp v63, v62 row_ror:8 row_mask:0xf bank_mask:0xf bound_ctrl:1
	v_med3_i32 v62, v62, v63, v119
	s_nop 1
	v_mov_b32_dpp v63, v62 row_half_mirror row_mask:0xf bank_mask:0xf bound_ctrl:1
	s_nop 1
	v_mov_b32_dpp v64, v63 quad_perm:[3,2,1,0] row_mask:0xf bank_mask:0xf bound_ctrl:1
	v_med3_i32 v62, v62, v64, v121
	s_nop 1
	v_mov_b32_dpp v63, v62 quad_perm:[2,3,0,1] row_mask:0xf bank_mask:0xf bound_ctrl:1
	v_med3_i32 v62, v62, v63, v123
	s_nop 1
	v_mov_b32_dpp v63, v62 quad_perm:[1,0,3,2] row_mask:0xf bank_mask:0xf bound_ctrl:1
	v_med3_i32 v62, v62, v63, v125
	v_bitop3_b32 v63, v3, s78, v3 bitop3:0xc
	v_bitop3_b32 v3, v3, v166, 63 bitop3:0xce
	v_lshlrev_b32_e32 v3, 2, v3
	ds_bpermute_b32 v59, v3, v59
	ds_bpermute_b32 v3, v3, v60
	v_bitop3_b32 v60, v62, v166, 63 bitop3:0xce
	v_lshlrev_b32_e32 v60, 2, v60
	ds_bpermute_b32 v61, v60, v61
	ds_bpermute_b32 v2, v60, v2
	v_bitop3_b32 v60, v62, s78, v62 bitop3:0xc
	v_cmp_gt_u32_e32 vcc, 64, v63
	s_waitcnt lgkmcnt(2)
	s_nop 0
	v_cndmask_b32_e32 v3, v3, v59, vcc
	v_cmp_gt_u32_e32 vcc, 64, v60
	ds_bpermute_b32 v3, v167, v3
	ds_bpermute_b32 v60, v168, v60
	s_waitcnt lgkmcnt(2)
	v_cndmask_b32_e32 v2, v2, v61, vcc
	ds_bpermute_b32 v2, v168, v2
	s_waitcnt lgkmcnt(0)
	v_add_f32_e32 v2, v3, v2
	v_ashrrev_i32_e32 v3, 31, v2
	v_and_b32_e32 v3, 0x7fffffc0, v3
	v_and_b32_e32 v59, 0xffffffc0, v2
	v_bitop3_b32 v3, v3, v165, v59 bitop3:0xde
	v_cndmask_b32_e64 v3, v3, v173, s[4:5]
	s_nop 1
	v_mov_b32_dpp v59, v3 quad_perm:[1,0,3,2] row_mask:0xf bank_mask:0xf bound_ctrl:1
	v_med3_i32 v3, v3, v59, v100
	s_nop 1
	v_mov_b32_dpp v59, v3 quad_perm:[2,3,0,1] row_mask:0xf bank_mask:0xf bound_ctrl:1
	v_med3_i32 v3, v3, v59, v101
	s_nop 1
	v_mov_b32_dpp v59, v3 quad_perm:[1,0,3,2] row_mask:0xf bank_mask:0xf bound_ctrl:1
	v_med3_i32 v3, v3, v59, v102
	s_nop 1
	v_mov_b32_dpp v59, v3 row_half_mirror row_mask:0xf bank_mask:0xf bound_ctrl:1
	s_nop 1
	v_mov_b32_dpp v61, v59 quad_perm:[3,2,1,0] row_mask:0xf bank_mask:0xf bound_ctrl:1
	v_med3_i32 v3, v3, v61, v103
	s_nop 1
	v_mov_b32_dpp v59, v3 quad_perm:[2,3,0,1] row_mask:0xf bank_mask:0xf bound_ctrl:1
	v_med3_i32 v3, v3, v59, v104
	s_nop 1
	v_mov_b32_dpp v59, v3 quad_perm:[1,0,3,2] row_mask:0xf bank_mask:0xf bound_ctrl:1
	v_med3_i32 v3, v3, v59, v105
	s_nop 1
	v_mov_b32_dpp v59, v3 row_ror:8 row_mask:0xf bank_mask:0xf bound_ctrl:1
	v_med3_i32 v3, v3, v59, v106
	s_nop 1
	v_mov_b32_dpp v59, v3 row_half_mirror row_mask:0xf bank_mask:0xf bound_ctrl:1
	s_nop 1
	v_mov_b32_dpp v61, v59 quad_perm:[3,2,1,0] row_mask:0xf bank_mask:0xf bound_ctrl:1
	v_med3_i32 v3, v3, v61, v107
	s_nop 1
	v_mov_b32_dpp v59, v3 quad_perm:[2,3,0,1] row_mask:0xf bank_mask:0xf bound_ctrl:1
	v_med3_i32 v3, v3, v59, v108
	s_nop 1
	v_mov_b32_dpp v59, v3 quad_perm:[1,0,3,2] row_mask:0xf bank_mask:0xf bound_ctrl:1
	v_med3_i32 v3, v3, v59, v109
	v_mov_b32_e32 v59, v3
	v_mov_b32_e32 v61, v3
	s_nop 1
	v_permlane16_swap_b32_e32 v59, v61
	v_cndmask_b32_e64 v59, v59, v61, s[6:7]
	v_med3_i32 v3, v3, v59, v110
	s_nop 1
	v_mov_b32_dpp v59, v3 row_ror:8 row_mask:0xf bank_mask:0xf bound_ctrl:1
	v_med3_i32 v3, v3, v59, v111
	s_nop 1
	v_mov_b32_dpp v59, v3 row_half_mirror row_mask:0xf bank_mask:0xf bound_ctrl:1
	s_nop 1
	v_mov_b32_dpp v61, v59 quad_perm:[3,2,1,0] row_mask:0xf bank_mask:0xf bound_ctrl:1
	v_med3_i32 v3, v3, v61, v112
	s_nop 1
	v_mov_b32_dpp v59, v3 quad_perm:[2,3,0,1] row_mask:0xf bank_mask:0xf bound_ctrl:1
	v_med3_i32 v3, v3, v59, v113
	s_nop 1
	v_mov_b32_dpp v59, v3 quad_perm:[1,0,3,2] row_mask:0xf bank_mask:0xf bound_ctrl:1
	v_med3_i32 v3, v3, v59, v114
	v_mov_b32_e32 v59, v3
	v_mov_b32_e32 v61, v3
	s_nop 1
	v_permlane32_swap_b32_e32 v59, v61
	v_cndmask_b32_e64 v59, v59, v61, s[8:9]
	v_med3_i32 v3, v3, v59, v127
	v_mov_b32_e32 v59, v3
	v_mov_b32_e32 v61, v3
	s_nop 1
	v_permlane16_swap_b32_e32 v59, v61
	v_cndmask_b32_e64 v59, v59, v61, s[6:7]
	v_med3_i32 v3, v3, v59, v117
	s_nop 1
	v_mov_b32_dpp v59, v3 row_ror:8 row_mask:0xf bank_mask:0xf bound_ctrl:1
	v_med3_i32 v3, v3, v59, v119
	s_nop 1
	v_mov_b32_dpp v59, v3 row_half_mirror row_mask:0xf bank_mask:0xf bound_ctrl:1
	s_nop 1
	v_mov_b32_dpp v61, v59 quad_perm:[3,2,1,0] row_mask:0xf bank_mask:0xf bound_ctrl:1
	v_med3_i32 v3, v3, v61, v121
	s_nop 1
	v_mov_b32_dpp v59, v3 quad_perm:[2,3,0,1] row_mask:0xf bank_mask:0xf bound_ctrl:1
	v_med3_i32 v3, v3, v59, v123
	s_nop 1
	v_mov_b32_dpp v59, v3 quad_perm:[1,0,3,2] row_mask:0xf bank_mask:0xf bound_ctrl:1
	v_med3_i32 v3, v3, v59, v125
	v_and_or_b32 v3, v3, 63, v166
	v_lshlrev_b32_e32 v3, 2, v3
	v_xor_b32_e32 v3, 0xfc, v3
	ds_bpermute_b32 v2, v3, v2
	ds_bpermute_b32 v59, v167, v63
	s_waitcnt lgkmcnt(1)
	v_readlane_b32 s33, v2, 0
	s_nop 1
	v_subrev_f32_e32 v2, s33, v2
	v_mul_f32_e32 v2, v24, v2
	v_mul_f32_e32 v2, 0x3fb8aa3b, v2
	v_exp_f32_e32 v2, v2
	s_waitcnt lgkmcnt(0)
	v_lshl_add_u32 v59, v59, 7, v60
	ds_bpermute_b32 v3, v3, v59
	v_cndmask_b32_e64 v59, 0, v2, s[54:55]
	s_nop 1
	v_add_f32_dpp v59, v59, v59 row_ror:8 row_mask:0xf bank_mask:0xf bound_ctrl:1
	s_nop 1
	v_mov_b32_dpp v60, v59 row_half_mirror row_mask:0xf bank_mask:0xf bound_ctrl:1
	s_nop 1
	v_add_f32_dpp v59, v60, v59 quad_perm:[3,2,1,0] row_mask:0xf bank_mask:0xf bound_ctrl:1
	s_nop 1
	v_add_f32_dpp v59, v59, v59 quad_perm:[2,3,0,1] row_mask:0xf bank_mask:0xf bound_ctrl:1
	s_nop 1
	v_mov_b32_dpp v60, v59 quad_perm:[1,0,3,2] row_mask:0xf bank_mask:0xf bound_ctrl:1
	s_and_saveexec_b64 s[66:67], s[54:55]
	s_cbranch_execz .LBB0_921
	v_add_f32_e32 v59, v59, v60
	v_div_scale_f32 v60, s[68:69], v59, v59, v2
	v_rcp_f32_e32 v61, v60
	v_div_scale_f32 v62, vcc, v2, v59, v2
	v_fma_f32 v63, -v60, v61, 1.0
	v_fmac_f32_e32 v61, v63, v61
	v_mul_f32_e32 v63, v62, v61
	v_fma_f32 v64, -v60, v63, v62
	v_fmac_f32_e32 v63, v64, v61
	v_fma_f32 v60, -v60, v63, v62
	v_div_fmas_f32 v60, v60, v61, v63
	v_div_fixup_f32 v2, v60, v59, v2
	s_waitcnt lgkmcnt(0)
	ds_write2_b32 v28, v3, v2 offset0:16 offset1:144
	s_branch .LBB0_921
